# GEMM k-loops: first iteration peeled, first MFMA of every accumulator tile takes inline 0 as C, the 127 v_mov accumulator-zeroing instructions per unit removed
# speedup vs baseline: 1.0270x; 1.0029x over previous
; #define PG8_STAGE(bufoff, gbase, voff) do { _Pragma("unroll") for (int _i = 0; _i < 2; ++_i) \
;         __builtin_amdgcn_global_load_lds((const unsigned*)((const char*)(gbase) + (voff)[_i]), (PG8_LAS unsigned*)(lds + (bufoff) + ldsw + _i * 8192), 16, 0, 0); } while (0)
; #define PG8_LDA(dst, b, h) do { _Pragma("unroll") for (int m = 0; m < 4; ++m) _Pragma("unroll") for (int k = 0; k < 2; ++k) dst[m][k] = *(const PG8_LAS bf16x8*)(lds + PG8_SA(b, h) + aoff + m * 2048 + k * 1024); } while (0)
; #define PG8_LDB(dst, b, h) do { _Pragma("unroll") for (int n = 0; n < 2; ++n) _Pragma("unroll") for (int k = 0; k < 2; ++k) dst[n][k] = *(const PG8_LAS bf16x8*)(lds + PG8_SB(b, h) + boff + n * 2048 + k * 1024); } while (0)
; #define PG8_MMA(ai, bj, At, Bt) do { __builtin_amdgcn_s_setprio(1); _Pragma("unroll") for (int m = 0; m < 4; ++m) _Pragma("unroll") for (int n = 0; n < 2; ++n) _Pragma("unroll") for (int k = 0; k < 2; ++k) \
;         acc[ai][bj][m][n] = __builtin_amdgcn_mfma_f32_16x16x32_bf16(Bt[n][k], At[m][k], acc[ai][bj][m][n], 0, 0, 0); __builtin_amdgcn_s_setprio(0); } while (0)
; #define PG8_BAR __builtin_amdgcn_s_barrier()
; template <class Epi, class Sched>
; __device__ __forceinline__ void gemm_phase(PG8_LAS unsigned char* lds, PG8_LAS unsigned char* xl, const Gemm g, const Sched& S, const Epi& E) {
;     ...
;         const bool has_next = S.next(ui + 1, nxt);
;         const char* nA = has_next ? (const char*)g.A + nxt.aoff : cA; const char* nB = has_next ? (const char*)g.Bt + nxt.boff : cB;
; #pragma unroll 1
;         for (int t = 0; t < nt; t += 2) {
;             const bool last = (t == nt - 2);
;             const char* a1 = cA + (size_t)(t + 1) * kstep;
;             const char* a2 = last ? nA : cA + (size_t)(t + 2) * kstep; const char* b2 = last ? nB : cB + (size_t)(t + 2) * kstep;
;             const char* a3 = a2 + kstep; const char* b3 = b2 + kstep;
;             PG8_LDB(B0, 0, 0); PG8_LDB(B1, 0, 1); PG8_SCHED; PG8_LDA(At, 0, 0); PG8_STAGE(PG8_SA(1, 1), a1 + hsA, voffA);
;             PG8_WAIT_V(8); PG8_WAIT_L(0); PG8_BAR; PG8_MMA(0, 0, At, B0); PG8_MMA(0, 1, At, B1); PG8_BAR; PG8_SCHED;
;             PG8_LDA(At, 0, 1); PG8_STAGE(PG8_SB(0, 0), b2, voffB); PG8_STAGE(PG8_SB(0, 1), b2 + hsB, voffB); PG8_STAGE(PG8_SA(0, 0), a2, voffA);
;             PG8_WAIT_V(8); PG8_WAIT_L(0); PG8_BAR; PG8_MMA(1, 0, At, B0); PG8_MMA(1, 1, At, B1); PG8_BAR; PG8_SCHED;
.LBB0_101:
	s_add_u32 s20, s35, s16
	s_addc_u32 s21, s36, s17
	s_and_b64 s[22:23], s[4:5], exec
	s_cselect_b32 s73, s21, s29
	s_cselect_b32 s74, s20, s28
	s_add_u32 s22, s2, s18
	s_addc_u32 s23, s3, s19
	s_and_b64 s[30:31], s[4:5], exec
	s_cselect_b32 s75, s23, s27
	s_cselect_b32 s76, s22, s26
	s_add_u32 s77, s26, 0x100
	s_addc_u32 s78, s27, 0
	s_add_u32 s26, s28, 0x40080
	v_mov_b32_e32 v0, 0
	s_addc_u32 s27, s29, 0
	s_mov_b32 s79, -2
	ds_read_b128 v[148:151], v153
	ds_read_b128 v[158:161], v153 offset:1024
	ds_read_b128 v[162:165], v153 offset:2048
	ds_read_b128 v[166:169], v153 offset:3072
	ds_read_b128 v[170:173], v154
	ds_read_b128 v[174:177], v154 offset:1024
	ds_read_b128 v[178:181], v154 offset:2048
	ds_read_b128 v[182:185], v154 offset:3072
	s_add_u32 s28, s26, 0xfffc0080
	s_addc_u32 s29, s27, -1
	s_cmp_eq_u32 s79, 12
	s_cselect_b32 s31, s73, s29
	s_cselect_b32 s30, s74, s28
	s_cselect_b32 s29, s75, s78
	s_cselect_b32 s28, s76, s77
	v_lshl_add_u64 v[218:219], s[26:27], 0, v[142:143]
	s_add_i32 m0, s52, 0xc000
	ds_read_b128 v[186:189], v155
	ds_read_b128 v[190:193], v155 offset:1024
	ds_read_b128 v[194:197], v155 offset:2048
	ds_read_b128 v[198:201], v155 offset:3072
	ds_read_b128 v[202:205], v155 offset:4096
	ds_read_b128 v[206:209], v155 offset:5120
	ds_read_b128 v[210:213], v155 offset:6144
	ds_read_b128 v[214:217], v155 offset:7168
	global_load_lds_dwordx4 v[218:219], off
	v_lshl_add_u64 v[218:219], s[26:27], 0, v[140:141]
	s_add_i32 m0, s52, 0xe000
	s_nop 0
	global_load_lds_dwordx4 v[218:219], off
	s_waitcnt vmcnt(8)
	s_waitcnt lgkmcnt(0)
	s_barrier
	s_setprio 1
	s_waitcnt lgkmcnt(0)
	v_mfma_f32_16x16x32_bf16 v[124:127], v[148:151], v[186:189], 0
	v_mfma_f32_16x16x32_bf16 v[116:119], v[162:165], v[186:189], 0
	v_mfma_f32_16x16x32_bf16 v[108:111], v[148:151], v[194:197], 0
	v_mfma_f32_16x16x32_bf16 v[100:103], v[162:165], v[194:197], 0
	v_mfma_f32_16x16x32_bf16 v[92:95], v[148:151], v[202:205], 0
	v_mfma_f32_16x16x32_bf16 v[84:87], v[162:165], v[202:205], 0
	v_mfma_f32_16x16x32_bf16 v[76:79], v[148:151], v[210:213], 0
	v_mfma_f32_16x16x32_bf16 v[68:71], v[162:165], v[210:213], 0
	v_mfma_f32_16x16x32_bf16 v[124:127], v[158:161], v[190:193], v[124:127]
	v_mfma_f32_16x16x32_bf16 v[116:119], v[166:169], v[190:193], v[116:119]
	v_mfma_f32_16x16x32_bf16 v[108:111], v[158:161], v[198:201], v[108:111]
	v_mfma_f32_16x16x32_bf16 v[100:103], v[166:169], v[198:201], v[100:103]
	v_mfma_f32_16x16x32_bf16 v[92:95], v[158:161], v[206:209], v[92:95]
	v_mfma_f32_16x16x32_bf16 v[84:87], v[166:169], v[206:209], v[84:87]
	v_mfma_f32_16x16x32_bf16 v[76:79], v[158:161], v[214:217], v[76:79]
	v_mfma_f32_16x16x32_bf16 v[68:71], v[166:169], v[214:217], v[68:71]
	s_setprio 0
	s_setprio 1
	v_mfma_f32_16x16x32_bf16 v[120:123], v[170:173], v[186:189], 0
	v_mfma_f32_16x16x32_bf16 v[112:115], v[178:181], v[186:189], 0
	v_mfma_f32_16x16x32_bf16 v[104:107], v[170:173], v[194:197], 0
	v_mfma_f32_16x16x32_bf16 v[96:99], v[178:181], v[194:197], 0
	v_mfma_f32_16x16x32_bf16 v[88:91], v[170:173], v[202:205], 0
	v_mfma_f32_16x16x32_bf16 v[80:83], v[178:181], v[202:205], 0
	v_mfma_f32_16x16x32_bf16 v[72:75], v[170:173], v[210:213], 0
	v_mfma_f32_16x16x32_bf16 v[64:67], v[178:181], v[210:213], 0
	v_mfma_f32_16x16x32_bf16 v[120:123], v[174:177], v[190:193], v[120:123]
	v_mfma_f32_16x16x32_bf16 v[112:115], v[182:185], v[190:193], v[112:115]
	v_mfma_f32_16x16x32_bf16 v[104:107], v[174:177], v[198:201], v[104:107]
	v_mfma_f32_16x16x32_bf16 v[96:99], v[182:185], v[198:201], v[96:99]
	v_mfma_f32_16x16x32_bf16 v[88:91], v[174:177], v[206:209], v[88:91]
	v_mfma_f32_16x16x32_bf16 v[80:83], v[182:185], v[206:209], v[80:83]
	v_mfma_f32_16x16x32_bf16 v[72:75], v[174:177], v[214:217], v[72:75]
	v_mfma_f32_16x16x32_bf16 v[64:67], v[182:185], v[214:217], v[64:67]
	s_setprio 0
	s_barrier
	s_add_i32 s68, s60, s42
	v_lshl_add_u64 v[218:219], s[28:29], 0, v[132:133]
	s_mov_b32 m0, s68
	ds_read_b128 v[186:189], v155 offset:16384
	ds_read_b128 v[190:193], v155 offset:17408
	ds_read_b128 v[194:197], v155 offset:18432
	ds_read_b128 v[198:201], v155 offset:19456
	ds_read_b128 v[202:205], v155 offset:20480
	ds_read_b128 v[206:209], v155 offset:21504
	ds_read_b128 v[210:213], v155 offset:22528
	ds_read_b128 v[214:217], v155 offset:23552
	global_load_lds_dwordx4 v[218:219], off
	s_add_i32 m0, s68, 0x2000
	s_add_u32 s80, s28, 0x40000
	v_lshl_add_u64 v[222:223], s[28:29], 0, v[128:129]
	s_addc_u32 s81, s29, 0
	s_add_i32 s68, s61, s42
	global_load_lds_dwordx4 v[222:223], off
	v_lshl_add_u64 v[224:225], s[80:81], 0, v[132:133]
	s_mov_b32 m0, s68
	v_lshl_add_u64 v[226:227], s[30:31], 0, v[130:131]
	global_load_lds_dwordx4 v[224:225], off
	v_lshl_add_u64 v[224:225], s[80:81], 0, v[128:129]
	s_add_i32 m0, s68, 0x2000
	s_nop 0
	global_load_lds_dwordx4 v[224:225], off
	v_lshl_add_u64 v[224:225], s[30:31], 0, v[134:135]
	s_mov_b32 m0, s52
	s_nop 0
	global_load_lds_dwordx4 v[224:225], off
	s_mov_b32 m0, s53
	s_nop 0
	global_load_lds_dwordx4 v[226:227], off
	s_waitcnt vmcnt(8)
	s_waitcnt lgkmcnt(0)
	s_barrier
; #define PG8_STAGE(bufoff, gbase, voff) do { _Pragma("unroll") for (int _i = 0; _i < 2; ++_i) \
;         __builtin_amdgcn_global_load_lds((const unsigned*)((const char*)(gbase) + (voff)[_i]), (PG8_LAS unsigned*)(lds + (bufoff) + ldsw + _i * 8192), 16, 0, 0); } while (0)
; #define PG8_LDA(dst, b, h) do { _Pragma("unroll") for (int m = 0; m < 4; ++m) _Pragma("unroll") for (int k = 0; k < 2; ++k) dst[m][k] = *(const PG8_LAS bf16x8*)(lds + PG8_SA(b, h) + aoff + m * 2048 + k * 1024); } while (0)
; #define PG8_LDB(dst, b, h) do { _Pragma("unroll") for (int n = 0; n < 2; ++n) _Pragma("unroll") for (int k = 0; k < 2; ++k) dst[n][k] = *(const PG8_LAS bf16x8*)(lds + PG8_SB(b, h) + boff + n * 2048 + k * 1024); } while (0)
; #define PG8_MMA(ai, bj, At, Bt) do { __builtin_amdgcn_s_setprio(1); _Pragma("unroll") for (int m = 0; m < 4; ++m) _Pragma("unroll") for (int n = 0; n < 2; ++n) _Pragma("unroll") for (int k = 0; k < 2; ++k) \
;         acc[ai][bj][m][n] = __builtin_amdgcn_mfma_f32_16x16x32_bf16(Bt[n][k], At[m][k], acc[ai][bj][m][n], 0, 0, 0); __builtin_amdgcn_s_setprio(0); } while (0)
; #define PG8_WAIT_V(n) asm volatile("s_waitcnt vmcnt(" #n ")" ::: "memory")
; #define PG8_WAIT_L(n) asm volatile("s_waitcnt lgkmcnt(" #n ")" ::: "memory")
; #define PG8_BAR __builtin_amdgcn_s_barrier()
; #define PG8_SCHED __builtin_amdgcn_sched_barrier(0)
; template <class Epi, class Sched>
; __device__ __forceinline__ void gemm_phase(PG8_LAS unsigned char* lds, PG8_LAS unsigned char* xl, const Gemm g, const Sched& S, const Epi& E) {
;     ...
;             PG8_WAIT_V(8); PG8_WAIT_L(0); PG8_BAR; PG8_MMA(1, 0, At, B0); PG8_MMA(1, 1, At, B1); PG8_BAR; PG8_SCHED;
;             PG8_LDB(B0, 1, 0); PG8_LDB(B1, 1, 1); PG8_SCHED; PG8_LDA(At, 1, 0); PG8_STAGE(PG8_SA(0, 1), a2 + hsA, voffA);
;             PG8_WAIT_V(8); PG8_WAIT_L(0); PG8_BAR; PG8_MMA(0, 0, At, B0); PG8_MMA(0, 1, At, B1); PG8_BAR; PG8_SCHED;
;             PG8_LDA(At, 1, 1); PG8_STAGE(PG8_SB(1, 0), b3, voffB); PG8_STAGE(PG8_SB(1, 1), b3 + hsB, voffB); PG8_STAGE(PG8_SA(1, 0), a3, voffA);
	s_setprio 1
	s_waitcnt lgkmcnt(0)
	v_mfma_f32_16x16x32_bf16 v[60:63], v[148:151], v[186:189], 0
	v_mfma_f32_16x16x32_bf16 v[52:55], v[162:165], v[186:189], 0
	v_mfma_f32_16x16x32_bf16 v[44:47], v[148:151], v[194:197], 0
	v_mfma_f32_16x16x32_bf16 v[36:39], v[162:165], v[194:197], 0
	v_mfma_f32_16x16x32_bf16 v[28:31], v[148:151], v[202:205], 0
	v_mfma_f32_16x16x32_bf16 v[20:23], v[162:165], v[202:205], 0
	v_mfma_f32_16x16x32_bf16 v[12:15], v[148:151], v[210:213], 0
	v_mfma_f32_16x16x32_bf16 v[4:7], v[162:165], v[210:213], 0
	v_mfma_f32_16x16x32_bf16 v[60:63], v[158:161], v[190:193], v[60:63]
	v_mfma_f32_16x16x32_bf16 v[52:55], v[166:169], v[190:193], v[52:55]
	v_mfma_f32_16x16x32_bf16 v[44:47], v[158:161], v[198:201], v[44:47]
	v_mfma_f32_16x16x32_bf16 v[36:39], v[166:169], v[198:201], v[36:39]
	v_mfma_f32_16x16x32_bf16 v[28:31], v[158:161], v[206:209], v[28:31]
	v_mfma_f32_16x16x32_bf16 v[20:23], v[166:169], v[206:209], v[20:23]
	v_mfma_f32_16x16x32_bf16 v[12:15], v[158:161], v[214:217], v[12:15]
	v_mfma_f32_16x16x32_bf16 v[4:7], v[166:169], v[214:217], v[4:7]
	s_setprio 0
	s_setprio 1
	v_mfma_f32_16x16x32_bf16 v[56:59], v[170:173], v[186:189], 0
	v_mfma_f32_16x16x32_bf16 v[48:51], v[178:181], v[186:189], 0
	v_mfma_f32_16x16x32_bf16 v[40:43], v[170:173], v[194:197], 0
	v_mfma_f32_16x16x32_bf16 v[32:35], v[178:181], v[194:197], 0
	v_mfma_f32_16x16x32_bf16 v[24:27], v[170:173], v[202:205], 0
	v_mfma_f32_16x16x32_bf16 v[16:19], v[178:181], v[202:205], 0
	v_mfma_f32_16x16x32_bf16 v[8:11], v[170:173], v[210:213], 0
	v_mfma_f32_16x16x32_bf16 v[0:3], v[178:181], v[210:213], 0
	v_mfma_f32_16x16x32_bf16 v[56:59], v[174:177], v[190:193], v[56:59]
	v_mfma_f32_16x16x32_bf16 v[48:51], v[182:185], v[190:193], v[48:51]
	v_mfma_f32_16x16x32_bf16 v[40:43], v[174:177], v[198:201], v[40:43]
	v_mfma_f32_16x16x32_bf16 v[32:35], v[182:185], v[198:201], v[32:35]
	v_mfma_f32_16x16x32_bf16 v[24:27], v[174:177], v[206:209], v[24:27]
	v_mfma_f32_16x16x32_bf16 v[16:19], v[182:185], v[206:209], v[16:19]
	v_mfma_f32_16x16x32_bf16 v[8:11], v[174:177], v[214:217], v[8:11]
	v_mfma_f32_16x16x32_bf16 v[0:3], v[182:185], v[214:217], v[0:3]
	s_setprio 0
	s_barrier
	s_add_i32 s68, 0, 0x18000
	v_add_u32_e32 v136, s68, v152
	s_add_i32 s80, 0, 0x1c000
	ds_read_b128 v[148:151], v136
	ds_read_b128 v[158:161], v136 offset:1024
	ds_read_b128 v[162:165], v136 offset:2048
	ds_read_b128 v[166:169], v136 offset:3072
	v_add_u32_e32 v136, s80, v152
	ds_read_b128 v[170:173], v136
	ds_read_b128 v[174:177], v136 offset:1024
	ds_read_b128 v[178:181], v136 offset:2048
	ds_read_b128 v[182:185], v136 offset:3072
	s_add_u32 s30, s30, 0x40000
	s_addc_u32 s31, s31, 0
	s_mov_b32 m0, s54
	v_lshl_add_u64 v[228:229], s[30:31], 0, v[134:135]
	ds_read_b128 v[186:189], v155 offset:32768
	ds_read_b128 v[190:193], v155 offset:33792
	ds_read_b128 v[194:197], v155 offset:34816
	ds_read_b128 v[198:201], v155 offset:35840
	ds_read_b128 v[202:205], v155 offset:36864
	ds_read_b128 v[206:209], v155 offset:37888
	ds_read_b128 v[210:213], v155 offset:38912
	ds_read_b128 v[214:217], v155 offset:39936
	global_load_lds_dwordx4 v[228:229], off
	v_lshl_add_u64 v[228:229], s[30:31], 0, v[130:131]
	s_mov_b32 m0, s55
	s_nop 0
	global_load_lds_dwordx4 v[228:229], off
	s_waitcnt vmcnt(8)
	s_waitcnt lgkmcnt(0)
	s_barrier
	s_setprio 1
	s_waitcnt lgkmcnt(0)
	v_mfma_f32_16x16x32_bf16 v[124:127], v[148:151], v[186:189], v[124:127]
	v_mfma_f32_16x16x32_bf16 v[116:119], v[162:165], v[186:189], v[116:119]
	v_mfma_f32_16x16x32_bf16 v[108:111], v[148:151], v[194:197], v[108:111]
	v_mfma_f32_16x16x32_bf16 v[100:103], v[162:165], v[194:197], v[100:103]
	v_mfma_f32_16x16x32_bf16 v[92:95], v[148:151], v[202:205], v[92:95]
	v_mfma_f32_16x16x32_bf16 v[84:87], v[162:165], v[202:205], v[84:87]
	v_mfma_f32_16x16x32_bf16 v[76:79], v[148:151], v[210:213], v[76:79]
	v_mfma_f32_16x16x32_bf16 v[68:71], v[162:165], v[210:213], v[68:71]
	v_mfma_f32_16x16x32_bf16 v[124:127], v[158:161], v[190:193], v[124:127]
	v_mfma_f32_16x16x32_bf16 v[116:119], v[166:169], v[190:193], v[116:119]
	v_mfma_f32_16x16x32_bf16 v[108:111], v[158:161], v[198:201], v[108:111]
	v_mfma_f32_16x16x32_bf16 v[100:103], v[166:169], v[198:201], v[100:103]
	v_mfma_f32_16x16x32_bf16 v[92:95], v[158:161], v[206:209], v[92:95]
	v_mfma_f32_16x16x32_bf16 v[84:87], v[166:169], v[206:209], v[84:87]
	v_mfma_f32_16x16x32_bf16 v[76:79], v[158:161], v[214:217], v[76:79]
	v_mfma_f32_16x16x32_bf16 v[68:71], v[166:169], v[214:217], v[68:71]
	s_setprio 0
	s_setprio 1
	v_mfma_f32_16x16x32_bf16 v[120:123], v[170:173], v[186:189], v[120:123]
	v_mfma_f32_16x16x32_bf16 v[112:115], v[178:181], v[186:189], v[112:115]
	v_mfma_f32_16x16x32_bf16 v[104:107], v[170:173], v[194:197], v[104:107]
	v_mfma_f32_16x16x32_bf16 v[96:99], v[178:181], v[194:197], v[96:99]
	v_mfma_f32_16x16x32_bf16 v[88:91], v[170:173], v[202:205], v[88:91]
	v_mfma_f32_16x16x32_bf16 v[80:83], v[178:181], v[202:205], v[80:83]
	v_mfma_f32_16x16x32_bf16 v[72:75], v[170:173], v[210:213], v[72:75]
	v_mfma_f32_16x16x32_bf16 v[64:67], v[178:181], v[210:213], v[64:67]
	v_mfma_f32_16x16x32_bf16 v[120:123], v[174:177], v[190:193], v[120:123]
	v_mfma_f32_16x16x32_bf16 v[112:115], v[182:185], v[190:193], v[112:115]
	v_mfma_f32_16x16x32_bf16 v[104:107], v[174:177], v[198:201], v[104:107]
	v_mfma_f32_16x16x32_bf16 v[96:99], v[182:185], v[198:201], v[96:99]
	v_mfma_f32_16x16x32_bf16 v[88:91], v[174:177], v[206:209], v[88:91]
	v_mfma_f32_16x16x32_bf16 v[80:83], v[182:185], v[206:209], v[80:83]
	v_mfma_f32_16x16x32_bf16 v[72:75], v[174:177], v[214:217], v[72:75]
	v_mfma_f32_16x16x32_bf16 v[64:67], v[182:185], v[214:217], v[64:67]
	s_setprio 0
	s_barrier
; #define PG8_STAGE(bufoff, gbase, voff) do { _Pragma("unroll") for (int _i = 0; _i < 2; ++_i) \
;         __builtin_amdgcn_global_load_lds((const unsigned*)((const char*)(gbase) + (voff)[_i]), (PG8_LAS unsigned*)(lds + (bufoff) + ldsw + _i * 8192), 16, 0, 0); } while (0)
; #define PG8_LDA(dst, b, h) do { _Pragma("unroll") for (int m = 0; m < 4; ++m) _Pragma("unroll") for (int k = 0; k < 2; ++k) dst[m][k] = *(const PG8_LAS bf16x8*)(lds + PG8_SA(b, h) + aoff + m * 2048 + k * 1024); } while (0)
; #define PG8_MMA(ai, bj, At, Bt) do { __builtin_amdgcn_s_setprio(1); _Pragma("unroll") for (int m = 0; m < 4; ++m) _Pragma("unroll") for (int n = 0; n < 2; ++n) _Pragma("unroll") for (int k = 0; k < 2; ++k) \
;         acc[ai][bj][m][n] = __builtin_amdgcn_mfma_f32_16x16x32_bf16(Bt[n][k], At[m][k], acc[ai][bj][m][n], 0, 0, 0); __builtin_amdgcn_s_setprio(0); } while (0)
; #define PG8_WAIT_V(n) asm volatile("s_waitcnt vmcnt(" #n ")" ::: "memory")
; #define PG8_WAIT_L(n) asm volatile("s_waitcnt lgkmcnt(" #n ")" ::: "memory")
; #define PG8_BAR __builtin_amdgcn_s_barrier()
; #define PG8_SCHED __builtin_amdgcn_sched_barrier(0)
; template <class Epi, class Sched>
; __device__ __forceinline__ void gemm_phase(PG8_LAS unsigned char* lds, PG8_LAS unsigned char* xl, const Gemm g, const Sched& S, const Epi& E) {
;     ...
;             PG8_LDA(At, 1, 1); PG8_STAGE(PG8_SB(1, 0), b3, voffB); PG8_STAGE(PG8_SB(1, 1), b3 + hsB, voffB); PG8_STAGE(PG8_SA(1, 0), a3, voffA);
;             PG8_WAIT_V(8); PG8_WAIT_L(0); PG8_BAR; PG8_MMA(1, 0, At, B0); PG8_MMA(1, 1, At, B1); PG8_BAR; PG8_SCHED;
;         }
	s_add_i32 s30, s68, s42
	v_lshl_add_u64 v[218:219], v[218:219], 0, s[12:13]
	s_mov_b32 m0, s30
	ds_read_b128 v[186:189], v155 offset:49152
	ds_read_b128 v[190:193], v155 offset:50176
	ds_read_b128 v[194:197], v155 offset:51200
	ds_read_b128 v[198:201], v155 offset:52224
	ds_read_b128 v[202:205], v155 offset:53248
	ds_read_b128 v[206:209], v155 offset:54272
	ds_read_b128 v[210:213], v155 offset:55296
	ds_read_b128 v[214:217], v155 offset:56320
	global_load_lds_dwordx4 v[218:219], off
	s_add_i32 m0, s30, 0x2000
	s_add_u32 s28, s28, 0x40080
	v_lshl_add_u64 v[218:219], v[222:223], 0, s[12:13]
	s_addc_u32 s29, s29, 0
	s_add_i32 s30, s80, s42
	global_load_lds_dwordx4 v[218:219], off
	v_lshl_add_u64 v[218:219], s[28:29], 0, v[132:133]
	s_mov_b32 m0, s30
	s_nop 0
	global_load_lds_dwordx4 v[218:219], off
	v_lshl_add_u64 v[218:219], s[28:29], 0, v[128:129]
	s_add_i32 m0, s30, 0x2000
	s_nop 0
	global_load_lds_dwordx4 v[218:219], off
	v_lshl_add_u64 v[218:219], v[224:225], 0, s[12:13]
	s_mov_b32 m0, s58
	s_nop 0
	global_load_lds_dwordx4 v[218:219], off
	v_lshl_add_u64 v[218:219], v[226:227], 0, s[12:13]
	s_mov_b32 m0, s59
	s_nop 0
	global_load_lds_dwordx4 v[218:219], off
	s_waitcnt vmcnt(8)
	s_waitcnt lgkmcnt(0)
	s_barrier
	s_setprio 1
	s_waitcnt lgkmcnt(0)
	v_mfma_f32_16x16x32_bf16 v[60:63], v[148:151], v[186:189], v[60:63]
	v_mfma_f32_16x16x32_bf16 v[52:55], v[162:165], v[186:189], v[52:55]
	v_mfma_f32_16x16x32_bf16 v[44:47], v[148:151], v[194:197], v[44:47]
	v_mfma_f32_16x16x32_bf16 v[36:39], v[162:165], v[194:197], v[36:39]
	v_mfma_f32_16x16x32_bf16 v[28:31], v[148:151], v[202:205], v[28:31]
	v_mfma_f32_16x16x32_bf16 v[20:23], v[162:165], v[202:205], v[20:23]
	v_mfma_f32_16x16x32_bf16 v[12:15], v[148:151], v[210:213], v[12:15]
	v_mfma_f32_16x16x32_bf16 v[4:7], v[162:165], v[210:213], v[4:7]
	v_mfma_f32_16x16x32_bf16 v[60:63], v[158:161], v[190:193], v[60:63]
	v_mfma_f32_16x16x32_bf16 v[52:55], v[166:169], v[190:193], v[52:55]
	v_mfma_f32_16x16x32_bf16 v[44:47], v[158:161], v[198:201], v[44:47]
	v_mfma_f32_16x16x32_bf16 v[36:39], v[166:169], v[198:201], v[36:39]
	v_mfma_f32_16x16x32_bf16 v[28:31], v[158:161], v[206:209], v[28:31]
	v_mfma_f32_16x16x32_bf16 v[20:23], v[166:169], v[206:209], v[20:23]
	v_mfma_f32_16x16x32_bf16 v[12:15], v[158:161], v[214:217], v[12:15]
	v_mfma_f32_16x16x32_bf16 v[4:7], v[166:169], v[214:217], v[4:7]
	s_setprio 0
	s_setprio 1
	v_mfma_f32_16x16x32_bf16 v[56:59], v[170:173], v[186:189], v[56:59]
	v_mfma_f32_16x16x32_bf16 v[48:51], v[178:181], v[186:189], v[48:51]
	v_mfma_f32_16x16x32_bf16 v[40:43], v[170:173], v[194:197], v[40:43]
	v_mfma_f32_16x16x32_bf16 v[32:35], v[178:181], v[194:197], v[32:35]
	v_mfma_f32_16x16x32_bf16 v[24:27], v[170:173], v[202:205], v[24:27]
	v_mfma_f32_16x16x32_bf16 v[16:19], v[178:181], v[202:205], v[16:19]
	v_mfma_f32_16x16x32_bf16 v[8:11], v[170:173], v[210:213], v[8:11]
	v_mfma_f32_16x16x32_bf16 v[0:3], v[178:181], v[210:213], v[0:3]
	v_mfma_f32_16x16x32_bf16 v[56:59], v[174:177], v[190:193], v[56:59]
	v_mfma_f32_16x16x32_bf16 v[48:51], v[182:185], v[190:193], v[48:51]
	v_mfma_f32_16x16x32_bf16 v[40:43], v[174:177], v[198:201], v[40:43]
	v_mfma_f32_16x16x32_bf16 v[32:35], v[182:185], v[198:201], v[32:35]
	v_mfma_f32_16x16x32_bf16 v[24:27], v[174:177], v[206:209], v[24:27]
	v_mfma_f32_16x16x32_bf16 v[16:19], v[182:185], v[206:209], v[16:19]
	v_mfma_f32_16x16x32_bf16 v[8:11], v[174:177], v[214:217], v[8:11]
	v_mfma_f32_16x16x32_bf16 v[0:3], v[182:185], v[214:217], v[0:3]
	s_setprio 0
	s_barrier
	s_add_i32 s79, s79, 2
	s_add_u32 s77, s77, 0x100
	s_addc_u32 s78, s78, 0
	s_add_u32 s26, s26, 0x100
	s_addc_u32 s27, s27, 0
	s_cmp_gt_u32 s79, 13
	s_cbranch_scc1 .Lpeel_after_P1

; #define PG8_BAR __builtin_amdgcn_s_barrier()
; template <class Epi, class Sched>
; __device__ __forceinline__ void gemm_phase(PG8_LAS unsigned char* lds, PG8_LAS unsigned char* xl, const Gemm g, const Sched& S, const Epi& E) {
;     ...
;         if (wr == 0) PG8_BAR;
.Lpeel_after_P1:
	s_and_b64 vcc, exec, s[14:15]
	s_cbranch_vccz .LBB0_105
	s_barrier

; #define PG8_STAGE(bufoff, gbase, voff) do { _Pragma("unroll") for (int _i = 0; _i < 2; ++_i) \
;         __builtin_amdgcn_global_load_lds((const unsigned*)((const char*)(gbase) + (voff)[_i]), (PG8_LAS unsigned*)(lds + (bufoff) + ldsw + _i * 8192), 16, 0, 0); } while (0)
; #define PG8_LDA(dst, b, h) do { _Pragma("unroll") for (int m = 0; m < 4; ++m) _Pragma("unroll") for (int k = 0; k < 2; ++k) dst[m][k] = *(const PG8_LAS bf16x8*)(lds + PG8_SA(b, h) + aoff + m * 2048 + k * 1024); } while (0)
; #define PG8_LDB(dst, b, h) do { _Pragma("unroll") for (int n = 0; n < 2; ++n) _Pragma("unroll") for (int k = 0; k < 2; ++k) dst[n][k] = *(const PG8_LAS bf16x8*)(lds + PG8_SB(b, h) + boff + n * 2048 + k * 1024); } while (0)
; #define PG8_MMA(ai, bj, At, Bt) do { __builtin_amdgcn_s_setprio(1); _Pragma("unroll") for (int m = 0; m < 4; ++m) _Pragma("unroll") for (int n = 0; n < 2; ++n) _Pragma("unroll") for (int k = 0; k < 2; ++k) \
;         acc[ai][bj][m][n] = __builtin_amdgcn_mfma_f32_16x16x32_bf16(Bt[n][k], At[m][k], acc[ai][bj][m][n], 0, 0, 0); __builtin_amdgcn_s_setprio(0); } while (0)
; #define PG8_BAR __builtin_amdgcn_s_barrier()
; template <class Epi, class Sched>
; __device__ __forceinline__ void gemm_phase(PG8_LAS unsigned char* lds, PG8_LAS unsigned char* xl, const Gemm g, const Sched& S, const Epi& E) {
;     ...
;         const bool has_next = S.next(ui + 1, nxt);
;         const char* nA = has_next ? (const char*)g.A + nxt.aoff : cA; const char* nB = has_next ? (const char*)g.Bt + nxt.boff : cB;
; #pragma unroll 1
;         for (int t = 0; t < nt; t += 2) {
;             const bool last = (t == nt - 2);
;             const char* a1 = cA + (size_t)(t + 1) * kstep;
;             const char* a2 = last ? nA : cA + (size_t)(t + 2) * kstep; const char* b2 = last ? nB : cB + (size_t)(t + 2) * kstep;
;             const char* a3 = a2 + kstep; const char* b3 = b2 + kstep;
;             PG8_LDB(B0, 0, 0); PG8_LDB(B1, 0, 1); PG8_SCHED; PG8_LDA(At, 0, 0); PG8_STAGE(PG8_SA(1, 1), a1 + hsA, voffA);
;             PG8_WAIT_V(8); PG8_WAIT_L(0); PG8_BAR; PG8_MMA(0, 0, At, B0); PG8_MMA(0, 1, At, B1); PG8_BAR; PG8_SCHED;
;             PG8_LDA(At, 0, 1); PG8_STAGE(PG8_SB(0, 0), b2, voffB); PG8_STAGE(PG8_SB(0, 1), b2 + hsB, voffB); PG8_STAGE(PG8_SA(0, 0), a2, voffA);
;             PG8_WAIT_V(8); PG8_WAIT_L(0); PG8_BAR; PG8_MMA(1, 0, At, B0); PG8_MMA(1, 1, At, B1); PG8_BAR; PG8_SCHED;
.LBB0_129:
	s_add_u32 s18, s35, s14
	s_addc_u32 s19, s36, s15
	s_and_b64 s[20:21], s[4:5], exec
	s_cselect_b32 s70, s19, s29
	s_cselect_b32 s72, s18, s28
	s_add_u32 s20, s37, s16
	s_addc_u32 s21, s42, s17
	s_and_b64 s[30:31], s[4:5], exec
	s_cselect_b32 s73, s21, s27
	s_cselect_b32 s74, s20, s26
	s_add_u32 s75, s26, 0x100
	s_addc_u32 s76, s27, 0
	s_add_u32 s26, s28, 0x40080
	v_mov_b32_e32 v0, 0
	s_addc_u32 s27, s29, 0
	s_mov_b32 s77, -2
	ds_read_b128 v[154:157], v150
	ds_read_b128 v[158:161], v150 offset:1024
	ds_read_b128 v[162:165], v150 offset:2048
	ds_read_b128 v[166:169], v150 offset:3072
	ds_read_b128 v[170:173], v151
	ds_read_b128 v[174:177], v151 offset:1024
	ds_read_b128 v[178:181], v151 offset:2048
	ds_read_b128 v[182:185], v151 offset:3072
	s_add_u32 s28, s26, 0xfffc0080
	s_addc_u32 s29, s27, -1
	s_cmp_eq_u32 s77, 12
	s_cselect_b32 s31, s70, s29
	s_cselect_b32 s30, s72, s28
	s_cselect_b32 s29, s73, s76
	s_cselect_b32 s28, s74, s75
	v_lshl_add_u64 v[146:147], s[26:27], 0, v[140:141]
	s_add_i32 m0, s46, 0xc000
	ds_read_b128 v[186:189], v152
	ds_read_b128 v[190:193], v152 offset:1024
	ds_read_b128 v[194:197], v152 offset:2048
	ds_read_b128 v[198:201], v152 offset:3072
	ds_read_b128 v[202:205], v152 offset:4096
	ds_read_b128 v[206:209], v152 offset:5120
	ds_read_b128 v[210:213], v152 offset:6144
	ds_read_b128 v[214:217], v152 offset:7168
	global_load_lds_dwordx4 v[146:147], off
	v_lshl_add_u64 v[146:147], s[26:27], 0, v[138:139]
	s_add_i32 m0, s46, 0xe000
	s_nop 0
	global_load_lds_dwordx4 v[146:147], off
	s_waitcnt vmcnt(8)
	s_waitcnt lgkmcnt(0)
	s_barrier
	s_setprio 1
	s_waitcnt lgkmcnt(0)
	v_mfma_f32_16x16x32_bf16 v[124:127], v[154:157], v[186:189], 0
	v_mfma_f32_16x16x32_bf16 v[120:123], v[162:165], v[186:189], 0
	v_mfma_f32_16x16x32_bf16 v[116:119], v[154:157], v[194:197], 0
	v_mfma_f32_16x16x32_bf16 v[108:111], v[162:165], v[194:197], 0
	v_mfma_f32_16x16x32_bf16 v[100:103], v[154:157], v[202:205], 0
	v_mfma_f32_16x16x32_bf16 v[92:95], v[162:165], v[202:205], 0
	v_mfma_f32_16x16x32_bf16 v[84:87], v[154:157], v[210:213], 0
	v_mfma_f32_16x16x32_bf16 v[76:79], v[162:165], v[210:213], 0
	v_mfma_f32_16x16x32_bf16 v[124:127], v[158:161], v[190:193], v[124:127]
	v_mfma_f32_16x16x32_bf16 v[120:123], v[166:169], v[190:193], v[120:123]
	v_mfma_f32_16x16x32_bf16 v[116:119], v[158:161], v[198:201], v[116:119]
	v_mfma_f32_16x16x32_bf16 v[108:111], v[166:169], v[198:201], v[108:111]
	v_mfma_f32_16x16x32_bf16 v[100:103], v[158:161], v[206:209], v[100:103]
	v_mfma_f32_16x16x32_bf16 v[92:95], v[166:169], v[206:209], v[92:95]
	v_mfma_f32_16x16x32_bf16 v[84:87], v[158:161], v[214:217], v[84:87]
	v_mfma_f32_16x16x32_bf16 v[76:79], v[166:169], v[214:217], v[76:79]
	s_setprio 0
	s_setprio 1
	v_mfma_f32_16x16x32_bf16 v[112:115], v[170:173], v[186:189], 0
	v_mfma_f32_16x16x32_bf16 v[104:107], v[178:181], v[186:189], 0
	v_mfma_f32_16x16x32_bf16 v[96:99], v[170:173], v[194:197], 0
	v_mfma_f32_16x16x32_bf16 v[88:91], v[178:181], v[194:197], 0
	v_mfma_f32_16x16x32_bf16 v[80:83], v[170:173], v[202:205], 0
	v_mfma_f32_16x16x32_bf16 v[72:75], v[178:181], v[202:205], 0
	v_mfma_f32_16x16x32_bf16 v[68:71], v[170:173], v[210:213], 0
	v_mfma_f32_16x16x32_bf16 v[64:67], v[178:181], v[210:213], 0
	v_mfma_f32_16x16x32_bf16 v[112:115], v[174:177], v[190:193], v[112:115]
	v_mfma_f32_16x16x32_bf16 v[104:107], v[182:185], v[190:193], v[104:107]
	v_mfma_f32_16x16x32_bf16 v[96:99], v[174:177], v[198:201], v[96:99]
	v_mfma_f32_16x16x32_bf16 v[88:91], v[182:185], v[198:201], v[88:91]
	v_mfma_f32_16x16x32_bf16 v[80:83], v[174:177], v[206:209], v[80:83]
	v_mfma_f32_16x16x32_bf16 v[72:75], v[182:185], v[206:209], v[72:75]
	v_mfma_f32_16x16x32_bf16 v[68:71], v[174:177], v[214:217], v[68:71]
	v_mfma_f32_16x16x32_bf16 v[64:67], v[182:185], v[214:217], v[64:67]
	s_setprio 0
	s_barrier
	s_add_i32 s68, s57, s43
	v_lshl_add_u64 v[146:147], s[28:29], 0, v[130:131]
	s_mov_b32 m0, s68
	ds_read_b128 v[186:189], v152 offset:16384
	ds_read_b128 v[190:193], v152 offset:17408
	ds_read_b128 v[194:197], v152 offset:18432
	ds_read_b128 v[198:201], v152 offset:19456
	ds_read_b128 v[202:205], v152 offset:20480
	ds_read_b128 v[206:209], v152 offset:21504
	ds_read_b128 v[210:213], v152 offset:22528
	ds_read_b128 v[214:217], v152 offset:23552
	global_load_lds_dwordx4 v[146:147], off
	s_add_i32 m0, s68, 0x2000
	s_add_u32 s78, s28, 0x40000
	v_lshl_add_u64 v[218:219], s[28:29], 0, v[134:135]
	s_addc_u32 s79, s29, 0
	s_add_i32 s68, s58, s43
	global_load_lds_dwordx4 v[218:219], off
	v_lshl_add_u64 v[222:223], s[78:79], 0, v[130:131]
	s_mov_b32 m0, s68
	v_lshl_add_u64 v[224:225], s[30:31], 0, v[132:133]
	global_load_lds_dwordx4 v[222:223], off
	v_lshl_add_u64 v[222:223], s[78:79], 0, v[134:135]
	s_add_i32 m0, s68, 0x2000
	s_nop 0
	global_load_lds_dwordx4 v[222:223], off
	v_lshl_add_u64 v[222:223], s[30:31], 0, v[128:129]
	s_mov_b32 m0, s46
	s_nop 0
	global_load_lds_dwordx4 v[222:223], off
	s_mov_b32 m0, s47
	s_nop 0
	global_load_lds_dwordx4 v[224:225], off
	s_waitcnt vmcnt(8)
	s_waitcnt lgkmcnt(0)
	s_barrier
; #define PG8_STAGE(bufoff, gbase, voff) do { _Pragma("unroll") for (int _i = 0; _i < 2; ++_i) \
;         __builtin_amdgcn_global_load_lds((const unsigned*)((const char*)(gbase) + (voff)[_i]), (PG8_LAS unsigned*)(lds + (bufoff) + ldsw + _i * 8192), 16, 0, 0); } while (0)
; #define PG8_LDA(dst, b, h) do { _Pragma("unroll") for (int m = 0; m < 4; ++m) _Pragma("unroll") for (int k = 0; k < 2; ++k) dst[m][k] = *(const PG8_LAS bf16x8*)(lds + PG8_SA(b, h) + aoff + m * 2048 + k * 1024); } while (0)
; #define PG8_LDB(dst, b, h) do { _Pragma("unroll") for (int n = 0; n < 2; ++n) _Pragma("unroll") for (int k = 0; k < 2; ++k) dst[n][k] = *(const PG8_LAS bf16x8*)(lds + PG8_SB(b, h) + boff + n * 2048 + k * 1024); } while (0)
; #define PG8_MMA(ai, bj, At, Bt) do { __builtin_amdgcn_s_setprio(1); _Pragma("unroll") for (int m = 0; m < 4; ++m) _Pragma("unroll") for (int n = 0; n < 2; ++n) _Pragma("unroll") for (int k = 0; k < 2; ++k) \
;         acc[ai][bj][m][n] = __builtin_amdgcn_mfma_f32_16x16x32_bf16(Bt[n][k], At[m][k], acc[ai][bj][m][n], 0, 0, 0); __builtin_amdgcn_s_setprio(0); } while (0)
; #define PG8_WAIT_V(n) asm volatile("s_waitcnt vmcnt(" #n ")" ::: "memory")
; #define PG8_WAIT_L(n) asm volatile("s_waitcnt lgkmcnt(" #n ")" ::: "memory")
; #define PG8_BAR __builtin_amdgcn_s_barrier()
; #define PG8_SCHED __builtin_amdgcn_sched_barrier(0)
; template <class Epi, class Sched>
; __device__ __forceinline__ void gemm_phase(PG8_LAS unsigned char* lds, PG8_LAS unsigned char* xl, const Gemm g, const Sched& S, const Epi& E) {
;     ...
;             PG8_WAIT_V(8); PG8_WAIT_L(0); PG8_BAR; PG8_MMA(1, 0, At, B0); PG8_MMA(1, 1, At, B1); PG8_BAR; PG8_SCHED;
;             PG8_LDB(B0, 1, 0); PG8_LDB(B1, 1, 1); PG8_SCHED; PG8_LDA(At, 1, 0); PG8_STAGE(PG8_SA(0, 1), a2 + hsA, voffA);
;             PG8_WAIT_V(8); PG8_WAIT_L(0); PG8_BAR; PG8_MMA(0, 0, At, B0); PG8_MMA(0, 1, At, B1); PG8_BAR; PG8_SCHED;
;             PG8_LDA(At, 1, 1); PG8_STAGE(PG8_SB(1, 0), b3, voffB); PG8_STAGE(PG8_SB(1, 1), b3 + hsB, voffB); PG8_STAGE(PG8_SA(1, 0), a3, voffA);
	s_setprio 1
	s_waitcnt lgkmcnt(0)
	v_mfma_f32_16x16x32_bf16 v[60:63], v[154:157], v[186:189], 0
	v_mfma_f32_16x16x32_bf16 v[56:59], v[162:165], v[186:189], 0
	v_mfma_f32_16x16x32_bf16 v[52:55], v[154:157], v[194:197], 0
	v_mfma_f32_16x16x32_bf16 v[44:47], v[162:165], v[194:197], 0
	v_mfma_f32_16x16x32_bf16 v[36:39], v[154:157], v[202:205], 0
	v_mfma_f32_16x16x32_bf16 v[28:31], v[162:165], v[202:205], 0
	v_mfma_f32_16x16x32_bf16 v[20:23], v[154:157], v[210:213], 0
	v_mfma_f32_16x16x32_bf16 v[12:15], v[162:165], v[210:213], 0
	v_mfma_f32_16x16x32_bf16 v[60:63], v[158:161], v[190:193], v[60:63]
	v_mfma_f32_16x16x32_bf16 v[56:59], v[166:169], v[190:193], v[56:59]
	v_mfma_f32_16x16x32_bf16 v[52:55], v[158:161], v[198:201], v[52:55]
	v_mfma_f32_16x16x32_bf16 v[44:47], v[166:169], v[198:201], v[44:47]
	v_mfma_f32_16x16x32_bf16 v[36:39], v[158:161], v[206:209], v[36:39]
	v_mfma_f32_16x16x32_bf16 v[28:31], v[166:169], v[206:209], v[28:31]
	v_mfma_f32_16x16x32_bf16 v[20:23], v[158:161], v[214:217], v[20:23]
	v_mfma_f32_16x16x32_bf16 v[12:15], v[166:169], v[214:217], v[12:15]
	s_setprio 0
	s_setprio 1
	v_mfma_f32_16x16x32_bf16 v[48:51], v[170:173], v[186:189], 0
	v_mfma_f32_16x16x32_bf16 v[40:43], v[178:181], v[186:189], 0
	v_mfma_f32_16x16x32_bf16 v[32:35], v[170:173], v[194:197], 0
	v_mfma_f32_16x16x32_bf16 v[24:27], v[178:181], v[194:197], 0
	v_mfma_f32_16x16x32_bf16 v[16:19], v[170:173], v[202:205], 0
	v_mfma_f32_16x16x32_bf16 v[8:11], v[178:181], v[202:205], 0
	v_mfma_f32_16x16x32_bf16 v[4:7], v[170:173], v[210:213], 0
	v_mfma_f32_16x16x32_bf16 v[0:3], v[178:181], v[210:213], 0
	v_mfma_f32_16x16x32_bf16 v[48:51], v[174:177], v[190:193], v[48:51]
	v_mfma_f32_16x16x32_bf16 v[40:43], v[182:185], v[190:193], v[40:43]
	v_mfma_f32_16x16x32_bf16 v[32:35], v[174:177], v[198:201], v[32:35]
	v_mfma_f32_16x16x32_bf16 v[24:27], v[182:185], v[198:201], v[24:27]
	v_mfma_f32_16x16x32_bf16 v[16:19], v[174:177], v[206:209], v[16:19]
	v_mfma_f32_16x16x32_bf16 v[8:11], v[182:185], v[206:209], v[8:11]
	v_mfma_f32_16x16x32_bf16 v[4:7], v[174:177], v[214:217], v[4:7]
	v_mfma_f32_16x16x32_bf16 v[0:3], v[182:185], v[214:217], v[0:3]
	s_setprio 0
	s_barrier
	s_add_i32 s68, 0, 0x18000
	v_add_u32_e32 v153, s68, v149
	s_add_i32 s78, 0, 0x1c000
	ds_read_b128 v[154:157], v153
	ds_read_b128 v[158:161], v153 offset:1024
	ds_read_b128 v[162:165], v153 offset:2048
	ds_read_b128 v[166:169], v153 offset:3072
	v_add_u32_e32 v153, s78, v149
	ds_read_b128 v[170:173], v153
	ds_read_b128 v[174:177], v153 offset:1024
	ds_read_b128 v[178:181], v153 offset:2048
	ds_read_b128 v[182:185], v153 offset:3072
	s_add_u32 s30, s30, 0x40000
	s_addc_u32 s31, s31, 0
	s_mov_b32 m0, s52
	v_lshl_add_u64 v[226:227], s[30:31], 0, v[128:129]
	ds_read_b128 v[186:189], v152 offset:32768
	ds_read_b128 v[190:193], v152 offset:33792
	ds_read_b128 v[194:197], v152 offset:34816
	ds_read_b128 v[198:201], v152 offset:35840
	ds_read_b128 v[202:205], v152 offset:36864
	ds_read_b128 v[206:209], v152 offset:37888
	ds_read_b128 v[210:213], v152 offset:38912
	ds_read_b128 v[214:217], v152 offset:39936
	global_load_lds_dwordx4 v[226:227], off
	v_lshl_add_u64 v[226:227], s[30:31], 0, v[132:133]
	s_mov_b32 m0, s53
	s_nop 0
	global_load_lds_dwordx4 v[226:227], off
	s_waitcnt vmcnt(8)
	s_waitcnt lgkmcnt(0)
	s_barrier
	s_setprio 1
	s_waitcnt lgkmcnt(0)
	v_mfma_f32_16x16x32_bf16 v[124:127], v[154:157], v[186:189], v[124:127]
	v_mfma_f32_16x16x32_bf16 v[120:123], v[162:165], v[186:189], v[120:123]
	v_mfma_f32_16x16x32_bf16 v[116:119], v[154:157], v[194:197], v[116:119]
	v_mfma_f32_16x16x32_bf16 v[108:111], v[162:165], v[194:197], v[108:111]
	v_mfma_f32_16x16x32_bf16 v[100:103], v[154:157], v[202:205], v[100:103]
	v_mfma_f32_16x16x32_bf16 v[92:95], v[162:165], v[202:205], v[92:95]
	v_mfma_f32_16x16x32_bf16 v[84:87], v[154:157], v[210:213], v[84:87]
	v_mfma_f32_16x16x32_bf16 v[76:79], v[162:165], v[210:213], v[76:79]
	v_mfma_f32_16x16x32_bf16 v[124:127], v[158:161], v[190:193], v[124:127]
	v_mfma_f32_16x16x32_bf16 v[120:123], v[166:169], v[190:193], v[120:123]
	v_mfma_f32_16x16x32_bf16 v[116:119], v[158:161], v[198:201], v[116:119]
	v_mfma_f32_16x16x32_bf16 v[108:111], v[166:169], v[198:201], v[108:111]
	v_mfma_f32_16x16x32_bf16 v[100:103], v[158:161], v[206:209], v[100:103]
	v_mfma_f32_16x16x32_bf16 v[92:95], v[166:169], v[206:209], v[92:95]
	v_mfma_f32_16x16x32_bf16 v[84:87], v[158:161], v[214:217], v[84:87]
	v_mfma_f32_16x16x32_bf16 v[76:79], v[166:169], v[214:217], v[76:79]
	s_setprio 0
	s_setprio 1
	v_mfma_f32_16x16x32_bf16 v[112:115], v[170:173], v[186:189], v[112:115]
	v_mfma_f32_16x16x32_bf16 v[104:107], v[178:181], v[186:189], v[104:107]
	v_mfma_f32_16x16x32_bf16 v[96:99], v[170:173], v[194:197], v[96:99]
	v_mfma_f32_16x16x32_bf16 v[88:91], v[178:181], v[194:197], v[88:91]
	v_mfma_f32_16x16x32_bf16 v[80:83], v[170:173], v[202:205], v[80:83]
	v_mfma_f32_16x16x32_bf16 v[72:75], v[178:181], v[202:205], v[72:75]
	v_mfma_f32_16x16x32_bf16 v[68:71], v[170:173], v[210:213], v[68:71]
	v_mfma_f32_16x16x32_bf16 v[64:67], v[178:181], v[210:213], v[64:67]
	v_mfma_f32_16x16x32_bf16 v[112:115], v[174:177], v[190:193], v[112:115]
	v_mfma_f32_16x16x32_bf16 v[104:107], v[182:185], v[190:193], v[104:107]
	v_mfma_f32_16x16x32_bf16 v[96:99], v[174:177], v[198:201], v[96:99]
	v_mfma_f32_16x16x32_bf16 v[88:91], v[182:185], v[198:201], v[88:91]
	v_mfma_f32_16x16x32_bf16 v[80:83], v[174:177], v[206:209], v[80:83]
	v_mfma_f32_16x16x32_bf16 v[72:75], v[182:185], v[206:209], v[72:75]
	v_mfma_f32_16x16x32_bf16 v[68:71], v[174:177], v[214:217], v[68:71]
	v_mfma_f32_16x16x32_bf16 v[64:67], v[182:185], v[214:217], v[64:67]
	s_setprio 0
	s_barrier
; #define PG8_STAGE(bufoff, gbase, voff) do { _Pragma("unroll") for (int _i = 0; _i < 2; ++_i) \
;         __builtin_amdgcn_global_load_lds((const unsigned*)((const char*)(gbase) + (voff)[_i]), (PG8_LAS unsigned*)(lds + (bufoff) + ldsw + _i * 8192), 16, 0, 0); } while (0)
; #define PG8_LDA(dst, b, h) do { _Pragma("unroll") for (int m = 0; m < 4; ++m) _Pragma("unroll") for (int k = 0; k < 2; ++k) dst[m][k] = *(const PG8_LAS bf16x8*)(lds + PG8_SA(b, h) + aoff + m * 2048 + k * 1024); } while (0)
; #define PG8_MMA(ai, bj, At, Bt) do { __builtin_amdgcn_s_setprio(1); _Pragma("unroll") for (int m = 0; m < 4; ++m) _Pragma("unroll") for (int n = 0; n < 2; ++n) _Pragma("unroll") for (int k = 0; k < 2; ++k) \
;         acc[ai][bj][m][n] = __builtin_amdgcn_mfma_f32_16x16x32_bf16(Bt[n][k], At[m][k], acc[ai][bj][m][n], 0, 0, 0); __builtin_amdgcn_s_setprio(0); } while (0)
; #define PG8_WAIT_V(n) asm volatile("s_waitcnt vmcnt(" #n ")" ::: "memory")
; #define PG8_WAIT_L(n) asm volatile("s_waitcnt lgkmcnt(" #n ")" ::: "memory")
; #define PG8_BAR __builtin_amdgcn_s_barrier()
; #define PG8_SCHED __builtin_amdgcn_sched_barrier(0)
; template <class Epi, class Sched>
; __device__ __forceinline__ void gemm_phase(PG8_LAS unsigned char* lds, PG8_LAS unsigned char* xl, const Gemm g, const Sched& S, const Epi& E) {
;     ...
;             PG8_LDA(At, 1, 1); PG8_STAGE(PG8_SB(1, 0), b3, voffB); PG8_STAGE(PG8_SB(1, 1), b3 + hsB, voffB); PG8_STAGE(PG8_SA(1, 0), a3, voffA);
;             PG8_WAIT_V(8); PG8_WAIT_L(0); PG8_BAR; PG8_MMA(1, 0, At, B0); PG8_MMA(1, 1, At, B1); PG8_BAR; PG8_SCHED;
;         }
	s_add_i32 s30, s68, s43
	v_lshl_add_u64 v[146:147], v[146:147], 0, s[10:11]
	s_mov_b32 m0, s30
	ds_read_b128 v[186:189], v152 offset:49152
	ds_read_b128 v[190:193], v152 offset:50176
	ds_read_b128 v[194:197], v152 offset:51200
	ds_read_b128 v[198:201], v152 offset:52224
	ds_read_b128 v[202:205], v152 offset:53248
	ds_read_b128 v[206:209], v152 offset:54272
	ds_read_b128 v[210:213], v152 offset:55296
	ds_read_b128 v[214:217], v152 offset:56320
	global_load_lds_dwordx4 v[146:147], off
	s_add_i32 m0, s30, 0x2000
	s_add_u32 s28, s28, 0x40080
	v_lshl_add_u64 v[146:147], v[218:219], 0, s[10:11]
	s_addc_u32 s29, s29, 0
	s_add_i32 s30, s78, s43
	global_load_lds_dwordx4 v[146:147], off
	v_lshl_add_u64 v[146:147], s[28:29], 0, v[130:131]
	s_mov_b32 m0, s30
	s_nop 0
	global_load_lds_dwordx4 v[146:147], off
	v_lshl_add_u64 v[146:147], s[28:29], 0, v[134:135]
	s_add_i32 m0, s30, 0x2000
	s_nop 0
	global_load_lds_dwordx4 v[146:147], off
	v_lshl_add_u64 v[146:147], v[222:223], 0, s[10:11]
	s_mov_b32 m0, s55
	s_nop 0
	global_load_lds_dwordx4 v[146:147], off
	v_lshl_add_u64 v[146:147], v[224:225], 0, s[10:11]
	s_mov_b32 m0, s56
	s_nop 0
	global_load_lds_dwordx4 v[146:147], off
	s_waitcnt vmcnt(8)
	s_waitcnt lgkmcnt(0)
	s_barrier
	s_setprio 1
	s_waitcnt lgkmcnt(0)
	v_mfma_f32_16x16x32_bf16 v[60:63], v[154:157], v[186:189], v[60:63]
	v_mfma_f32_16x16x32_bf16 v[56:59], v[162:165], v[186:189], v[56:59]
	v_mfma_f32_16x16x32_bf16 v[52:55], v[154:157], v[194:197], v[52:55]
	v_mfma_f32_16x16x32_bf16 v[44:47], v[162:165], v[194:197], v[44:47]
	v_mfma_f32_16x16x32_bf16 v[36:39], v[154:157], v[202:205], v[36:39]
	v_mfma_f32_16x16x32_bf16 v[28:31], v[162:165], v[202:205], v[28:31]
	v_mfma_f32_16x16x32_bf16 v[20:23], v[154:157], v[210:213], v[20:23]
	v_mfma_f32_16x16x32_bf16 v[12:15], v[162:165], v[210:213], v[12:15]
	v_mfma_f32_16x16x32_bf16 v[60:63], v[158:161], v[190:193], v[60:63]
	v_mfma_f32_16x16x32_bf16 v[56:59], v[166:169], v[190:193], v[56:59]
	v_mfma_f32_16x16x32_bf16 v[52:55], v[158:161], v[198:201], v[52:55]
	v_mfma_f32_16x16x32_bf16 v[44:47], v[166:169], v[198:201], v[44:47]
	v_mfma_f32_16x16x32_bf16 v[36:39], v[158:161], v[206:209], v[36:39]
	v_mfma_f32_16x16x32_bf16 v[28:31], v[166:169], v[206:209], v[28:31]
	v_mfma_f32_16x16x32_bf16 v[20:23], v[158:161], v[214:217], v[20:23]
	v_mfma_f32_16x16x32_bf16 v[12:15], v[166:169], v[214:217], v[12:15]
	s_setprio 0
	s_setprio 1
	v_mfma_f32_16x16x32_bf16 v[48:51], v[170:173], v[186:189], v[48:51]
	v_mfma_f32_16x16x32_bf16 v[40:43], v[178:181], v[186:189], v[40:43]
	v_mfma_f32_16x16x32_bf16 v[32:35], v[170:173], v[194:197], v[32:35]
	v_mfma_f32_16x16x32_bf16 v[24:27], v[178:181], v[194:197], v[24:27]
	v_mfma_f32_16x16x32_bf16 v[16:19], v[170:173], v[202:205], v[16:19]
	v_mfma_f32_16x16x32_bf16 v[8:11], v[178:181], v[202:205], v[8:11]
	v_mfma_f32_16x16x32_bf16 v[4:7], v[170:173], v[210:213], v[4:7]
	v_mfma_f32_16x16x32_bf16 v[0:3], v[178:181], v[210:213], v[0:3]
	v_mfma_f32_16x16x32_bf16 v[48:51], v[174:177], v[190:193], v[48:51]
	v_mfma_f32_16x16x32_bf16 v[40:43], v[182:185], v[190:193], v[40:43]
	v_mfma_f32_16x16x32_bf16 v[32:35], v[174:177], v[198:201], v[32:35]
	v_mfma_f32_16x16x32_bf16 v[24:27], v[182:185], v[198:201], v[24:27]
	v_mfma_f32_16x16x32_bf16 v[16:19], v[174:177], v[206:209], v[16:19]
	v_mfma_f32_16x16x32_bf16 v[8:11], v[182:185], v[206:209], v[8:11]
	v_mfma_f32_16x16x32_bf16 v[4:7], v[174:177], v[214:217], v[4:7]
	v_mfma_f32_16x16x32_bf16 v[0:3], v[182:185], v[214:217], v[0:3]
	s_setprio 0
	s_barrier
	s_add_i32 s77, s77, 2
	s_add_u32 s75, s75, 0x100
	s_addc_u32 s76, s76, 0
	s_add_u32 s26, s26, 0x100
	s_addc_u32 s27, s27, 0
	s_cmp_gt_u32 s77, 13
	s_cbranch_scc1 .Lpeel_after_P11

; #define PG8_BAR __builtin_amdgcn_s_barrier()
; template <class Epi, class Sched>
; __device__ __forceinline__ void gemm_phase(PG8_LAS unsigned char* lds, PG8_LAS unsigned char* xl, const Gemm g, const Sched& S, const Epi& E) {
;     ...
;         if (wr == 0) PG8_BAR;
.Lpeel_after_P11:
	s_and_b64 vcc, exec, s[12:13]
	s_cbranch_vccz .LBB0_133
	s_barrier

; #define PG8_STAGE(bufoff, gbase, voff) do { _Pragma("unroll") for (int _i = 0; _i < 2; ++_i) \
;         __builtin_amdgcn_global_load_lds((const unsigned*)((const char*)(gbase) + (voff)[_i]), (PG8_LAS unsigned*)(lds + (bufoff) + ldsw + _i * 8192), 16, 0, 0); } while (0)
; #define PG8_LDA(dst, b, h) do { _Pragma("unroll") for (int m = 0; m < 4; ++m) _Pragma("unroll") for (int k = 0; k < 2; ++k) dst[m][k] = *(const PG8_LAS bf16x8*)(lds + PG8_SA(b, h) + aoff + m * 2048 + k * 1024); } while (0)
; #define PG8_LDB(dst, b, h) do { _Pragma("unroll") for (int n = 0; n < 2; ++n) _Pragma("unroll") for (int k = 0; k < 2; ++k) dst[n][k] = *(const PG8_LAS bf16x8*)(lds + PG8_SB(b, h) + boff + n * 2048 + k * 1024); } while (0)
; #define PG8_MMA(ai, bj, At, Bt) do { __builtin_amdgcn_s_setprio(1); _Pragma("unroll") for (int m = 0; m < 4; ++m) _Pragma("unroll") for (int n = 0; n < 2; ++n) _Pragma("unroll") for (int k = 0; k < 2; ++k) \
;         acc[ai][bj][m][n] = __builtin_amdgcn_mfma_f32_16x16x32_bf16(Bt[n][k], At[m][k], acc[ai][bj][m][n], 0, 0, 0); __builtin_amdgcn_s_setprio(0); } while (0)
; #define PG8_BAR __builtin_amdgcn_s_barrier()
; template <class Epi, class Sched>
; __device__ __forceinline__ void gemm_phase(PG8_LAS unsigned char* lds, PG8_LAS unsigned char* xl, const Gemm g, const Sched& S, const Epi& E) {
;     ...
;         const bool has_next = S.next(ui + 1, nxt);
;         const char* nA = has_next ? (const char*)g.A + nxt.aoff : cA; const char* nB = has_next ? (const char*)g.Bt + nxt.boff : cB;
; #pragma unroll 1
;         for (int t = 0; t < nt; t += 2) {
;             const bool last = (t == nt - 2);
;             const char* a1 = cA + (size_t)(t + 1) * kstep;
;             const char* a2 = last ? nA : cA + (size_t)(t + 2) * kstep; const char* b2 = last ? nB : cB + (size_t)(t + 2) * kstep;
;             const char* a3 = a2 + kstep; const char* b3 = b2 + kstep;
;             PG8_LDB(B0, 0, 0); PG8_LDB(B1, 0, 1); PG8_SCHED; PG8_LDA(At, 0, 0); PG8_STAGE(PG8_SA(1, 1), a1 + hsA, voffA);
;             PG8_WAIT_V(8); PG8_WAIT_L(0); PG8_BAR; PG8_MMA(0, 0, At, B0); PG8_MMA(0, 1, At, B1); PG8_BAR; PG8_SCHED;
;             PG8_LDA(At, 0, 1); PG8_STAGE(PG8_SB(0, 0), b2, voffB); PG8_STAGE(PG8_SB(0, 1), b2 + hsB, voffB); PG8_STAGE(PG8_SA(0, 0), a2, voffA);
;             PG8_WAIT_V(8); PG8_WAIT_L(0); PG8_BAR; PG8_MMA(1, 0, At, B0); PG8_MMA(1, 1, At, B1); PG8_BAR; PG8_SCHED;
.LBB0_376:
	s_add_u32 s20, s2, s16
	s_addc_u32 s21, s3, s17
	s_and_b64 s[22:23], s[4:5], exec
	s_cselect_b32 s82, s21, s31
	s_cselect_b32 s83, s20, s30
	s_add_u32 s22, s2, s18
	s_addc_u32 s23, s3, s19
	s_and_b64 s[34:35], s[4:5], exec
	v_mov_b32_e32 v0, 0
	s_cselect_b32 s84, s23, s29
	s_cselect_b32 s85, s22, s28
	s_mov_b64 s[50:51], 0
	s_mov_b64 s[34:35], -1
	s_mov_b64 s[36:37], 0
	s_add_u32 s56, s30, s50
	s_addc_u32 s57, s31, s51
	s_add_u32 s54, s56, 0x100
	s_addc_u32 s55, s57, 0
	s_and_b64 s[52:53], s[36:37], exec
	s_cselect_b32 s53, s82, s55
	s_cselect_b32 s52, s83, s54
	s_add_u32 s50, s28, s50
	s_addc_u32 s51, s29, s51
	s_add_u32 s50, s50, 0x100
	s_addc_u32 s51, s51, 0
	s_and_b64 s[36:37], s[36:37], exec
	s_cselect_b32 s55, s84, s51
	s_cselect_b32 s54, s85, s50
	s_add_u32 s58, s56, 0x80080
	ds_read_b128 v[152:155], v147
	ds_read_b128 v[156:159], v147 offset:1024
	ds_read_b128 v[160:163], v147 offset:2048
	ds_read_b128 v[164:167], v147 offset:3072
	ds_read_b128 v[168:171], v148
	ds_read_b128 v[172:175], v148 offset:1024
	ds_read_b128 v[176:179], v148 offset:2048
	ds_read_b128 v[180:183], v148 offset:3072
	s_addc_u32 s59, s57, 0
	s_add_i32 s94, s73, s33
	s_add_i32 m0, s43, 0xc000
	s_add_i32 s95, s43, 0xe000
	s_add_i32 s91, s94, 0x2000
	s_add_u32 s56, s54, 0x80000
	s_addc_u32 s57, s55, 0
	s_add_i32 s93, s74, s33
	s_add_i32 s92, s93, 0x2000
	s_add_i32 s90, 0, 0x18000
	s_add_i32 s89, 0, 0x1c000
	s_add_u32 s50, s52, 0x80000
	s_addc_u32 s51, s53, 0
	s_add_i32 s88, s90, s33
	s_add_i32 s86, s88, 0x2000
	s_add_u32 s36, s54, 0x80080
	s_addc_u32 s37, s55, 0
	s_add_i32 s87, s89, s33
	s_add_i32 s68, s87, 0x2000
	v_lshl_add_u64 v[144:145], s[58:59], 0, v[128:129]
	ds_read_b128 v[184:187], v149
	ds_read_b128 v[188:191], v149 offset:1024
	ds_read_b128 v[192:195], v149 offset:2048
	ds_read_b128 v[196:199], v149 offset:3072
	ds_read_b128 v[200:203], v149 offset:4096
	ds_read_b128 v[204:207], v149 offset:5120
	ds_read_b128 v[208:211], v149 offset:6144
	ds_read_b128 v[212:215], v149 offset:7168
	global_load_lds_dwordx4 v[144:145], off
	v_lshl_add_u64 v[144:145], s[58:59], 0, v[132:133]
	s_mov_b32 m0, s95
	s_nop 0
	global_load_lds_dwordx4 v[144:145], off
	s_waitcnt vmcnt(8)
	s_waitcnt lgkmcnt(0)
	s_barrier
	s_setprio 1
	s_waitcnt lgkmcnt(0)
	v_mfma_f32_16x16x32_bf16 v[124:127], v[152:155], v[184:187], 0
	v_mfma_f32_16x16x32_bf16 v[120:123], v[160:163], v[184:187], 0
	v_mfma_f32_16x16x32_bf16 v[112:115], v[152:155], v[192:195], 0
	v_mfma_f32_16x16x32_bf16 v[104:107], v[160:163], v[192:195], 0
	v_mfma_f32_16x16x32_bf16 v[96:99], v[152:155], v[200:203], 0
	v_mfma_f32_16x16x32_bf16 v[88:91], v[160:163], v[200:203], 0
	v_mfma_f32_16x16x32_bf16 v[80:83], v[152:155], v[208:211], 0
	v_mfma_f32_16x16x32_bf16 v[72:75], v[160:163], v[208:211], 0
	v_mfma_f32_16x16x32_bf16 v[124:127], v[156:159], v[188:191], v[124:127]
	v_mfma_f32_16x16x32_bf16 v[120:123], v[164:167], v[188:191], v[120:123]
	v_mfma_f32_16x16x32_bf16 v[112:115], v[156:159], v[196:199], v[112:115]
	v_mfma_f32_16x16x32_bf16 v[104:107], v[164:167], v[196:199], v[104:107]
	v_mfma_f32_16x16x32_bf16 v[96:99], v[156:159], v[204:207], v[96:99]
	v_mfma_f32_16x16x32_bf16 v[88:91], v[164:167], v[204:207], v[88:91]
	v_mfma_f32_16x16x32_bf16 v[80:83], v[156:159], v[212:215], v[80:83]
	v_mfma_f32_16x16x32_bf16 v[72:75], v[164:167], v[212:215], v[72:75]
	s_setprio 0
	s_setprio 1
	v_mfma_f32_16x16x32_bf16 v[116:119], v[168:171], v[184:187], 0
	v_mfma_f32_16x16x32_bf16 v[108:111], v[176:179], v[184:187], 0
	v_mfma_f32_16x16x32_bf16 v[100:103], v[168:171], v[192:195], 0
	v_mfma_f32_16x16x32_bf16 v[92:95], v[176:179], v[192:195], 0
	v_mfma_f32_16x16x32_bf16 v[84:87], v[168:171], v[200:203], 0
	v_mfma_f32_16x16x32_bf16 v[76:79], v[176:179], v[200:203], 0
	v_mfma_f32_16x16x32_bf16 v[68:71], v[168:171], v[208:211], 0
	v_mfma_f32_16x16x32_bf16 v[64:67], v[176:179], v[208:211], 0
	v_mfma_f32_16x16x32_bf16 v[116:119], v[172:175], v[188:191], v[116:119]
	v_mfma_f32_16x16x32_bf16 v[108:111], v[180:183], v[188:191], v[108:111]
	v_mfma_f32_16x16x32_bf16 v[100:103], v[172:175], v[196:199], v[100:103]
	v_mfma_f32_16x16x32_bf16 v[92:95], v[180:183], v[196:199], v[92:95]
	v_mfma_f32_16x16x32_bf16 v[84:87], v[172:175], v[204:207], v[84:87]
	v_mfma_f32_16x16x32_bf16 v[76:79], v[180:183], v[204:207], v[76:79]
	v_mfma_f32_16x16x32_bf16 v[68:71], v[172:175], v[212:215], v[68:71]
	v_mfma_f32_16x16x32_bf16 v[64:67], v[180:183], v[212:215], v[64:67]
	s_setprio 0
	s_barrier
	s_mov_b32 m0, s94
	v_lshl_add_u64 v[144:145], s[54:55], 0, v[130:131]
	ds_read_b128 v[184:187], v149 offset:16384
	ds_read_b128 v[188:191], v149 offset:17408
	ds_read_b128 v[192:195], v149 offset:18432
	ds_read_b128 v[196:199], v149 offset:19456
	ds_read_b128 v[200:203], v149 offset:20480
	ds_read_b128 v[204:207], v149 offset:21504
	ds_read_b128 v[208:211], v149 offset:22528
	ds_read_b128 v[212:215], v149 offset:23552
	global_load_lds_dwordx4 v[144:145], off
	v_lshl_add_u64 v[216:217], s[54:55], 0, v[134:135]
	s_mov_b32 m0, s91
	v_lshl_add_u64 v[218:219], s[56:57], 0, v[130:131]
	global_load_lds_dwordx4 v[216:217], off
	s_mov_b32 m0, s93
	v_lshl_add_u64 v[222:223], s[52:53], 0, v[132:133]
	global_load_lds_dwordx4 v[218:219], off
	v_lshl_add_u64 v[218:219], s[56:57], 0, v[134:135]
	s_mov_b32 m0, s92
	s_nop 0
	global_load_lds_dwordx4 v[218:219], off
	v_lshl_add_u64 v[218:219], s[52:53], 0, v[128:129]
	s_mov_b32 m0, s43
	s_nop 0
	global_load_lds_dwordx4 v[218:219], off
	s_mov_b32 m0, s46
	s_nop 0
	global_load_lds_dwordx4 v[222:223], off
	s_waitcnt vmcnt(8)
	s_waitcnt lgkmcnt(0)
	s_barrier
; #define PG8_STAGE(bufoff, gbase, voff) do { _Pragma("unroll") for (int _i = 0; _i < 2; ++_i) \
;         __builtin_amdgcn_global_load_lds((const unsigned*)((const char*)(gbase) + (voff)[_i]), (PG8_LAS unsigned*)(lds + (bufoff) + ldsw + _i * 8192), 16, 0, 0); } while (0)
; #define PG8_LDA(dst, b, h) do { _Pragma("unroll") for (int m = 0; m < 4; ++m) _Pragma("unroll") for (int k = 0; k < 2; ++k) dst[m][k] = *(const PG8_LAS bf16x8*)(lds + PG8_SA(b, h) + aoff + m * 2048 + k * 1024); } while (0)
; #define PG8_LDB(dst, b, h) do { _Pragma("unroll") for (int n = 0; n < 2; ++n) _Pragma("unroll") for (int k = 0; k < 2; ++k) dst[n][k] = *(const PG8_LAS bf16x8*)(lds + PG8_SB(b, h) + boff + n * 2048 + k * 1024); } while (0)
; #define PG8_MMA(ai, bj, At, Bt) do { __builtin_amdgcn_s_setprio(1); _Pragma("unroll") for (int m = 0; m < 4; ++m) _Pragma("unroll") for (int n = 0; n < 2; ++n) _Pragma("unroll") for (int k = 0; k < 2; ++k) \
;         acc[ai][bj][m][n] = __builtin_amdgcn_mfma_f32_16x16x32_bf16(Bt[n][k], At[m][k], acc[ai][bj][m][n], 0, 0, 0); __builtin_amdgcn_s_setprio(0); } while (0)
; #define PG8_WAIT_V(n) asm volatile("s_waitcnt vmcnt(" #n ")" ::: "memory")
; #define PG8_WAIT_L(n) asm volatile("s_waitcnt lgkmcnt(" #n ")" ::: "memory")
; #define PG8_BAR __builtin_amdgcn_s_barrier()
; #define PG8_SCHED __builtin_amdgcn_sched_barrier(0)
; template <class Epi, class Sched>
; __device__ __forceinline__ void gemm_phase(PG8_LAS unsigned char* lds, PG8_LAS unsigned char* xl, const Gemm g, const Sched& S, const Epi& E) {
;     ...
;             PG8_WAIT_V(8); PG8_WAIT_L(0); PG8_BAR; PG8_MMA(1, 0, At, B0); PG8_MMA(1, 1, At, B1); PG8_BAR; PG8_SCHED;
;             PG8_LDB(B0, 1, 0); PG8_LDB(B1, 1, 1); PG8_SCHED; PG8_LDA(At, 1, 0); PG8_STAGE(PG8_SA(0, 1), a2 + hsA, voffA);
;             PG8_WAIT_V(8); PG8_WAIT_L(0); PG8_BAR; PG8_MMA(0, 0, At, B0); PG8_MMA(0, 1, At, B1); PG8_BAR; PG8_SCHED;
;             PG8_LDA(At, 1, 1); PG8_STAGE(PG8_SB(1, 0), b3, voffB); PG8_STAGE(PG8_SB(1, 1), b3 + hsB, voffB); PG8_STAGE(PG8_SA(1, 0), a3, voffA);
	s_setprio 1
	s_waitcnt lgkmcnt(0)
	v_mfma_f32_16x16x32_bf16 v[60:63], v[152:155], v[184:187], 0
	v_mfma_f32_16x16x32_bf16 v[56:59], v[160:163], v[184:187], 0
	v_mfma_f32_16x16x32_bf16 v[48:51], v[152:155], v[192:195], 0
	v_mfma_f32_16x16x32_bf16 v[40:43], v[160:163], v[192:195], 0
	v_mfma_f32_16x16x32_bf16 v[32:35], v[152:155], v[200:203], 0
	v_mfma_f32_16x16x32_bf16 v[24:27], v[160:163], v[200:203], 0
	v_mfma_f32_16x16x32_bf16 v[16:19], v[152:155], v[208:211], 0
	v_mfma_f32_16x16x32_bf16 v[8:11], v[160:163], v[208:211], 0
	v_mfma_f32_16x16x32_bf16 v[60:63], v[156:159], v[188:191], v[60:63]
	v_mfma_f32_16x16x32_bf16 v[56:59], v[164:167], v[188:191], v[56:59]
	v_mfma_f32_16x16x32_bf16 v[48:51], v[156:159], v[196:199], v[48:51]
	v_mfma_f32_16x16x32_bf16 v[40:43], v[164:167], v[196:199], v[40:43]
	v_mfma_f32_16x16x32_bf16 v[32:35], v[156:159], v[204:207], v[32:35]
	v_mfma_f32_16x16x32_bf16 v[24:27], v[164:167], v[204:207], v[24:27]
	v_mfma_f32_16x16x32_bf16 v[16:19], v[156:159], v[212:215], v[16:19]
	v_mfma_f32_16x16x32_bf16 v[8:11], v[164:167], v[212:215], v[8:11]
	s_setprio 0
	s_setprio 1
	v_mfma_f32_16x16x32_bf16 v[52:55], v[168:171], v[184:187], 0
	v_mfma_f32_16x16x32_bf16 v[44:47], v[176:179], v[184:187], 0
	v_mfma_f32_16x16x32_bf16 v[36:39], v[168:171], v[192:195], 0
	v_mfma_f32_16x16x32_bf16 v[28:31], v[176:179], v[192:195], 0
	v_mfma_f32_16x16x32_bf16 v[20:23], v[168:171], v[200:203], 0
	v_mfma_f32_16x16x32_bf16 v[12:15], v[176:179], v[200:203], 0
	v_mfma_f32_16x16x32_bf16 v[4:7], v[168:171], v[208:211], 0
	v_mfma_f32_16x16x32_bf16 v[0:3], v[176:179], v[208:211], 0
	v_mfma_f32_16x16x32_bf16 v[52:55], v[172:175], v[188:191], v[52:55]
	v_mfma_f32_16x16x32_bf16 v[44:47], v[180:183], v[188:191], v[44:47]
	v_mfma_f32_16x16x32_bf16 v[36:39], v[172:175], v[196:199], v[36:39]
	v_mfma_f32_16x16x32_bf16 v[28:31], v[180:183], v[196:199], v[28:31]
	v_mfma_f32_16x16x32_bf16 v[20:23], v[172:175], v[204:207], v[20:23]
	v_mfma_f32_16x16x32_bf16 v[12:15], v[180:183], v[204:207], v[12:15]
	v_mfma_f32_16x16x32_bf16 v[4:7], v[172:175], v[212:215], v[4:7]
	v_mfma_f32_16x16x32_bf16 v[0:3], v[180:183], v[212:215], v[0:3]
	s_setprio 0
	s_barrier
	v_add_u32_e32 v142, s90, v146
	ds_read_b128 v[152:155], v142
	ds_read_b128 v[156:159], v142 offset:1024
	ds_read_b128 v[160:163], v142 offset:2048
	ds_read_b128 v[164:167], v142 offset:3072
	v_add_u32_e32 v142, s89, v146
	ds_read_b128 v[168:171], v142
	ds_read_b128 v[172:175], v142 offset:1024
	ds_read_b128 v[176:179], v142 offset:2048
	ds_read_b128 v[180:183], v142 offset:3072
	s_mov_b32 m0, s47
	v_lshl_add_u64 v[224:225], s[50:51], 0, v[128:129]
	ds_read_b128 v[184:187], v149 offset:32768
	ds_read_b128 v[188:191], v149 offset:33792
	ds_read_b128 v[192:195], v149 offset:34816
	ds_read_b128 v[196:199], v149 offset:35840
	ds_read_b128 v[200:203], v149 offset:36864
	ds_read_b128 v[204:207], v149 offset:37888
	ds_read_b128 v[208:211], v149 offset:38912
	ds_read_b128 v[212:215], v149 offset:39936
	global_load_lds_dwordx4 v[224:225], off
	v_lshl_add_u64 v[224:225], s[50:51], 0, v[132:133]
	s_mov_b32 m0, s60
	s_nop 0
	global_load_lds_dwordx4 v[224:225], off
	s_waitcnt vmcnt(8)
	s_waitcnt lgkmcnt(0)
	s_barrier
	s_setprio 1
	s_waitcnt lgkmcnt(0)
	v_mfma_f32_16x16x32_bf16 v[124:127], v[152:155], v[184:187], v[124:127]
	v_mfma_f32_16x16x32_bf16 v[120:123], v[160:163], v[184:187], v[120:123]
	v_mfma_f32_16x16x32_bf16 v[112:115], v[152:155], v[192:195], v[112:115]
	v_mfma_f32_16x16x32_bf16 v[104:107], v[160:163], v[192:195], v[104:107]
	v_mfma_f32_16x16x32_bf16 v[96:99], v[152:155], v[200:203], v[96:99]
	v_mfma_f32_16x16x32_bf16 v[88:91], v[160:163], v[200:203], v[88:91]
	v_mfma_f32_16x16x32_bf16 v[80:83], v[152:155], v[208:211], v[80:83]
	v_mfma_f32_16x16x32_bf16 v[72:75], v[160:163], v[208:211], v[72:75]
	v_mfma_f32_16x16x32_bf16 v[124:127], v[156:159], v[188:191], v[124:127]
	v_mfma_f32_16x16x32_bf16 v[120:123], v[164:167], v[188:191], v[120:123]
	v_mfma_f32_16x16x32_bf16 v[112:115], v[156:159], v[196:199], v[112:115]
	v_mfma_f32_16x16x32_bf16 v[104:107], v[164:167], v[196:199], v[104:107]
	v_mfma_f32_16x16x32_bf16 v[96:99], v[156:159], v[204:207], v[96:99]
	v_mfma_f32_16x16x32_bf16 v[88:91], v[164:167], v[204:207], v[88:91]
	v_mfma_f32_16x16x32_bf16 v[80:83], v[156:159], v[212:215], v[80:83]
	v_mfma_f32_16x16x32_bf16 v[72:75], v[164:167], v[212:215], v[72:75]
	s_setprio 0
	s_setprio 1
	v_mfma_f32_16x16x32_bf16 v[116:119], v[168:171], v[184:187], v[116:119]
	v_mfma_f32_16x16x32_bf16 v[108:111], v[176:179], v[184:187], v[108:111]
	v_mfma_f32_16x16x32_bf16 v[100:103], v[168:171], v[192:195], v[100:103]
	v_mfma_f32_16x16x32_bf16 v[92:95], v[176:179], v[192:195], v[92:95]
	v_mfma_f32_16x16x32_bf16 v[84:87], v[168:171], v[200:203], v[84:87]
	v_mfma_f32_16x16x32_bf16 v[76:79], v[176:179], v[200:203], v[76:79]
	v_mfma_f32_16x16x32_bf16 v[68:71], v[168:171], v[208:211], v[68:71]
	v_mfma_f32_16x16x32_bf16 v[64:67], v[176:179], v[208:211], v[64:67]
	v_mfma_f32_16x16x32_bf16 v[116:119], v[172:175], v[188:191], v[116:119]
	v_mfma_f32_16x16x32_bf16 v[108:111], v[180:183], v[188:191], v[108:111]
	v_mfma_f32_16x16x32_bf16 v[100:103], v[172:175], v[196:199], v[100:103]
	v_mfma_f32_16x16x32_bf16 v[92:95], v[180:183], v[196:199], v[92:95]
	v_mfma_f32_16x16x32_bf16 v[84:87], v[172:175], v[204:207], v[84:87]
	v_mfma_f32_16x16x32_bf16 v[76:79], v[180:183], v[204:207], v[76:79]
	v_mfma_f32_16x16x32_bf16 v[68:71], v[172:175], v[212:215], v[68:71]
	v_mfma_f32_16x16x32_bf16 v[64:67], v[180:183], v[212:215], v[64:67]
	s_setprio 0
	s_barrier
; #define PG8_STAGE(bufoff, gbase, voff) do { _Pragma("unroll") for (int _i = 0; _i < 2; ++_i) \
;         __builtin_amdgcn_global_load_lds((const unsigned*)((const char*)(gbase) + (voff)[_i]), (PG8_LAS unsigned*)(lds + (bufoff) + ldsw + _i * 8192), 16, 0, 0); } while (0)
; #define PG8_LDA(dst, b, h) do { _Pragma("unroll") for (int m = 0; m < 4; ++m) _Pragma("unroll") for (int k = 0; k < 2; ++k) dst[m][k] = *(const PG8_LAS bf16x8*)(lds + PG8_SA(b, h) + aoff + m * 2048 + k * 1024); } while (0)
; #define PG8_MMA(ai, bj, At, Bt) do { __builtin_amdgcn_s_setprio(1); _Pragma("unroll") for (int m = 0; m < 4; ++m) _Pragma("unroll") for (int n = 0; n < 2; ++n) _Pragma("unroll") for (int k = 0; k < 2; ++k) \
;         acc[ai][bj][m][n] = __builtin_amdgcn_mfma_f32_16x16x32_bf16(Bt[n][k], At[m][k], acc[ai][bj][m][n], 0, 0, 0); __builtin_amdgcn_s_setprio(0); } while (0)
; #define PG8_WAIT_V(n) asm volatile("s_waitcnt vmcnt(" #n ")" ::: "memory")
; #define PG8_WAIT_L(n) asm volatile("s_waitcnt lgkmcnt(" #n ")" ::: "memory")
; #define PG8_BAR __builtin_amdgcn_s_barrier()
; #define PG8_SCHED __builtin_amdgcn_sched_barrier(0)
; template <class Epi, class Sched>
; __device__ __forceinline__ void gemm_phase(PG8_LAS unsigned char* lds, PG8_LAS unsigned char* xl, const Gemm g, const Sched& S, const Epi& E) {
;     ...
;             PG8_LDA(At, 1, 1); PG8_STAGE(PG8_SB(1, 0), b3, voffB); PG8_STAGE(PG8_SB(1, 1), b3 + hsB, voffB); PG8_STAGE(PG8_SA(1, 0), a3, voffA);
;             PG8_WAIT_V(8); PG8_WAIT_L(0); PG8_BAR; PG8_MMA(1, 0, At, B0); PG8_MMA(1, 1, At, B1); PG8_BAR; PG8_SCHED;
;         }
	s_mov_b32 m0, s88
	v_lshl_add_u64 v[144:145], v[144:145], 0, s[10:11]
	ds_read_b128 v[184:187], v149 offset:49152
	ds_read_b128 v[188:191], v149 offset:50176
	ds_read_b128 v[192:195], v149 offset:51200
	ds_read_b128 v[196:199], v149 offset:52224
	ds_read_b128 v[200:203], v149 offset:53248
	ds_read_b128 v[204:207], v149 offset:54272
	ds_read_b128 v[208:211], v149 offset:55296
	ds_read_b128 v[212:215], v149 offset:56320
	global_load_lds_dwordx4 v[144:145], off
	v_lshl_add_u64 v[144:145], v[216:217], 0, s[10:11]
	s_mov_b32 m0, s86
	s_nop 0
	global_load_lds_dwordx4 v[144:145], off
	v_lshl_add_u64 v[144:145], s[36:37], 0, v[130:131]
	s_mov_b32 m0, s87
	s_nop 0
	global_load_lds_dwordx4 v[144:145], off
	v_lshl_add_u64 v[144:145], s[36:37], 0, v[134:135]
	s_mov_b32 m0, s68
	s_nop 0
	global_load_lds_dwordx4 v[144:145], off
	v_lshl_add_u64 v[144:145], v[218:219], 0, s[10:11]
	s_mov_b32 m0, s65
	s_nop 0
	global_load_lds_dwordx4 v[144:145], off
	v_lshl_add_u64 v[144:145], v[222:223], 0, s[10:11]
	s_mov_b32 m0, s66
	s_nop 0
	global_load_lds_dwordx4 v[144:145], off
	s_waitcnt vmcnt(8)
	s_waitcnt lgkmcnt(0)
	s_barrier
	s_setprio 1
	s_waitcnt lgkmcnt(0)
	v_mfma_f32_16x16x32_bf16 v[60:63], v[152:155], v[184:187], v[60:63]
	v_mfma_f32_16x16x32_bf16 v[56:59], v[160:163], v[184:187], v[56:59]
	v_mfma_f32_16x16x32_bf16 v[48:51], v[152:155], v[192:195], v[48:51]
	v_mfma_f32_16x16x32_bf16 v[40:43], v[160:163], v[192:195], v[40:43]
	v_mfma_f32_16x16x32_bf16 v[32:35], v[152:155], v[200:203], v[32:35]
	v_mfma_f32_16x16x32_bf16 v[24:27], v[160:163], v[200:203], v[24:27]
	v_mfma_f32_16x16x32_bf16 v[16:19], v[152:155], v[208:211], v[16:19]
	v_mfma_f32_16x16x32_bf16 v[8:11], v[160:163], v[208:211], v[8:11]
	v_mfma_f32_16x16x32_bf16 v[60:63], v[156:159], v[188:191], v[60:63]
	v_mfma_f32_16x16x32_bf16 v[56:59], v[164:167], v[188:191], v[56:59]
	v_mfma_f32_16x16x32_bf16 v[48:51], v[156:159], v[196:199], v[48:51]
	v_mfma_f32_16x16x32_bf16 v[40:43], v[164:167], v[196:199], v[40:43]
	v_mfma_f32_16x16x32_bf16 v[32:35], v[156:159], v[204:207], v[32:35]
	v_mfma_f32_16x16x32_bf16 v[24:27], v[164:167], v[204:207], v[24:27]
	v_mfma_f32_16x16x32_bf16 v[16:19], v[156:159], v[212:215], v[16:19]
	v_mfma_f32_16x16x32_bf16 v[8:11], v[164:167], v[212:215], v[8:11]
	s_setprio 0
	s_setprio 1
	v_mfma_f32_16x16x32_bf16 v[52:55], v[168:171], v[184:187], v[52:55]
	v_mfma_f32_16x16x32_bf16 v[44:47], v[176:179], v[184:187], v[44:47]
	v_mfma_f32_16x16x32_bf16 v[36:39], v[168:171], v[192:195], v[36:39]
	v_mfma_f32_16x16x32_bf16 v[28:31], v[176:179], v[192:195], v[28:31]
	v_mfma_f32_16x16x32_bf16 v[20:23], v[168:171], v[200:203], v[20:23]
	v_mfma_f32_16x16x32_bf16 v[12:15], v[176:179], v[200:203], v[12:15]
	v_mfma_f32_16x16x32_bf16 v[4:7], v[168:171], v[208:211], v[4:7]
	v_mfma_f32_16x16x32_bf16 v[0:3], v[176:179], v[208:211], v[0:3]
	v_mfma_f32_16x16x32_bf16 v[52:55], v[172:175], v[188:191], v[52:55]
	v_mfma_f32_16x16x32_bf16 v[44:47], v[180:183], v[188:191], v[44:47]
	v_mfma_f32_16x16x32_bf16 v[36:39], v[172:175], v[196:199], v[36:39]
	v_mfma_f32_16x16x32_bf16 v[28:31], v[180:183], v[196:199], v[28:31]
	v_mfma_f32_16x16x32_bf16 v[20:23], v[172:175], v[204:207], v[20:23]
	v_mfma_f32_16x16x32_bf16 v[12:15], v[180:183], v[204:207], v[12:15]
	v_mfma_f32_16x16x32_bf16 v[4:7], v[172:175], v[212:215], v[4:7]
	v_mfma_f32_16x16x32_bf16 v[0:3], v[180:183], v[212:215], v[0:3]
	s_setprio 0
	s_barrier
	s_andn2_b64 vcc, exec, s[34:35]
	s_mov_b64 s[36:37], -1
	s_mov_b64 s[34:35], 0
	s_mov_b64 s[50:51], 0x100
	s_cbranch_vccnz .Lpeel_after_PX

; #define PG8_STAGE(bufoff, gbase, voff) do { _Pragma("unroll") for (int _i = 0; _i < 2; ++_i) \
;         __builtin_amdgcn_global_load_lds((const unsigned*)((const char*)(gbase) + (voff)[_i]), (PG8_LAS unsigned*)(lds + (bufoff) + ldsw + _i * 8192), 16, 0, 0); } while (0)
; #define PG8_LDA(dst, b, h) do { _Pragma("unroll") for (int m = 0; m < 4; ++m) _Pragma("unroll") for (int k = 0; k < 2; ++k) dst[m][k] = *(const PG8_LAS bf16x8*)(lds + PG8_SA(b, h) + aoff + m * 2048 + k * 1024); } while (0)
; #define PG8_LDB(dst, b, h) do { _Pragma("unroll") for (int n = 0; n < 2; ++n) _Pragma("unroll") for (int k = 0; k < 2; ++k) dst[n][k] = *(const PG8_LAS bf16x8*)(lds + PG8_SB(b, h) + boff + n * 2048 + k * 1024); } while (0)
; #define PG8_MMA(ai, bj, At, Bt) do { __builtin_amdgcn_s_setprio(1); _Pragma("unroll") for (int m = 0; m < 4; ++m) _Pragma("unroll") for (int n = 0; n < 2; ++n) _Pragma("unroll") for (int k = 0; k < 2; ++k) \
;         acc[ai][bj][m][n] = __builtin_amdgcn_mfma_f32_16x16x32_bf16(Bt[n][k], At[m][k], acc[ai][bj][m][n], 0, 0, 0); __builtin_amdgcn_s_setprio(0); } while (0)
; #define PG8_BAR __builtin_amdgcn_s_barrier()
; template <class Epi, class Sched>
; __device__ __forceinline__ void gemm_phase(PG8_LAS unsigned char* lds, PG8_LAS unsigned char* xl, const Gemm g, const Sched& S, const Epi& E) {
;     ...
;         const bool has_next = S.next(ui + 1, nxt);
;         const char* nA = has_next ? (const char*)g.A + nxt.aoff : cA; const char* nB = has_next ? (const char*)g.Bt + nxt.boff : cB;
; #pragma unroll 1
;         for (int t = 0; t < nt; t += 2) {
;             const bool last = (t == nt - 2);
;             const char* a1 = cA + (size_t)(t + 1) * kstep;
;             const char* a2 = last ? nA : cA + (size_t)(t + 2) * kstep; const char* b2 = last ? nB : cB + (size_t)(t + 2) * kstep;
;             const char* a3 = a2 + kstep; const char* b3 = b2 + kstep;
;             PG8_LDB(B0, 0, 0); PG8_LDB(B1, 0, 1); PG8_SCHED; PG8_LDA(At, 0, 0); PG8_STAGE(PG8_SA(1, 1), a1 + hsA, voffA);
;             PG8_WAIT_V(8); PG8_WAIT_L(0); PG8_BAR; PG8_MMA(0, 0, At, B0); PG8_MMA(0, 1, At, B1); PG8_BAR; PG8_SCHED;
;             PG8_LDA(At, 0, 1); PG8_STAGE(PG8_SB(0, 0), b2, voffB); PG8_STAGE(PG8_SB(0, 1), b2 + hsB, voffB); PG8_STAGE(PG8_SA(0, 0), a2, voffA);
;             PG8_WAIT_V(8); PG8_WAIT_L(0); PG8_BAR; PG8_MMA(1, 0, At, B0); PG8_MMA(1, 1, At, B1); PG8_BAR; PG8_SCHED;
.LBB0_470:
	s_add_u32 s26, s43, s20
	s_addc_u32 s27, s50, s21
	s_and_b64 s[28:29], s[8:9], exec
	s_cselect_b32 s33, s27, s35
	s_cselect_b32 s46, s26, s34
	s_add_u32 s28, s51, s22
	s_addc_u32 s29, s52, s23
	s_and_b64 s[36:37], s[8:9], exec
	s_cselect_b32 s47, s29, s31
	s_cselect_b32 s70, s28, s30
	s_add_u32 s72, s30, 0x100
	s_addc_u32 s73, s31, 0
	s_add_u32 s30, s34, 0x40080
	v_mov_b32_e32 v0, 0
	s_addc_u32 s31, s35, 0
	s_mov_b32 s74, -2
	s_waitcnt lgkmcnt(0)
	ds_read_b128 v[168:171], v156
	ds_read_b128 v[172:175], v156 offset:1024
	ds_read_b128 v[180:183], v156 offset:2048
	ds_read_b128 v[184:187], v156 offset:3072
	ds_read_b128 v[188:191], v157
	ds_read_b128 v[192:195], v157 offset:1024
	ds_read_b128 v[196:199], v157 offset:2048
	ds_read_b128 v[200:203], v157 offset:3072
	s_add_u32 s34, s30, 0xfffc0080
	s_addc_u32 s35, s31, -1
	s_cmp_eq_u32 s74, 12
	s_cselect_b32 s37, s33, s35
	s_cselect_b32 s36, s46, s34
	s_cselect_b32 s35, s47, s73
	s_cselect_b32 s34, s70, s72
	v_lshl_add_u64 v[144:145], s[30:31], 0, v[138:139]
	s_add_i32 m0, s56, 0xc000
	ds_read_b128 v[204:207], v158
	ds_read_b128 v[208:211], v158 offset:1024
	ds_read_b128 v[212:215], v158 offset:2048
	ds_read_b128 v[216:219], v158 offset:3072
	ds_read_b128 v[222:225], v158 offset:4096
	ds_read_b128 v[226:229], v158 offset:5120
	ds_read_b128 v[230:233], v158 offset:6144
	ds_read_b128 v[234:237], v158 offset:7168
	global_load_lds_dwordx4 v[144:145], off
	v_lshl_add_u64 v[144:145], s[30:31], 0, v[136:137]
	s_add_i32 m0, s56, 0xe000
	s_nop 0
	global_load_lds_dwordx4 v[144:145], off
	s_waitcnt vmcnt(8)
	s_waitcnt lgkmcnt(0)
	s_barrier
	s_setprio 1
	s_waitcnt lgkmcnt(0)
	v_mfma_f32_16x16x32_bf16 v[124:127], v[168:171], v[204:207], 0
	v_mfma_f32_16x16x32_bf16 v[120:123], v[180:183], v[204:207], 0
	v_mfma_f32_16x16x32_bf16 v[108:111], v[168:171], v[212:215], 0
	v_mfma_f32_16x16x32_bf16 v[104:107], v[180:183], v[212:215], 0
	v_mfma_f32_16x16x32_bf16 v[92:95], v[168:171], v[222:225], 0
	v_mfma_f32_16x16x32_bf16 v[88:91], v[180:183], v[222:225], 0
	v_mfma_f32_16x16x32_bf16 v[76:79], v[168:171], v[230:233], 0
	v_mfma_f32_16x16x32_bf16 v[72:75], v[180:183], v[230:233], 0
	v_mfma_f32_16x16x32_bf16 v[124:127], v[172:175], v[208:211], v[124:127]
	v_mfma_f32_16x16x32_bf16 v[120:123], v[184:187], v[208:211], v[120:123]
	v_mfma_f32_16x16x32_bf16 v[108:111], v[172:175], v[216:219], v[108:111]
	v_mfma_f32_16x16x32_bf16 v[104:107], v[184:187], v[216:219], v[104:107]
	v_mfma_f32_16x16x32_bf16 v[92:95], v[172:175], v[226:229], v[92:95]
	v_mfma_f32_16x16x32_bf16 v[88:91], v[184:187], v[226:229], v[88:91]
	v_mfma_f32_16x16x32_bf16 v[76:79], v[172:175], v[234:237], v[76:79]
	v_mfma_f32_16x16x32_bf16 v[72:75], v[184:187], v[234:237], v[72:75]
	s_setprio 0
	s_setprio 1
	v_mfma_f32_16x16x32_bf16 v[116:119], v[188:191], v[204:207], 0
	v_mfma_f32_16x16x32_bf16 v[112:115], v[196:199], v[204:207], 0
	v_mfma_f32_16x16x32_bf16 v[100:103], v[188:191], v[212:215], 0
	v_mfma_f32_16x16x32_bf16 v[96:99], v[196:199], v[212:215], 0
	v_mfma_f32_16x16x32_bf16 v[84:87], v[188:191], v[222:225], 0
	v_mfma_f32_16x16x32_bf16 v[80:83], v[196:199], v[222:225], 0
	v_mfma_f32_16x16x32_bf16 v[68:71], v[188:191], v[230:233], 0
	v_mfma_f32_16x16x32_bf16 v[64:67], v[196:199], v[230:233], 0
	v_mfma_f32_16x16x32_bf16 v[116:119], v[192:195], v[208:211], v[116:119]
	v_mfma_f32_16x16x32_bf16 v[112:115], v[200:203], v[208:211], v[112:115]
	v_mfma_f32_16x16x32_bf16 v[100:103], v[192:195], v[216:219], v[100:103]
	v_mfma_f32_16x16x32_bf16 v[96:99], v[200:203], v[216:219], v[96:99]
	v_mfma_f32_16x16x32_bf16 v[84:87], v[192:195], v[226:229], v[84:87]
	v_mfma_f32_16x16x32_bf16 v[80:83], v[200:203], v[226:229], v[80:83]
	v_mfma_f32_16x16x32_bf16 v[68:71], v[192:195], v[234:237], v[68:71]
	v_mfma_f32_16x16x32_bf16 v[64:67], v[200:203], v[234:237], v[64:67]
	s_setprio 0
	s_barrier
	s_add_i32 s68, s64, s55
	v_lshl_add_u64 v[144:145], s[34:35], 0, v[130:131]
	s_mov_b32 m0, s68
	ds_read_b128 v[204:207], v158 offset:16384
	ds_read_b128 v[208:211], v158 offset:17408
	ds_read_b128 v[212:215], v158 offset:18432
	ds_read_b128 v[216:219], v158 offset:19456
	ds_read_b128 v[222:225], v158 offset:20480
	ds_read_b128 v[226:229], v158 offset:21504
	ds_read_b128 v[230:233], v158 offset:22528
	ds_read_b128 v[234:237], v158 offset:23552
	global_load_lds_dwordx4 v[144:145], off
	s_add_i32 m0, s68, 0x2000
	s_add_u32 s76, s34, 0x40000
	v_lshl_add_u64 v[176:177], s[34:35], 0, v[134:135]
	s_addc_u32 s77, s35, 0
	s_add_i32 s68, s65, s55
	global_load_lds_dwordx4 v[176:177], off
	v_lshl_add_u64 v[238:239], s[76:77], 0, v[130:131]
	s_mov_b32 m0, s68
	v_lshl_add_u64 v[240:241], s[36:37], 0, v[132:133]
	global_load_lds_dwordx4 v[238:239], off
	v_lshl_add_u64 v[238:239], s[76:77], 0, v[134:135]
	s_add_i32 m0, s68, 0x2000
	s_nop 0
	global_load_lds_dwordx4 v[238:239], off
	v_lshl_add_u64 v[238:239], s[36:37], 0, v[128:129]
	s_mov_b32 m0, s56
	s_nop 0
	global_load_lds_dwordx4 v[238:239], off
	s_mov_b32 m0, s57
	s_nop 0
	global_load_lds_dwordx4 v[240:241], off
	s_waitcnt vmcnt(8)
	s_waitcnt lgkmcnt(0)
	s_barrier
; #define PG8_STAGE(bufoff, gbase, voff) do { _Pragma("unroll") for (int _i = 0; _i < 2; ++_i) \
;         __builtin_amdgcn_global_load_lds((const unsigned*)((const char*)(gbase) + (voff)[_i]), (PG8_LAS unsigned*)(lds + (bufoff) + ldsw + _i * 8192), 16, 0, 0); } while (0)
; #define PG8_LDA(dst, b, h) do { _Pragma("unroll") for (int m = 0; m < 4; ++m) _Pragma("unroll") for (int k = 0; k < 2; ++k) dst[m][k] = *(const PG8_LAS bf16x8*)(lds + PG8_SA(b, h) + aoff + m * 2048 + k * 1024); } while (0)
; #define PG8_LDB(dst, b, h) do { _Pragma("unroll") for (int n = 0; n < 2; ++n) _Pragma("unroll") for (int k = 0; k < 2; ++k) dst[n][k] = *(const PG8_LAS bf16x8*)(lds + PG8_SB(b, h) + boff + n * 2048 + k * 1024); } while (0)
; #define PG8_MMA(ai, bj, At, Bt) do { __builtin_amdgcn_s_setprio(1); _Pragma("unroll") for (int m = 0; m < 4; ++m) _Pragma("unroll") for (int n = 0; n < 2; ++n) _Pragma("unroll") for (int k = 0; k < 2; ++k) \
;         acc[ai][bj][m][n] = __builtin_amdgcn_mfma_f32_16x16x32_bf16(Bt[n][k], At[m][k], acc[ai][bj][m][n], 0, 0, 0); __builtin_amdgcn_s_setprio(0); } while (0)
; #define PG8_WAIT_V(n) asm volatile("s_waitcnt vmcnt(" #n ")" ::: "memory")
; #define PG8_WAIT_L(n) asm volatile("s_waitcnt lgkmcnt(" #n ")" ::: "memory")
; #define PG8_BAR __builtin_amdgcn_s_barrier()
; #define PG8_SCHED __builtin_amdgcn_sched_barrier(0)
; template <class Epi, class Sched>
; __device__ __forceinline__ void gemm_phase(PG8_LAS unsigned char* lds, PG8_LAS unsigned char* xl, const Gemm g, const Sched& S, const Epi& E) {
;     ...
;             PG8_WAIT_V(8); PG8_WAIT_L(0); PG8_BAR; PG8_MMA(1, 0, At, B0); PG8_MMA(1, 1, At, B1); PG8_BAR; PG8_SCHED;
;             PG8_LDB(B0, 1, 0); PG8_LDB(B1, 1, 1); PG8_SCHED; PG8_LDA(At, 1, 0); PG8_STAGE(PG8_SA(0, 1), a2 + hsA, voffA);
;             PG8_WAIT_V(8); PG8_WAIT_L(0); PG8_BAR; PG8_MMA(0, 0, At, B0); PG8_MMA(0, 1, At, B1); PG8_BAR; PG8_SCHED;
;             PG8_LDA(At, 1, 1); PG8_STAGE(PG8_SB(1, 0), b3, voffB); PG8_STAGE(PG8_SB(1, 1), b3 + hsB, voffB); PG8_STAGE(PG8_SA(1, 0), a3, voffA);
	s_setprio 1
	s_waitcnt lgkmcnt(0)
	v_mfma_f32_16x16x32_bf16 v[60:63], v[168:171], v[204:207], 0
	v_mfma_f32_16x16x32_bf16 v[56:59], v[180:183], v[204:207], 0
	v_mfma_f32_16x16x32_bf16 v[44:47], v[168:171], v[212:215], 0
	v_mfma_f32_16x16x32_bf16 v[40:43], v[180:183], v[212:215], 0
	v_mfma_f32_16x16x32_bf16 v[28:31], v[168:171], v[222:225], 0
	v_mfma_f32_16x16x32_bf16 v[24:27], v[180:183], v[222:225], 0
	v_mfma_f32_16x16x32_bf16 v[12:15], v[168:171], v[230:233], 0
	v_mfma_f32_16x16x32_bf16 v[8:11], v[180:183], v[230:233], 0
	v_mfma_f32_16x16x32_bf16 v[60:63], v[172:175], v[208:211], v[60:63]
	v_mfma_f32_16x16x32_bf16 v[56:59], v[184:187], v[208:211], v[56:59]
	v_mfma_f32_16x16x32_bf16 v[44:47], v[172:175], v[216:219], v[44:47]
	v_mfma_f32_16x16x32_bf16 v[40:43], v[184:187], v[216:219], v[40:43]
	v_mfma_f32_16x16x32_bf16 v[28:31], v[172:175], v[226:229], v[28:31]
	v_mfma_f32_16x16x32_bf16 v[24:27], v[184:187], v[226:229], v[24:27]
	v_mfma_f32_16x16x32_bf16 v[12:15], v[172:175], v[234:237], v[12:15]
	v_mfma_f32_16x16x32_bf16 v[8:11], v[184:187], v[234:237], v[8:11]
	s_setprio 0
	s_setprio 1
	v_mfma_f32_16x16x32_bf16 v[52:55], v[188:191], v[204:207], 0
	v_mfma_f32_16x16x32_bf16 v[48:51], v[196:199], v[204:207], 0
	v_mfma_f32_16x16x32_bf16 v[36:39], v[188:191], v[212:215], 0
	v_mfma_f32_16x16x32_bf16 v[32:35], v[196:199], v[212:215], 0
	v_mfma_f32_16x16x32_bf16 v[20:23], v[188:191], v[222:225], 0
	v_mfma_f32_16x16x32_bf16 v[16:19], v[196:199], v[222:225], 0
	v_mfma_f32_16x16x32_bf16 v[4:7], v[188:191], v[230:233], 0
	v_mfma_f32_16x16x32_bf16 v[0:3], v[196:199], v[230:233], 0
	v_mfma_f32_16x16x32_bf16 v[52:55], v[192:195], v[208:211], v[52:55]
	v_mfma_f32_16x16x32_bf16 v[48:51], v[200:203], v[208:211], v[48:51]
	v_mfma_f32_16x16x32_bf16 v[36:39], v[192:195], v[216:219], v[36:39]
	v_mfma_f32_16x16x32_bf16 v[32:35], v[200:203], v[216:219], v[32:35]
	v_mfma_f32_16x16x32_bf16 v[20:23], v[192:195], v[226:229], v[20:23]
	v_mfma_f32_16x16x32_bf16 v[16:19], v[200:203], v[226:229], v[16:19]
	v_mfma_f32_16x16x32_bf16 v[4:7], v[192:195], v[234:237], v[4:7]
	v_mfma_f32_16x16x32_bf16 v[0:3], v[200:203], v[234:237], v[0:3]
	s_setprio 0
	s_barrier
	s_add_i32 s68, 0, 0x18000
	v_add_u32_e32 v179, s68, v147
	s_add_i32 s75, 0, 0x1c000
	ds_read_b128 v[168:171], v179
	ds_read_b128 v[172:175], v179 offset:1024
	ds_read_b128 v[180:183], v179 offset:2048
	ds_read_b128 v[184:187], v179 offset:3072
	v_add_u32_e32 v179, s75, v147
	ds_read_b128 v[188:191], v179
	ds_read_b128 v[192:195], v179 offset:1024
	ds_read_b128 v[196:199], v179 offset:2048
	ds_read_b128 v[200:203], v179 offset:3072
	s_add_u32 s36, s36, 0x40000
	s_addc_u32 s37, s37, 0
	s_mov_b32 m0, s58
	v_lshl_add_u64 v[242:243], s[36:37], 0, v[128:129]
	ds_read_b128 v[204:207], v158 offset:32768
	ds_read_b128 v[208:211], v158 offset:33792
	ds_read_b128 v[212:215], v158 offset:34816
	ds_read_b128 v[216:219], v158 offset:35840
	ds_read_b128 v[222:225], v158 offset:36864
	ds_read_b128 v[226:229], v158 offset:37888
	ds_read_b128 v[230:233], v158 offset:38912
	ds_read_b128 v[234:237], v158 offset:39936
	global_load_lds_dwordx4 v[242:243], off
	v_lshl_add_u64 v[242:243], s[36:37], 0, v[132:133]
	s_mov_b32 m0, s59
	s_nop 0
	global_load_lds_dwordx4 v[242:243], off
	s_waitcnt vmcnt(8)
	s_waitcnt lgkmcnt(0)
	s_barrier
	s_setprio 1
	s_waitcnt lgkmcnt(0)
	v_mfma_f32_16x16x32_bf16 v[124:127], v[168:171], v[204:207], v[124:127]
	v_mfma_f32_16x16x32_bf16 v[120:123], v[180:183], v[204:207], v[120:123]
	v_mfma_f32_16x16x32_bf16 v[108:111], v[168:171], v[212:215], v[108:111]
	v_mfma_f32_16x16x32_bf16 v[104:107], v[180:183], v[212:215], v[104:107]
	v_mfma_f32_16x16x32_bf16 v[92:95], v[168:171], v[222:225], v[92:95]
	v_mfma_f32_16x16x32_bf16 v[88:91], v[180:183], v[222:225], v[88:91]
	v_mfma_f32_16x16x32_bf16 v[76:79], v[168:171], v[230:233], v[76:79]
	v_mfma_f32_16x16x32_bf16 v[72:75], v[180:183], v[230:233], v[72:75]
	v_mfma_f32_16x16x32_bf16 v[124:127], v[172:175], v[208:211], v[124:127]
	v_mfma_f32_16x16x32_bf16 v[120:123], v[184:187], v[208:211], v[120:123]
	v_mfma_f32_16x16x32_bf16 v[108:111], v[172:175], v[216:219], v[108:111]
	v_mfma_f32_16x16x32_bf16 v[104:107], v[184:187], v[216:219], v[104:107]
	v_mfma_f32_16x16x32_bf16 v[92:95], v[172:175], v[226:229], v[92:95]
	v_mfma_f32_16x16x32_bf16 v[88:91], v[184:187], v[226:229], v[88:91]
	v_mfma_f32_16x16x32_bf16 v[76:79], v[172:175], v[234:237], v[76:79]
	v_mfma_f32_16x16x32_bf16 v[72:75], v[184:187], v[234:237], v[72:75]
	s_setprio 0
	s_setprio 1
	v_mfma_f32_16x16x32_bf16 v[116:119], v[188:191], v[204:207], v[116:119]
	v_mfma_f32_16x16x32_bf16 v[112:115], v[196:199], v[204:207], v[112:115]
	v_mfma_f32_16x16x32_bf16 v[100:103], v[188:191], v[212:215], v[100:103]
	v_mfma_f32_16x16x32_bf16 v[96:99], v[196:199], v[212:215], v[96:99]
	v_mfma_f32_16x16x32_bf16 v[84:87], v[188:191], v[222:225], v[84:87]
	v_mfma_f32_16x16x32_bf16 v[80:83], v[196:199], v[222:225], v[80:83]
	v_mfma_f32_16x16x32_bf16 v[68:71], v[188:191], v[230:233], v[68:71]
	v_mfma_f32_16x16x32_bf16 v[64:67], v[196:199], v[230:233], v[64:67]
	v_mfma_f32_16x16x32_bf16 v[116:119], v[192:195], v[208:211], v[116:119]
	v_mfma_f32_16x16x32_bf16 v[112:115], v[200:203], v[208:211], v[112:115]
	v_mfma_f32_16x16x32_bf16 v[100:103], v[192:195], v[216:219], v[100:103]
	v_mfma_f32_16x16x32_bf16 v[96:99], v[200:203], v[216:219], v[96:99]
	v_mfma_f32_16x16x32_bf16 v[84:87], v[192:195], v[226:229], v[84:87]
	v_mfma_f32_16x16x32_bf16 v[80:83], v[200:203], v[226:229], v[80:83]
	v_mfma_f32_16x16x32_bf16 v[68:71], v[192:195], v[234:237], v[68:71]
	v_mfma_f32_16x16x32_bf16 v[64:67], v[200:203], v[234:237], v[64:67]
	s_setprio 0
	s_barrier
; #define PG8_STAGE(bufoff, gbase, voff) do { _Pragma("unroll") for (int _i = 0; _i < 2; ++_i) \
;         __builtin_amdgcn_global_load_lds((const unsigned*)((const char*)(gbase) + (voff)[_i]), (PG8_LAS unsigned*)(lds + (bufoff) + ldsw + _i * 8192), 16, 0, 0); } while (0)
; #define PG8_LDA(dst, b, h) do { _Pragma("unroll") for (int m = 0; m < 4; ++m) _Pragma("unroll") for (int k = 0; k < 2; ++k) dst[m][k] = *(const PG8_LAS bf16x8*)(lds + PG8_SA(b, h) + aoff + m * 2048 + k * 1024); } while (0)
; #define PG8_MMA(ai, bj, At, Bt) do { __builtin_amdgcn_s_setprio(1); _Pragma("unroll") for (int m = 0; m < 4; ++m) _Pragma("unroll") for (int n = 0; n < 2; ++n) _Pragma("unroll") for (int k = 0; k < 2; ++k) \
;         acc[ai][bj][m][n] = __builtin_amdgcn_mfma_f32_16x16x32_bf16(Bt[n][k], At[m][k], acc[ai][bj][m][n], 0, 0, 0); __builtin_amdgcn_s_setprio(0); } while (0)
; #define PG8_WAIT_V(n) asm volatile("s_waitcnt vmcnt(" #n ")" ::: "memory")
; #define PG8_WAIT_L(n) asm volatile("s_waitcnt lgkmcnt(" #n ")" ::: "memory")
; #define PG8_BAR __builtin_amdgcn_s_barrier()
; #define PG8_SCHED __builtin_amdgcn_sched_barrier(0)
; template <class Epi, class Sched>
; __device__ __forceinline__ void gemm_phase(PG8_LAS unsigned char* lds, PG8_LAS unsigned char* xl, const Gemm g, const Sched& S, const Epi& E) {
;     ...
;             PG8_LDA(At, 1, 1); PG8_STAGE(PG8_SB(1, 0), b3, voffB); PG8_STAGE(PG8_SB(1, 1), b3 + hsB, voffB); PG8_STAGE(PG8_SA(1, 0), a3, voffA);
;             PG8_WAIT_V(8); PG8_WAIT_L(0); PG8_BAR; PG8_MMA(1, 0, At, B0); PG8_MMA(1, 1, At, B1); PG8_BAR; PG8_SCHED;
;         }
	s_add_i32 s36, s68, s55
	v_lshl_add_u64 v[144:145], v[144:145], 0, s[16:17]
	s_mov_b32 m0, s36
	ds_read_b128 v[204:207], v158 offset:49152
	ds_read_b128 v[208:211], v158 offset:50176
	ds_read_b128 v[212:215], v158 offset:51200
	ds_read_b128 v[216:219], v158 offset:52224
	ds_read_b128 v[222:225], v158 offset:53248
	ds_read_b128 v[226:229], v158 offset:54272
	ds_read_b128 v[230:233], v158 offset:55296
	ds_read_b128 v[234:237], v158 offset:56320
	global_load_lds_dwordx4 v[144:145], off
	s_add_i32 m0, s36, 0x2000
	s_add_u32 s34, s34, 0x40080
	v_lshl_add_u64 v[144:145], v[176:177], 0, s[16:17]
	s_addc_u32 s35, s35, 0
	s_add_i32 s36, s75, s55
	global_load_lds_dwordx4 v[144:145], off
	v_lshl_add_u64 v[144:145], s[34:35], 0, v[130:131]
	s_mov_b32 m0, s36
	s_nop 0
	global_load_lds_dwordx4 v[144:145], off
	v_lshl_add_u64 v[144:145], s[34:35], 0, v[134:135]
	s_add_i32 m0, s36, 0x2000
	s_nop 0
	global_load_lds_dwordx4 v[144:145], off
	v_lshl_add_u64 v[144:145], v[238:239], 0, s[16:17]
	s_mov_b32 m0, s61
	s_nop 0
	global_load_lds_dwordx4 v[144:145], off
	v_lshl_add_u64 v[144:145], v[240:241], 0, s[16:17]
	s_mov_b32 m0, s62
	s_nop 0
	global_load_lds_dwordx4 v[144:145], off
	s_waitcnt vmcnt(8)
	s_waitcnt lgkmcnt(0)
	s_barrier
	s_setprio 1
	s_waitcnt lgkmcnt(0)
	v_mfma_f32_16x16x32_bf16 v[60:63], v[168:171], v[204:207], v[60:63]
	v_mfma_f32_16x16x32_bf16 v[56:59], v[180:183], v[204:207], v[56:59]
	v_mfma_f32_16x16x32_bf16 v[44:47], v[168:171], v[212:215], v[44:47]
	v_mfma_f32_16x16x32_bf16 v[40:43], v[180:183], v[212:215], v[40:43]
	v_mfma_f32_16x16x32_bf16 v[28:31], v[168:171], v[222:225], v[28:31]
	v_mfma_f32_16x16x32_bf16 v[24:27], v[180:183], v[222:225], v[24:27]
	v_mfma_f32_16x16x32_bf16 v[12:15], v[168:171], v[230:233], v[12:15]
	v_mfma_f32_16x16x32_bf16 v[8:11], v[180:183], v[230:233], v[8:11]
	v_mfma_f32_16x16x32_bf16 v[60:63], v[172:175], v[208:211], v[60:63]
	v_mfma_f32_16x16x32_bf16 v[56:59], v[184:187], v[208:211], v[56:59]
	v_mfma_f32_16x16x32_bf16 v[44:47], v[172:175], v[216:219], v[44:47]
	v_mfma_f32_16x16x32_bf16 v[40:43], v[184:187], v[216:219], v[40:43]
	v_mfma_f32_16x16x32_bf16 v[28:31], v[172:175], v[226:229], v[28:31]
	v_mfma_f32_16x16x32_bf16 v[24:27], v[184:187], v[226:229], v[24:27]
	v_mfma_f32_16x16x32_bf16 v[12:15], v[172:175], v[234:237], v[12:15]
	v_mfma_f32_16x16x32_bf16 v[8:11], v[184:187], v[234:237], v[8:11]
	s_setprio 0
	s_setprio 1
	v_mfma_f32_16x16x32_bf16 v[52:55], v[188:191], v[204:207], v[52:55]
	v_mfma_f32_16x16x32_bf16 v[48:51], v[196:199], v[204:207], v[48:51]
	v_mfma_f32_16x16x32_bf16 v[36:39], v[188:191], v[212:215], v[36:39]
	v_mfma_f32_16x16x32_bf16 v[32:35], v[196:199], v[212:215], v[32:35]
	v_mfma_f32_16x16x32_bf16 v[20:23], v[188:191], v[222:225], v[20:23]
	v_mfma_f32_16x16x32_bf16 v[16:19], v[196:199], v[222:225], v[16:19]
	v_mfma_f32_16x16x32_bf16 v[4:7], v[188:191], v[230:233], v[4:7]
	v_mfma_f32_16x16x32_bf16 v[0:3], v[196:199], v[230:233], v[0:3]
	v_mfma_f32_16x16x32_bf16 v[52:55], v[192:195], v[208:211], v[52:55]
	v_mfma_f32_16x16x32_bf16 v[48:51], v[200:203], v[208:211], v[48:51]
	v_mfma_f32_16x16x32_bf16 v[36:39], v[192:195], v[216:219], v[36:39]
	v_mfma_f32_16x16x32_bf16 v[32:35], v[200:203], v[216:219], v[32:35]
	v_mfma_f32_16x16x32_bf16 v[20:23], v[192:195], v[226:229], v[20:23]
	v_mfma_f32_16x16x32_bf16 v[16:19], v[200:203], v[226:229], v[16:19]
	v_mfma_f32_16x16x32_bf16 v[4:7], v[192:195], v[234:237], v[4:7]
	v_mfma_f32_16x16x32_bf16 v[0:3], v[200:203], v[234:237], v[0:3]
	s_setprio 0
	s_barrier
	s_add_i32 s74, s74, 2
	s_add_u32 s72, s72, 0x100
	s_addc_u32 s73, s73, 0
	s_add_u32 s30, s30, 0x100
	s_addc_u32 s31, s31, 0
	s_cmp_gt_u32 s74, 13
	s_cbranch_scc1 .Lpeel_after_P3

; #define PG8_BAR __builtin_amdgcn_s_barrier()
;     __device__ __forceinline__ void operator()(Acc& acc, const Unit& u, int wr, int wc, int fr, int fq, PG8_LAS unsigned char* xl) const {
;     ...
;         const int col = u.c0 + wc * 32 + 8 * fq;
; #pragma unroll
;         for (int ai = 0; ai < 2; ++ai)
; #pragma unroll
;             for (int m = 0; m < 4; ++m) { const int rl = ai * HALF + wr * 64 + m * 16 + fr; const int row = u.r0 + rl; const size_t off = (size_t)row * DM + col; float s = 0.f;
; #pragma unroll
;                 for (int bj = 0; bj < 2; ++bj) {
;                     f32x4 b0, b1;
;                     if (BASE_BF16) unpack8(*(const u32x4*)((const bf16_t*)base + off + bj * HALF), b0, b1);
;                     else { b0 = *(const f32x4*)((const float*)base + off + bj * HALF); b1 = *(const f32x4*)((const float*)base + off + bj * HALF + 4); }
; template <class Epi, class Sched>
; __device__ __forceinline__ void gemm_phase(PG8_LAS unsigned char* lds, PG8_LAS unsigned char* xl, const Gemm g, const Sched& S, const Epi& E) {
;     ...
;         if (wr == 0) PG8_BAR;
.Lpeel_after_P3:
	v_add_u32_e32 v252, s53, v148
	v_ashrrev_i32_e32 v253, 31, v252
	v_add_u32_e32 v222, s54, v146
	v_ashrrev_i32_e32 v223, 31, v222
	v_lshlrev_b64 v[222:223], 10, v[222:223]
	v_lshl_add_u64 v[222:223], v[222:223], 0, v[252:253]
	v_lshl_add_u64 v[222:223], v[222:223], 2, s[2:3]
	global_load_dwordx4 v[184:187], v[222:223], off
	global_load_dwordx4 v[188:191], v[222:223], off offset:16
	global_load_dwordx4 v[192:195], v[222:223], off offset:512
	global_load_dwordx4 v[196:199], v[222:223], off offset:528
	v_add_u32_e32 v222, s54, v149
	v_ashrrev_i32_e32 v223, 31, v222
	v_lshlrev_b64 v[222:223], 10, v[222:223]
	v_lshl_add_u64 v[222:223], v[222:223], 0, v[252:253]
	v_lshl_add_u64 v[222:223], v[222:223], 2, s[2:3]
	global_load_dwordx4 v[200:203], v[222:223], off
	global_load_dwordx4 v[204:207], v[222:223], off offset:16
	global_load_dwordx4 v[208:211], v[222:223], off offset:512
	global_load_dwordx4 v[212:215], v[222:223], off offset:528
	v_add_u32_e32 v222, s54, v150
	v_ashrrev_i32_e32 v223, 31, v222
	v_lshlrev_b64 v[222:223], 10, v[222:223]
	v_lshl_add_u64 v[222:223], v[222:223], 0, v[252:253]
	v_lshl_add_u64 v[222:223], v[222:223], 2, s[2:3]
	global_load_dwordx4 v[216:219], v[222:223], off
	global_load_dwordx4 v[224:227], v[222:223], off offset:16
	global_load_dwordx4 v[228:231], v[222:223], off offset:512
	global_load_dwordx4 v[232:235], v[222:223], off offset:528
	v_add_u32_e32 v222, s54, v151
	v_ashrrev_i32_e32 v223, 31, v222
	v_lshlrev_b64 v[222:223], 10, v[222:223]
	v_lshl_add_u64 v[222:223], v[222:223], 0, v[252:253]
	v_lshl_add_u64 v[222:223], v[222:223], 2, s[2:3]
	global_load_dwordx4 v[236:239], v[222:223], off
	global_load_dwordx4 v[240:243], v[222:223], off offset:16
	global_load_dwordx4 v[244:247], v[222:223], off offset:512
	global_load_dwordx4 v[248:251], v[222:223], off offset:528
	s_and_b64 vcc, exec, s[18:19]
	s_cbranch_vccz .LBB0_474
	s_barrier

; #define PG8_STAGE(bufoff, gbase, voff) do { _Pragma("unroll") for (int _i = 0; _i < 2; ++_i) \
;         __builtin_amdgcn_global_load_lds((const unsigned*)((const char*)(gbase) + (voff)[_i]), (PG8_LAS unsigned*)(lds + (bufoff) + ldsw + _i * 8192), 16, 0, 0); } while (0)
; #define PG8_LDA(dst, b, h) do { _Pragma("unroll") for (int m = 0; m < 4; ++m) _Pragma("unroll") for (int k = 0; k < 2; ++k) dst[m][k] = *(const PG8_LAS bf16x8*)(lds + PG8_SA(b, h) + aoff + m * 2048 + k * 1024); } while (0)
; #define PG8_LDB(dst, b, h) do { _Pragma("unroll") for (int n = 0; n < 2; ++n) _Pragma("unroll") for (int k = 0; k < 2; ++k) dst[n][k] = *(const PG8_LAS bf16x8*)(lds + PG8_SB(b, h) + boff + n * 2048 + k * 1024); } while (0)
; #define PG8_MMA(ai, bj, At, Bt) do { __builtin_amdgcn_s_setprio(1); _Pragma("unroll") for (int m = 0; m < 4; ++m) _Pragma("unroll") for (int n = 0; n < 2; ++n) _Pragma("unroll") for (int k = 0; k < 2; ++k) \
;         acc[ai][bj][m][n] = __builtin_amdgcn_mfma_f32_16x16x32_bf16(Bt[n][k], At[m][k], acc[ai][bj][m][n], 0, 0, 0); __builtin_amdgcn_s_setprio(0); } while (0)
; #define PG8_BAR __builtin_amdgcn_s_barrier()
; template <class Epi, class Sched>
; __device__ __forceinline__ void gemm_phase(PG8_LAS unsigned char* lds, PG8_LAS unsigned char* xl, const Gemm g, const Sched& S, const Epi& E) {
;     ...
;         const bool has_next = S.next(ui + 1, nxt);
;         const char* nA = has_next ? (const char*)g.A + nxt.aoff : cA; const char* nB = has_next ? (const char*)g.Bt + nxt.boff : cB;
; #pragma unroll 1
;         for (int t = 0; t < nt; t += 2) {
;             const bool last = (t == nt - 2);
;             const char* a1 = cA + (size_t)(t + 1) * kstep;
;             const char* a2 = last ? nA : cA + (size_t)(t + 2) * kstep; const char* b2 = last ? nB : cB + (size_t)(t + 2) * kstep;
;             const char* a3 = a2 + kstep; const char* b3 = b2 + kstep;
;             PG8_LDB(B0, 0, 0); PG8_LDB(B1, 0, 1); PG8_SCHED; PG8_LDA(At, 0, 0); PG8_STAGE(PG8_SA(1, 1), a1 + hsA, voffA);
;             PG8_WAIT_V(8); PG8_WAIT_L(0); PG8_BAR; PG8_MMA(0, 0, At, B0); PG8_MMA(0, 1, At, B1); PG8_BAR; PG8_SCHED;
;             PG8_LDA(At, 0, 1); PG8_STAGE(PG8_SB(0, 0), b2, voffB); PG8_STAGE(PG8_SB(0, 1), b2 + hsB, voffB); PG8_STAGE(PG8_SA(0, 0), a2, voffA);
;             PG8_WAIT_V(8); PG8_WAIT_L(0); PG8_BAR; PG8_MMA(1, 0, At, B0); PG8_MMA(1, 1, At, B1); PG8_BAR; PG8_SCHED;
.LBB0_576:
	s_add_u32 s34, s43, s28
	s_addc_u32 s35, s55, s29
	s_and_b64 s[36:37], s[10:11], exec
	s_cselect_b32 s13, s35, s51
	s_cselect_b32 s33, s34, s50
	s_add_u32 s36, s56, s30
	s_addc_u32 s37, s57, s31
	s_and_b64 s[46:47], s[10:11], exec
	s_cselect_b32 s46, s37, s3
	s_cselect_b32 s47, s36, s2
	s_add_u32 s79, s2, 0x100
	s_addc_u32 s80, s3, 0
	s_add_u32 s2, s50, 0x40080
	v_mov_b32_e32 v0, 0
	s_addc_u32 s3, s51, 0
	s_mov_b32 s81, -2
	ds_read_b128 v[146:149], v181
	ds_read_b128 v[150:153], v181 offset:1024
	ds_read_b128 v[188:191], v181 offset:2048
	ds_read_b128 v[192:195], v181 offset:3072
	ds_read_b128 v[196:199], v182
	ds_read_b128 v[200:203], v182 offset:1024
	ds_read_b128 v[204:207], v182 offset:2048
	ds_read_b128 v[208:211], v182 offset:3072
	s_add_u32 s50, s2, 0xfffc0080
	s_addc_u32 s51, s3, -1
	s_cmp_eq_u32 s81, 12
	s_cselect_b32 s53, s13, s51
	s_cselect_b32 s52, s33, s50
	s_cselect_b32 s51, s46, s80
	s_cselect_b32 s50, s47, s79
	v_lshl_add_u64 v[246:247], s[2:3], 0, v[140:141]
	s_add_i32 m0, s60, 0xc000
	ds_read_b128 v[212:215], v183
	ds_read_b128 v[216:219], v183 offset:1024
	ds_read_b128 v[222:225], v183 offset:2048
	ds_read_b128 v[226:229], v183 offset:3072
	ds_read_b128 v[230:233], v183 offset:4096
	ds_read_b128 v[234:237], v183 offset:5120
	ds_read_b128 v[238:241], v183 offset:6144
	ds_read_b128 v[242:245], v183 offset:7168
	global_load_lds_dwordx4 v[246:247], off
	v_lshl_add_u64 v[246:247], s[2:3], 0, v[138:139]
	s_add_i32 m0, s60, 0xe000
	s_nop 0
	global_load_lds_dwordx4 v[246:247], off
	s_waitcnt vmcnt(8)
	s_waitcnt lgkmcnt(0)
	s_barrier
	s_setprio 1
	s_waitcnt lgkmcnt(0)
	v_mfma_f32_16x16x32_bf16 v[124:127], v[146:149], v[212:215], 0
	v_mfma_f32_16x16x32_bf16 v[120:123], v[188:191], v[212:215], 0
	v_mfma_f32_16x16x32_bf16 v[108:111], v[146:149], v[222:225], 0
	v_mfma_f32_16x16x32_bf16 v[104:107], v[188:191], v[222:225], 0
	v_mfma_f32_16x16x32_bf16 v[92:95], v[146:149], v[230:233], 0
	v_mfma_f32_16x16x32_bf16 v[88:91], v[188:191], v[230:233], 0
	v_mfma_f32_16x16x32_bf16 v[76:79], v[146:149], v[238:241], 0
	v_mfma_f32_16x16x32_bf16 v[72:75], v[188:191], v[238:241], 0
	v_mfma_f32_16x16x32_bf16 v[124:127], v[150:153], v[216:219], v[124:127]
	v_mfma_f32_16x16x32_bf16 v[120:123], v[192:195], v[216:219], v[120:123]
	v_mfma_f32_16x16x32_bf16 v[108:111], v[150:153], v[226:229], v[108:111]
	v_mfma_f32_16x16x32_bf16 v[104:107], v[192:195], v[226:229], v[104:107]
	v_mfma_f32_16x16x32_bf16 v[92:95], v[150:153], v[234:237], v[92:95]
	v_mfma_f32_16x16x32_bf16 v[88:91], v[192:195], v[234:237], v[88:91]
	v_mfma_f32_16x16x32_bf16 v[76:79], v[150:153], v[242:245], v[76:79]
	v_mfma_f32_16x16x32_bf16 v[72:75], v[192:195], v[242:245], v[72:75]
	s_setprio 0
	s_setprio 1
	v_mfma_f32_16x16x32_bf16 v[116:119], v[196:199], v[212:215], 0
	v_mfma_f32_16x16x32_bf16 v[112:115], v[204:207], v[212:215], 0
	v_mfma_f32_16x16x32_bf16 v[100:103], v[196:199], v[222:225], 0
	v_mfma_f32_16x16x32_bf16 v[96:99], v[204:207], v[222:225], 0
	v_mfma_f32_16x16x32_bf16 v[84:87], v[196:199], v[230:233], 0
	v_mfma_f32_16x16x32_bf16 v[80:83], v[204:207], v[230:233], 0
	v_mfma_f32_16x16x32_bf16 v[68:71], v[196:199], v[238:241], 0
	v_mfma_f32_16x16x32_bf16 v[64:67], v[204:207], v[238:241], 0
	v_mfma_f32_16x16x32_bf16 v[116:119], v[200:203], v[216:219], v[116:119]
	v_mfma_f32_16x16x32_bf16 v[112:115], v[208:211], v[216:219], v[112:115]
	v_mfma_f32_16x16x32_bf16 v[100:103], v[200:203], v[226:229], v[100:103]
	v_mfma_f32_16x16x32_bf16 v[96:99], v[208:211], v[226:229], v[96:99]
	v_mfma_f32_16x16x32_bf16 v[84:87], v[200:203], v[234:237], v[84:87]
	v_mfma_f32_16x16x32_bf16 v[80:83], v[208:211], v[234:237], v[80:83]
	v_mfma_f32_16x16x32_bf16 v[68:71], v[200:203], v[242:245], v[68:71]
	v_mfma_f32_16x16x32_bf16 v[64:67], v[208:211], v[242:245], v[64:67]
	s_setprio 0
	s_barrier
	s_add_i32 s68, s72, s59
	v_lshl_add_u64 v[246:247], s[50:51], 0, v[130:131]
	s_mov_b32 m0, s68
	ds_read_b128 v[212:215], v183 offset:16384
	ds_read_b128 v[216:219], v183 offset:17408
	ds_read_b128 v[222:225], v183 offset:18432
	ds_read_b128 v[226:229], v183 offset:19456
	ds_read_b128 v[230:233], v183 offset:20480
	ds_read_b128 v[234:237], v183 offset:21504
	ds_read_b128 v[238:241], v183 offset:22528
	ds_read_b128 v[242:245], v183 offset:23552
	global_load_lds_dwordx4 v[246:247], off
	s_add_i32 m0, s68, 0x2000
	s_add_u32 s82, s50, 0x40000
	v_lshl_add_u64 v[248:249], s[50:51], 0, v[134:135]
	s_addc_u32 s83, s51, 0
	s_add_i32 s68, s73, s59
	global_load_lds_dwordx4 v[248:249], off
	v_lshl_add_u64 v[250:251], s[82:83], 0, v[130:131]
	s_mov_b32 m0, s68
	v_lshl_add_u64 v[252:253], s[52:53], 0, v[132:133]
	global_load_lds_dwordx4 v[250:251], off
	v_lshl_add_u64 v[250:251], s[82:83], 0, v[134:135]
	s_add_i32 m0, s68, 0x2000
	s_nop 0
	global_load_lds_dwordx4 v[250:251], off
	v_lshl_add_u64 v[250:251], s[52:53], 0, v[128:129]
	s_mov_b32 m0, s60
	s_nop 0
	global_load_lds_dwordx4 v[250:251], off
	s_mov_b32 m0, s61
	s_nop 0
	global_load_lds_dwordx4 v[252:253], off
	s_waitcnt vmcnt(8)
	s_waitcnt lgkmcnt(0)
	s_barrier
; #define PG8_STAGE(bufoff, gbase, voff) do { _Pragma("unroll") for (int _i = 0; _i < 2; ++_i) \
;         __builtin_amdgcn_global_load_lds((const unsigned*)((const char*)(gbase) + (voff)[_i]), (PG8_LAS unsigned*)(lds + (bufoff) + ldsw + _i * 8192), 16, 0, 0); } while (0)
; #define PG8_LDA(dst, b, h) do { _Pragma("unroll") for (int m = 0; m < 4; ++m) _Pragma("unroll") for (int k = 0; k < 2; ++k) dst[m][k] = *(const PG8_LAS bf16x8*)(lds + PG8_SA(b, h) + aoff + m * 2048 + k * 1024); } while (0)
; #define PG8_LDB(dst, b, h) do { _Pragma("unroll") for (int n = 0; n < 2; ++n) _Pragma("unroll") for (int k = 0; k < 2; ++k) dst[n][k] = *(const PG8_LAS bf16x8*)(lds + PG8_SB(b, h) + boff + n * 2048 + k * 1024); } while (0)
; #define PG8_MMA(ai, bj, At, Bt) do { __builtin_amdgcn_s_setprio(1); _Pragma("unroll") for (int m = 0; m < 4; ++m) _Pragma("unroll") for (int n = 0; n < 2; ++n) _Pragma("unroll") for (int k = 0; k < 2; ++k) \
;         acc[ai][bj][m][n] = __builtin_amdgcn_mfma_f32_16x16x32_bf16(Bt[n][k], At[m][k], acc[ai][bj][m][n], 0, 0, 0); __builtin_amdgcn_s_setprio(0); } while (0)
; #define PG8_WAIT_V(n) asm volatile("s_waitcnt vmcnt(" #n ")" ::: "memory")
; #define PG8_WAIT_L(n) asm volatile("s_waitcnt lgkmcnt(" #n ")" ::: "memory")
; #define PG8_BAR __builtin_amdgcn_s_barrier()
; #define PG8_SCHED __builtin_amdgcn_sched_barrier(0)
; template <class Epi, class Sched>
; __device__ __forceinline__ void gemm_phase(PG8_LAS unsigned char* lds, PG8_LAS unsigned char* xl, const Gemm g, const Sched& S, const Epi& E) {
;     ...
;             PG8_WAIT_V(8); PG8_WAIT_L(0); PG8_BAR; PG8_MMA(1, 0, At, B0); PG8_MMA(1, 1, At, B1); PG8_BAR; PG8_SCHED;
;             PG8_LDB(B0, 1, 0); PG8_LDB(B1, 1, 1); PG8_SCHED; PG8_LDA(At, 1, 0); PG8_STAGE(PG8_SA(0, 1), a2 + hsA, voffA);
;             PG8_WAIT_V(8); PG8_WAIT_L(0); PG8_BAR; PG8_MMA(0, 0, At, B0); PG8_MMA(0, 1, At, B1); PG8_BAR; PG8_SCHED;
;             PG8_LDA(At, 1, 1); PG8_STAGE(PG8_SB(1, 0), b3, voffB); PG8_STAGE(PG8_SB(1, 1), b3 + hsB, voffB); PG8_STAGE(PG8_SA(1, 0), a3, voffA);
	s_setprio 1
	s_waitcnt lgkmcnt(0)
	v_mfma_f32_16x16x32_bf16 v[60:63], v[146:149], v[212:215], 0
	v_mfma_f32_16x16x32_bf16 v[56:59], v[188:191], v[212:215], 0
	v_mfma_f32_16x16x32_bf16 v[44:47], v[146:149], v[222:225], 0
	v_mfma_f32_16x16x32_bf16 v[40:43], v[188:191], v[222:225], 0
	v_mfma_f32_16x16x32_bf16 v[28:31], v[146:149], v[230:233], 0
	v_mfma_f32_16x16x32_bf16 v[24:27], v[188:191], v[230:233], 0
	v_mfma_f32_16x16x32_bf16 v[12:15], v[146:149], v[238:241], 0
	v_mfma_f32_16x16x32_bf16 v[8:11], v[188:191], v[238:241], 0
	v_mfma_f32_16x16x32_bf16 v[60:63], v[150:153], v[216:219], v[60:63]
	v_mfma_f32_16x16x32_bf16 v[56:59], v[192:195], v[216:219], v[56:59]
	v_mfma_f32_16x16x32_bf16 v[44:47], v[150:153], v[226:229], v[44:47]
	v_mfma_f32_16x16x32_bf16 v[40:43], v[192:195], v[226:229], v[40:43]
	v_mfma_f32_16x16x32_bf16 v[28:31], v[150:153], v[234:237], v[28:31]
	v_mfma_f32_16x16x32_bf16 v[24:27], v[192:195], v[234:237], v[24:27]
	v_mfma_f32_16x16x32_bf16 v[12:15], v[150:153], v[242:245], v[12:15]
	v_mfma_f32_16x16x32_bf16 v[8:11], v[192:195], v[242:245], v[8:11]
	s_setprio 0
	s_setprio 1
	v_mfma_f32_16x16x32_bf16 v[52:55], v[196:199], v[212:215], 0
	v_mfma_f32_16x16x32_bf16 v[48:51], v[204:207], v[212:215], 0
	v_mfma_f32_16x16x32_bf16 v[36:39], v[196:199], v[222:225], 0
	v_mfma_f32_16x16x32_bf16 v[32:35], v[204:207], v[222:225], 0
	v_mfma_f32_16x16x32_bf16 v[20:23], v[196:199], v[230:233], 0
	v_mfma_f32_16x16x32_bf16 v[16:19], v[204:207], v[230:233], 0
	v_mfma_f32_16x16x32_bf16 v[4:7], v[196:199], v[238:241], 0
	v_mfma_f32_16x16x32_bf16 v[0:3], v[204:207], v[238:241], 0
	v_mfma_f32_16x16x32_bf16 v[52:55], v[200:203], v[216:219], v[52:55]
	v_mfma_f32_16x16x32_bf16 v[48:51], v[208:211], v[216:219], v[48:51]
	v_mfma_f32_16x16x32_bf16 v[36:39], v[200:203], v[226:229], v[36:39]
	v_mfma_f32_16x16x32_bf16 v[32:35], v[208:211], v[226:229], v[32:35]
	v_mfma_f32_16x16x32_bf16 v[20:23], v[200:203], v[234:237], v[20:23]
	v_mfma_f32_16x16x32_bf16 v[16:19], v[208:211], v[234:237], v[16:19]
	v_mfma_f32_16x16x32_bf16 v[4:7], v[200:203], v[242:245], v[4:7]
	v_mfma_f32_16x16x32_bf16 v[0:3], v[208:211], v[242:245], v[0:3]
	s_setprio 0
	s_barrier
	s_add_i32 s68, 0, 0x18000
	v_add_u32_e32 v184, s68, v156
	s_add_i32 s82, 0, 0x1c000
	ds_read_b128 v[146:149], v184
	ds_read_b128 v[150:153], v184 offset:1024
	ds_read_b128 v[188:191], v184 offset:2048
	ds_read_b128 v[192:195], v184 offset:3072
	v_add_u32_e32 v184, s82, v156
	ds_read_b128 v[196:199], v184
	ds_read_b128 v[200:203], v184 offset:1024
	ds_read_b128 v[204:207], v184 offset:2048
	ds_read_b128 v[208:211], v184 offset:3072
	s_add_u32 s52, s52, 0x40000
	s_addc_u32 s53, s53, 0
	s_mov_b32 m0, s62
	v_lshl_add_u64 v[184:185], s[52:53], 0, v[128:129]
	ds_read_b128 v[212:215], v183 offset:32768
	ds_read_b128 v[216:219], v183 offset:33792
	ds_read_b128 v[222:225], v183 offset:34816
	ds_read_b128 v[226:229], v183 offset:35840
	ds_read_b128 v[230:233], v183 offset:36864
	ds_read_b128 v[234:237], v183 offset:37888
	ds_read_b128 v[238:241], v183 offset:38912
	ds_read_b128 v[242:245], v183 offset:39936
	global_load_lds_dwordx4 v[184:185], off
	v_lshl_add_u64 v[184:185], s[52:53], 0, v[132:133]
	s_mov_b32 m0, s63
	s_nop 0
	global_load_lds_dwordx4 v[184:185], off
	s_waitcnt vmcnt(8)
	s_waitcnt lgkmcnt(0)
	s_barrier
	s_setprio 1
	s_waitcnt lgkmcnt(0)
	v_mfma_f32_16x16x32_bf16 v[124:127], v[146:149], v[212:215], v[124:127]
	v_mfma_f32_16x16x32_bf16 v[120:123], v[188:191], v[212:215], v[120:123]
	v_mfma_f32_16x16x32_bf16 v[108:111], v[146:149], v[222:225], v[108:111]
	v_mfma_f32_16x16x32_bf16 v[104:107], v[188:191], v[222:225], v[104:107]
	v_mfma_f32_16x16x32_bf16 v[92:95], v[146:149], v[230:233], v[92:95]
	v_mfma_f32_16x16x32_bf16 v[88:91], v[188:191], v[230:233], v[88:91]
	v_mfma_f32_16x16x32_bf16 v[76:79], v[146:149], v[238:241], v[76:79]
	v_mfma_f32_16x16x32_bf16 v[72:75], v[188:191], v[238:241], v[72:75]
	v_mfma_f32_16x16x32_bf16 v[124:127], v[150:153], v[216:219], v[124:127]
	v_mfma_f32_16x16x32_bf16 v[120:123], v[192:195], v[216:219], v[120:123]
	v_mfma_f32_16x16x32_bf16 v[108:111], v[150:153], v[226:229], v[108:111]
	v_mfma_f32_16x16x32_bf16 v[104:107], v[192:195], v[226:229], v[104:107]
	v_mfma_f32_16x16x32_bf16 v[92:95], v[150:153], v[234:237], v[92:95]
	v_mfma_f32_16x16x32_bf16 v[88:91], v[192:195], v[234:237], v[88:91]
	v_mfma_f32_16x16x32_bf16 v[76:79], v[150:153], v[242:245], v[76:79]
	v_mfma_f32_16x16x32_bf16 v[72:75], v[192:195], v[242:245], v[72:75]
	s_setprio 0
	s_setprio 1
	v_mfma_f32_16x16x32_bf16 v[116:119], v[196:199], v[212:215], v[116:119]
	v_mfma_f32_16x16x32_bf16 v[112:115], v[204:207], v[212:215], v[112:115]
	v_mfma_f32_16x16x32_bf16 v[100:103], v[196:199], v[222:225], v[100:103]
	v_mfma_f32_16x16x32_bf16 v[96:99], v[204:207], v[222:225], v[96:99]
	v_mfma_f32_16x16x32_bf16 v[84:87], v[196:199], v[230:233], v[84:87]
	v_mfma_f32_16x16x32_bf16 v[80:83], v[204:207], v[230:233], v[80:83]
	v_mfma_f32_16x16x32_bf16 v[68:71], v[196:199], v[238:241], v[68:71]
	v_mfma_f32_16x16x32_bf16 v[64:67], v[204:207], v[238:241], v[64:67]
	v_mfma_f32_16x16x32_bf16 v[116:119], v[200:203], v[216:219], v[116:119]
	v_mfma_f32_16x16x32_bf16 v[112:115], v[208:211], v[216:219], v[112:115]
	v_mfma_f32_16x16x32_bf16 v[100:103], v[200:203], v[226:229], v[100:103]
	v_mfma_f32_16x16x32_bf16 v[96:99], v[208:211], v[226:229], v[96:99]
	v_mfma_f32_16x16x32_bf16 v[84:87], v[200:203], v[234:237], v[84:87]
	v_mfma_f32_16x16x32_bf16 v[80:83], v[208:211], v[234:237], v[80:83]
	v_mfma_f32_16x16x32_bf16 v[68:71], v[200:203], v[242:245], v[68:71]
	v_mfma_f32_16x16x32_bf16 v[64:67], v[208:211], v[242:245], v[64:67]
	s_setprio 0
	s_barrier
; #define PG8_STAGE(bufoff, gbase, voff) do { _Pragma("unroll") for (int _i = 0; _i < 2; ++_i) \
;         __builtin_amdgcn_global_load_lds((const unsigned*)((const char*)(gbase) + (voff)[_i]), (PG8_LAS unsigned*)(lds + (bufoff) + ldsw + _i * 8192), 16, 0, 0); } while (0)
; #define PG8_LDA(dst, b, h) do { _Pragma("unroll") for (int m = 0; m < 4; ++m) _Pragma("unroll") for (int k = 0; k < 2; ++k) dst[m][k] = *(const PG8_LAS bf16x8*)(lds + PG8_SA(b, h) + aoff + m * 2048 + k * 1024); } while (0)
; #define PG8_MMA(ai, bj, At, Bt) do { __builtin_amdgcn_s_setprio(1); _Pragma("unroll") for (int m = 0; m < 4; ++m) _Pragma("unroll") for (int n = 0; n < 2; ++n) _Pragma("unroll") for (int k = 0; k < 2; ++k) \
;         acc[ai][bj][m][n] = __builtin_amdgcn_mfma_f32_16x16x32_bf16(Bt[n][k], At[m][k], acc[ai][bj][m][n], 0, 0, 0); __builtin_amdgcn_s_setprio(0); } while (0)
; #define PG8_WAIT_V(n) asm volatile("s_waitcnt vmcnt(" #n ")" ::: "memory")
; #define PG8_WAIT_L(n) asm volatile("s_waitcnt lgkmcnt(" #n ")" ::: "memory")
; #define PG8_BAR __builtin_amdgcn_s_barrier()
; #define PG8_SCHED __builtin_amdgcn_sched_barrier(0)
; template <class Epi, class Sched>
; __device__ __forceinline__ void gemm_phase(PG8_LAS unsigned char* lds, PG8_LAS unsigned char* xl, const Gemm g, const Sched& S, const Epi& E) {
;     ...
;             PG8_LDA(At, 1, 1); PG8_STAGE(PG8_SB(1, 0), b3, voffB); PG8_STAGE(PG8_SB(1, 1), b3 + hsB, voffB); PG8_STAGE(PG8_SA(1, 0), a3, voffA);
;             PG8_WAIT_V(8); PG8_WAIT_L(0); PG8_BAR; PG8_MMA(1, 0, At, B0); PG8_MMA(1, 1, At, B1); PG8_BAR; PG8_SCHED;
;         }
	s_add_i32 s52, s68, s59
	v_lshl_add_u64 v[184:185], v[246:247], 0, s[20:21]
	s_mov_b32 m0, s52
	ds_read_b128 v[212:215], v183 offset:49152
	ds_read_b128 v[216:219], v183 offset:50176
	ds_read_b128 v[222:225], v183 offset:51200
	ds_read_b128 v[226:229], v183 offset:52224
	ds_read_b128 v[230:233], v183 offset:53248
	ds_read_b128 v[234:237], v183 offset:54272
	ds_read_b128 v[238:241], v183 offset:55296
	ds_read_b128 v[242:245], v183 offset:56320
	global_load_lds_dwordx4 v[184:185], off
	s_add_i32 m0, s52, 0x2000
	s_add_u32 s50, s50, 0x40080
	v_lshl_add_u64 v[184:185], v[248:249], 0, s[20:21]
	s_addc_u32 s51, s51, 0
	s_add_i32 s52, s82, s59
	global_load_lds_dwordx4 v[184:185], off
	v_lshl_add_u64 v[184:185], s[50:51], 0, v[130:131]
	s_mov_b32 m0, s52
	s_nop 0
	global_load_lds_dwordx4 v[184:185], off
	v_lshl_add_u64 v[184:185], s[50:51], 0, v[134:135]
	s_add_i32 m0, s52, 0x2000
	s_nop 0
	global_load_lds_dwordx4 v[184:185], off
	v_lshl_add_u64 v[184:185], v[250:251], 0, s[20:21]
	s_mov_b32 m0, s65
	s_nop 0
	global_load_lds_dwordx4 v[184:185], off
	v_lshl_add_u64 v[184:185], v[252:253], 0, s[20:21]
	s_mov_b32 m0, s66
	s_nop 0
	global_load_lds_dwordx4 v[184:185], off
	s_waitcnt vmcnt(8)
	s_waitcnt lgkmcnt(0)
	s_barrier
	s_setprio 1
	s_waitcnt lgkmcnt(0)
	v_mfma_f32_16x16x32_bf16 v[60:63], v[146:149], v[212:215], v[60:63]
	v_mfma_f32_16x16x32_bf16 v[56:59], v[188:191], v[212:215], v[56:59]
	v_mfma_f32_16x16x32_bf16 v[44:47], v[146:149], v[222:225], v[44:47]
	v_mfma_f32_16x16x32_bf16 v[40:43], v[188:191], v[222:225], v[40:43]
	v_mfma_f32_16x16x32_bf16 v[28:31], v[146:149], v[230:233], v[28:31]
	v_mfma_f32_16x16x32_bf16 v[24:27], v[188:191], v[230:233], v[24:27]
	v_mfma_f32_16x16x32_bf16 v[12:15], v[146:149], v[238:241], v[12:15]
	v_mfma_f32_16x16x32_bf16 v[8:11], v[188:191], v[238:241], v[8:11]
	v_mfma_f32_16x16x32_bf16 v[60:63], v[150:153], v[216:219], v[60:63]
	v_mfma_f32_16x16x32_bf16 v[56:59], v[192:195], v[216:219], v[56:59]
	v_mfma_f32_16x16x32_bf16 v[44:47], v[150:153], v[226:229], v[44:47]
	v_mfma_f32_16x16x32_bf16 v[40:43], v[192:195], v[226:229], v[40:43]
	v_mfma_f32_16x16x32_bf16 v[28:31], v[150:153], v[234:237], v[28:31]
	v_mfma_f32_16x16x32_bf16 v[24:27], v[192:195], v[234:237], v[24:27]
	v_mfma_f32_16x16x32_bf16 v[12:15], v[150:153], v[242:245], v[12:15]
	v_mfma_f32_16x16x32_bf16 v[8:11], v[192:195], v[242:245], v[8:11]
	s_setprio 0
	s_setprio 1
	v_mfma_f32_16x16x32_bf16 v[52:55], v[196:199], v[212:215], v[52:55]
	v_mfma_f32_16x16x32_bf16 v[48:51], v[204:207], v[212:215], v[48:51]
	v_mfma_f32_16x16x32_bf16 v[36:39], v[196:199], v[222:225], v[36:39]
	v_mfma_f32_16x16x32_bf16 v[32:35], v[204:207], v[222:225], v[32:35]
	v_mfma_f32_16x16x32_bf16 v[20:23], v[196:199], v[230:233], v[20:23]
	v_mfma_f32_16x16x32_bf16 v[16:19], v[204:207], v[230:233], v[16:19]
	v_mfma_f32_16x16x32_bf16 v[4:7], v[196:199], v[238:241], v[4:7]
	v_mfma_f32_16x16x32_bf16 v[0:3], v[204:207], v[238:241], v[0:3]
	v_mfma_f32_16x16x32_bf16 v[52:55], v[200:203], v[216:219], v[52:55]
	v_mfma_f32_16x16x32_bf16 v[48:51], v[208:211], v[216:219], v[48:51]
	v_mfma_f32_16x16x32_bf16 v[36:39], v[200:203], v[226:229], v[36:39]
	v_mfma_f32_16x16x32_bf16 v[32:35], v[208:211], v[226:229], v[32:35]
	v_mfma_f32_16x16x32_bf16 v[20:23], v[200:203], v[234:237], v[20:23]
	v_mfma_f32_16x16x32_bf16 v[16:19], v[208:211], v[234:237], v[16:19]
	v_mfma_f32_16x16x32_bf16 v[4:7], v[200:203], v[242:245], v[4:7]
	v_mfma_f32_16x16x32_bf16 v[0:3], v[208:211], v[242:245], v[0:3]
	s_setprio 0
	s_barrier
	s_add_i32 s81, s81, 2
	s_add_u32 s79, s79, 0x100
	s_addc_u32 s80, s80, 0
	s_add_u32 s2, s2, 0x100
	s_addc_u32 s3, s3, 0
	s_cmp_gt_u32 s81, 13
	s_cbranch_scc1 .Lpeel_after_P4

; #define PG8_BAR __builtin_amdgcn_s_barrier()
; template <class Epi, class Sched>
; __device__ __forceinline__ void gemm_phase(PG8_LAS unsigned char* lds, PG8_LAS unsigned char* xl, const Gemm g, const Sched& S, const Epi& E) {
;     ...
;         if (wr == 0) PG8_BAR;
.Lpeel_after_P4:
	s_and_b64 vcc, exec, s[26:27]
	s_cbranch_vccz .LBB0_580
	s_barrier

; #define PG8_STAGE(bufoff, gbase, voff) do { _Pragma("unroll") for (int _i = 0; _i < 2; ++_i) \
;         __builtin_amdgcn_global_load_lds((const unsigned*)((const char*)(gbase) + (voff)[_i]), (PG8_LAS unsigned*)(lds + (bufoff) + ldsw + _i * 8192), 16, 0, 0); } while (0)
; #define PG8_LDA(dst, b, h) do { _Pragma("unroll") for (int m = 0; m < 4; ++m) _Pragma("unroll") for (int k = 0; k < 2; ++k) dst[m][k] = *(const PG8_LAS bf16x8*)(lds + PG8_SA(b, h) + aoff + m * 2048 + k * 1024); } while (0)
; #define PG8_LDB(dst, b, h) do { _Pragma("unroll") for (int n = 0; n < 2; ++n) _Pragma("unroll") for (int k = 0; k < 2; ++k) dst[n][k] = *(const PG8_LAS bf16x8*)(lds + PG8_SB(b, h) + boff + n * 2048 + k * 1024); } while (0)
; #define PG8_MMA(ai, bj, At, Bt) do { __builtin_amdgcn_s_setprio(1); _Pragma("unroll") for (int m = 0; m < 4; ++m) _Pragma("unroll") for (int n = 0; n < 2; ++n) _Pragma("unroll") for (int k = 0; k < 2; ++k) \
;         acc[ai][bj][m][n] = __builtin_amdgcn_mfma_f32_16x16x32_bf16(Bt[n][k], At[m][k], acc[ai][bj][m][n], 0, 0, 0); __builtin_amdgcn_s_setprio(0); } while (0)
; #define PG8_BAR __builtin_amdgcn_s_barrier()
; template <class Epi, class Sched>
; __device__ __forceinline__ void gemm_phase(PG8_LAS unsigned char* lds, PG8_LAS unsigned char* xl, const Gemm g, const Sched& S, const Epi& E) {
;     ...
;         const bool has_next = S.next(ui + 1, nxt);
;         const char* nA = has_next ? (const char*)g.A + nxt.aoff : cA; const char* nB = has_next ? (const char*)g.Bt + nxt.boff : cB;
; #pragma unroll 1
;         for (int t = 0; t < nt; t += 2) {
;             const bool last = (t == nt - 2);
;             const char* a1 = cA + (size_t)(t + 1) * kstep;
;             const char* a2 = last ? nA : cA + (size_t)(t + 2) * kstep; const char* b2 = last ? nB : cB + (size_t)(t + 2) * kstep;
;             const char* a3 = a2 + kstep; const char* b3 = b2 + kstep;
;             PG8_LDB(B0, 0, 0); PG8_LDB(B1, 0, 1); PG8_SCHED; PG8_LDA(At, 0, 0); PG8_STAGE(PG8_SA(1, 1), a1 + hsA, voffA);
;             PG8_WAIT_V(8); PG8_WAIT_L(0); PG8_BAR; PG8_MMA(0, 0, At, B0); PG8_MMA(0, 1, At, B1); PG8_BAR; PG8_SCHED;
;             PG8_LDA(At, 0, 1); PG8_STAGE(PG8_SB(0, 0), b2, voffB); PG8_STAGE(PG8_SB(0, 1), b2 + hsB, voffB); PG8_STAGE(PG8_SA(0, 0), a2, voffA);
;             PG8_WAIT_V(8); PG8_WAIT_L(0); PG8_BAR; PG8_MMA(1, 0, At, B0); PG8_MMA(1, 1, At, B1); PG8_BAR; PG8_SCHED;
.LBB0_724:
	s_add_u32 s26, s43, s20
	s_addc_u32 s27, s50, s21
	s_and_b64 s[28:29], s[8:9], exec
	s_cselect_b32 s33, s27, s35
	s_cselect_b32 s46, s26, s34
	s_add_u32 s28, s51, s22
	s_addc_u32 s29, s52, s23
	s_and_b64 s[36:37], s[8:9], exec
	s_cselect_b32 s47, s29, s31
	s_cselect_b32 s72, s28, s30
	s_add_u32 s73, s30, 0x100
	s_addc_u32 s74, s31, 0
	s_add_u32 s30, s34, 0x40080
	v_mov_b32_e32 v0, 0
	s_addc_u32 s31, s35, 0
	s_mov_b32 s75, -2
	s_waitcnt lgkmcnt(0)
	ds_read_b128 v[170:173], v157
	ds_read_b128 v[174:177], v157 offset:1024
	ds_read_b128 v[180:183], v157 offset:2048
	ds_read_b128 v[184:187], v157 offset:3072
	ds_read_b128 v[188:191], v158
	ds_read_b128 v[192:195], v158 offset:1024
	ds_read_b128 v[196:199], v158 offset:2048
	ds_read_b128 v[200:203], v158 offset:3072
	s_add_u32 s34, s30, 0xfffc0080
	s_addc_u32 s35, s31, -1
	s_cmp_eq_u32 s75, 12
	s_cselect_b32 s37, s33, s35
	s_cselect_b32 s36, s46, s34
	s_cselect_b32 s35, s47, s74
	s_cselect_b32 s34, s72, s73
	v_lshl_add_u64 v[144:145], s[30:31], 0, v[138:139]
	s_add_i32 m0, s57, 0xc000
	ds_read_b128 v[204:207], v159
	ds_read_b128 v[208:211], v159 offset:1024
	ds_read_b128 v[212:215], v159 offset:2048
	ds_read_b128 v[216:219], v159 offset:3072
	ds_read_b128 v[222:225], v159 offset:4096
	ds_read_b128 v[226:229], v159 offset:5120
	ds_read_b128 v[230:233], v159 offset:6144
	ds_read_b128 v[234:237], v159 offset:7168
	global_load_lds_dwordx4 v[144:145], off
	v_lshl_add_u64 v[144:145], s[30:31], 0, v[136:137]
	s_add_i32 m0, s57, 0xe000
	s_nop 0
	global_load_lds_dwordx4 v[144:145], off
	s_waitcnt vmcnt(8)
	s_waitcnt lgkmcnt(0)
	s_barrier
	s_setprio 1
	s_waitcnt lgkmcnt(0)
	v_mfma_f32_16x16x32_bf16 v[124:127], v[170:173], v[204:207], 0
	v_mfma_f32_16x16x32_bf16 v[120:123], v[180:183], v[204:207], 0
	v_mfma_f32_16x16x32_bf16 v[108:111], v[170:173], v[212:215], 0
	v_mfma_f32_16x16x32_bf16 v[104:107], v[180:183], v[212:215], 0
	v_mfma_f32_16x16x32_bf16 v[92:95], v[170:173], v[222:225], 0
	v_mfma_f32_16x16x32_bf16 v[88:91], v[180:183], v[222:225], 0
	v_mfma_f32_16x16x32_bf16 v[76:79], v[170:173], v[230:233], 0
	v_mfma_f32_16x16x32_bf16 v[72:75], v[180:183], v[230:233], 0
	v_mfma_f32_16x16x32_bf16 v[124:127], v[174:177], v[208:211], v[124:127]
	v_mfma_f32_16x16x32_bf16 v[120:123], v[184:187], v[208:211], v[120:123]
	v_mfma_f32_16x16x32_bf16 v[108:111], v[174:177], v[216:219], v[108:111]
	v_mfma_f32_16x16x32_bf16 v[104:107], v[184:187], v[216:219], v[104:107]
	v_mfma_f32_16x16x32_bf16 v[92:95], v[174:177], v[226:229], v[92:95]
	v_mfma_f32_16x16x32_bf16 v[88:91], v[184:187], v[226:229], v[88:91]
	v_mfma_f32_16x16x32_bf16 v[76:79], v[174:177], v[234:237], v[76:79]
	v_mfma_f32_16x16x32_bf16 v[72:75], v[184:187], v[234:237], v[72:75]
	s_setprio 0
	s_setprio 1
	v_mfma_f32_16x16x32_bf16 v[116:119], v[188:191], v[204:207], 0
	v_mfma_f32_16x16x32_bf16 v[112:115], v[196:199], v[204:207], 0
	v_mfma_f32_16x16x32_bf16 v[100:103], v[188:191], v[212:215], 0
	v_mfma_f32_16x16x32_bf16 v[96:99], v[196:199], v[212:215], 0
	v_mfma_f32_16x16x32_bf16 v[84:87], v[188:191], v[222:225], 0
	v_mfma_f32_16x16x32_bf16 v[80:83], v[196:199], v[222:225], 0
	v_mfma_f32_16x16x32_bf16 v[68:71], v[188:191], v[230:233], 0
	v_mfma_f32_16x16x32_bf16 v[64:67], v[196:199], v[230:233], 0
	v_mfma_f32_16x16x32_bf16 v[116:119], v[192:195], v[208:211], v[116:119]
	v_mfma_f32_16x16x32_bf16 v[112:115], v[200:203], v[208:211], v[112:115]
	v_mfma_f32_16x16x32_bf16 v[100:103], v[192:195], v[216:219], v[100:103]
	v_mfma_f32_16x16x32_bf16 v[96:99], v[200:203], v[216:219], v[96:99]
	v_mfma_f32_16x16x32_bf16 v[84:87], v[192:195], v[226:229], v[84:87]
	v_mfma_f32_16x16x32_bf16 v[80:83], v[200:203], v[226:229], v[80:83]
	v_mfma_f32_16x16x32_bf16 v[68:71], v[192:195], v[234:237], v[68:71]
	v_mfma_f32_16x16x32_bf16 v[64:67], v[200:203], v[234:237], v[64:67]
	s_setprio 0
	s_barrier
	s_add_i32 s68, s65, s56
	v_lshl_add_u64 v[144:145], s[34:35], 0, v[130:131]
	s_mov_b32 m0, s68
	ds_read_b128 v[204:207], v159 offset:16384
	ds_read_b128 v[208:211], v159 offset:17408
	ds_read_b128 v[212:215], v159 offset:18432
	ds_read_b128 v[216:219], v159 offset:19456
	ds_read_b128 v[222:225], v159 offset:20480
	ds_read_b128 v[226:229], v159 offset:21504
	ds_read_b128 v[230:233], v159 offset:22528
	ds_read_b128 v[234:237], v159 offset:23552
	global_load_lds_dwordx4 v[144:145], off
	s_add_i32 m0, s68, 0x2000
	s_add_u32 s76, s34, 0x40000
	v_lshl_add_u64 v[238:239], s[34:35], 0, v[134:135]
	s_addc_u32 s77, s35, 0
	s_add_i32 s68, s66, s56
	global_load_lds_dwordx4 v[238:239], off
	v_lshl_add_u64 v[240:241], s[76:77], 0, v[130:131]
	s_mov_b32 m0, s68
	v_lshl_add_u64 v[242:243], s[36:37], 0, v[132:133]
	global_load_lds_dwordx4 v[240:241], off
	v_lshl_add_u64 v[240:241], s[76:77], 0, v[134:135]
	s_add_i32 m0, s68, 0x2000
	s_nop 0
	global_load_lds_dwordx4 v[240:241], off
	v_lshl_add_u64 v[240:241], s[36:37], 0, v[128:129]
	s_mov_b32 m0, s57
	s_nop 0
	global_load_lds_dwordx4 v[240:241], off
	s_mov_b32 m0, s58
	s_nop 0
	global_load_lds_dwordx4 v[242:243], off
	s_waitcnt vmcnt(8)
	s_waitcnt lgkmcnt(0)
	s_barrier
; #define PG8_STAGE(bufoff, gbase, voff) do { _Pragma("unroll") for (int _i = 0; _i < 2; ++_i) \
;         __builtin_amdgcn_global_load_lds((const unsigned*)((const char*)(gbase) + (voff)[_i]), (PG8_LAS unsigned*)(lds + (bufoff) + ldsw + _i * 8192), 16, 0, 0); } while (0)
; #define PG8_LDA(dst, b, h) do { _Pragma("unroll") for (int m = 0; m < 4; ++m) _Pragma("unroll") for (int k = 0; k < 2; ++k) dst[m][k] = *(const PG8_LAS bf16x8*)(lds + PG8_SA(b, h) + aoff + m * 2048 + k * 1024); } while (0)
; #define PG8_LDB(dst, b, h) do { _Pragma("unroll") for (int n = 0; n < 2; ++n) _Pragma("unroll") for (int k = 0; k < 2; ++k) dst[n][k] = *(const PG8_LAS bf16x8*)(lds + PG8_SB(b, h) + boff + n * 2048 + k * 1024); } while (0)
; #define PG8_MMA(ai, bj, At, Bt) do { __builtin_amdgcn_s_setprio(1); _Pragma("unroll") for (int m = 0; m < 4; ++m) _Pragma("unroll") for (int n = 0; n < 2; ++n) _Pragma("unroll") for (int k = 0; k < 2; ++k) \
;         acc[ai][bj][m][n] = __builtin_amdgcn_mfma_f32_16x16x32_bf16(Bt[n][k], At[m][k], acc[ai][bj][m][n], 0, 0, 0); __builtin_amdgcn_s_setprio(0); } while (0)
; #define PG8_WAIT_V(n) asm volatile("s_waitcnt vmcnt(" #n ")" ::: "memory")
; #define PG8_WAIT_L(n) asm volatile("s_waitcnt lgkmcnt(" #n ")" ::: "memory")
; #define PG8_BAR __builtin_amdgcn_s_barrier()
; #define PG8_SCHED __builtin_amdgcn_sched_barrier(0)
; template <class Epi, class Sched>
; __device__ __forceinline__ void gemm_phase(PG8_LAS unsigned char* lds, PG8_LAS unsigned char* xl, const Gemm g, const Sched& S, const Epi& E) {
;     ...
;             PG8_WAIT_V(8); PG8_WAIT_L(0); PG8_BAR; PG8_MMA(1, 0, At, B0); PG8_MMA(1, 1, At, B1); PG8_BAR; PG8_SCHED;
;             PG8_LDB(B0, 1, 0); PG8_LDB(B1, 1, 1); PG8_SCHED; PG8_LDA(At, 1, 0); PG8_STAGE(PG8_SA(0, 1), a2 + hsA, voffA);
;             PG8_WAIT_V(8); PG8_WAIT_L(0); PG8_BAR; PG8_MMA(0, 0, At, B0); PG8_MMA(0, 1, At, B1); PG8_BAR; PG8_SCHED;
;             PG8_LDA(At, 1, 1); PG8_STAGE(PG8_SB(1, 0), b3, voffB); PG8_STAGE(PG8_SB(1, 1), b3 + hsB, voffB); PG8_STAGE(PG8_SA(1, 0), a3, voffA);
	s_setprio 1
	s_waitcnt lgkmcnt(0)
	v_mfma_f32_16x16x32_bf16 v[60:63], v[170:173], v[204:207], 0
	v_mfma_f32_16x16x32_bf16 v[56:59], v[180:183], v[204:207], 0
	v_mfma_f32_16x16x32_bf16 v[44:47], v[170:173], v[212:215], 0
	v_mfma_f32_16x16x32_bf16 v[40:43], v[180:183], v[212:215], 0
	v_mfma_f32_16x16x32_bf16 v[28:31], v[170:173], v[222:225], 0
	v_mfma_f32_16x16x32_bf16 v[24:27], v[180:183], v[222:225], 0
	v_mfma_f32_16x16x32_bf16 v[12:15], v[170:173], v[230:233], 0
	v_mfma_f32_16x16x32_bf16 v[8:11], v[180:183], v[230:233], 0
	v_mfma_f32_16x16x32_bf16 v[60:63], v[174:177], v[208:211], v[60:63]
	v_mfma_f32_16x16x32_bf16 v[56:59], v[184:187], v[208:211], v[56:59]
	v_mfma_f32_16x16x32_bf16 v[44:47], v[174:177], v[216:219], v[44:47]
	v_mfma_f32_16x16x32_bf16 v[40:43], v[184:187], v[216:219], v[40:43]
	v_mfma_f32_16x16x32_bf16 v[28:31], v[174:177], v[226:229], v[28:31]
	v_mfma_f32_16x16x32_bf16 v[24:27], v[184:187], v[226:229], v[24:27]
	v_mfma_f32_16x16x32_bf16 v[12:15], v[174:177], v[234:237], v[12:15]
	v_mfma_f32_16x16x32_bf16 v[8:11], v[184:187], v[234:237], v[8:11]
	s_setprio 0
	s_setprio 1
	v_mfma_f32_16x16x32_bf16 v[52:55], v[188:191], v[204:207], 0
	v_mfma_f32_16x16x32_bf16 v[48:51], v[196:199], v[204:207], 0
	v_mfma_f32_16x16x32_bf16 v[36:39], v[188:191], v[212:215], 0
	v_mfma_f32_16x16x32_bf16 v[32:35], v[196:199], v[212:215], 0
	v_mfma_f32_16x16x32_bf16 v[20:23], v[188:191], v[222:225], 0
	v_mfma_f32_16x16x32_bf16 v[16:19], v[196:199], v[222:225], 0
	v_mfma_f32_16x16x32_bf16 v[4:7], v[188:191], v[230:233], 0
	v_mfma_f32_16x16x32_bf16 v[0:3], v[196:199], v[230:233], 0
	v_mfma_f32_16x16x32_bf16 v[52:55], v[192:195], v[208:211], v[52:55]
	v_mfma_f32_16x16x32_bf16 v[48:51], v[200:203], v[208:211], v[48:51]
	v_mfma_f32_16x16x32_bf16 v[36:39], v[192:195], v[216:219], v[36:39]
	v_mfma_f32_16x16x32_bf16 v[32:35], v[200:203], v[216:219], v[32:35]
	v_mfma_f32_16x16x32_bf16 v[20:23], v[192:195], v[226:229], v[20:23]
	v_mfma_f32_16x16x32_bf16 v[16:19], v[200:203], v[226:229], v[16:19]
	v_mfma_f32_16x16x32_bf16 v[4:7], v[192:195], v[234:237], v[4:7]
	v_mfma_f32_16x16x32_bf16 v[0:3], v[200:203], v[234:237], v[0:3]
	s_setprio 0
	s_barrier
	s_add_i32 s68, 0, 0x18000
	v_add_u32_e32 v169, s68, v147
	s_add_i32 s76, 0, 0x1c000
	ds_read_b128 v[170:173], v169
	ds_read_b128 v[174:177], v169 offset:1024
	ds_read_b128 v[180:183], v169 offset:2048
	ds_read_b128 v[184:187], v169 offset:3072
	v_add_u32_e32 v169, s76, v147
	ds_read_b128 v[188:191], v169
	ds_read_b128 v[192:195], v169 offset:1024
	ds_read_b128 v[196:199], v169 offset:2048
	ds_read_b128 v[200:203], v169 offset:3072
	s_add_u32 s36, s36, 0x40000
	s_addc_u32 s37, s37, 0
	s_mov_b32 m0, s59
	v_lshl_add_u64 v[244:245], s[36:37], 0, v[128:129]
	ds_read_b128 v[204:207], v159 offset:32768
	ds_read_b128 v[208:211], v159 offset:33792
	ds_read_b128 v[212:215], v159 offset:34816
	ds_read_b128 v[216:219], v159 offset:35840
	ds_read_b128 v[222:225], v159 offset:36864
	ds_read_b128 v[226:229], v159 offset:37888
	ds_read_b128 v[230:233], v159 offset:38912
	ds_read_b128 v[234:237], v159 offset:39936
	global_load_lds_dwordx4 v[244:245], off
	v_lshl_add_u64 v[244:245], s[36:37], 0, v[132:133]
	s_mov_b32 m0, s60
	s_nop 0
	global_load_lds_dwordx4 v[244:245], off
	s_waitcnt vmcnt(8)
	s_waitcnt lgkmcnt(0)
	s_barrier
	s_setprio 1
	s_waitcnt lgkmcnt(0)
	v_mfma_f32_16x16x32_bf16 v[124:127], v[170:173], v[204:207], v[124:127]
	v_mfma_f32_16x16x32_bf16 v[120:123], v[180:183], v[204:207], v[120:123]
	v_mfma_f32_16x16x32_bf16 v[108:111], v[170:173], v[212:215], v[108:111]
	v_mfma_f32_16x16x32_bf16 v[104:107], v[180:183], v[212:215], v[104:107]
	v_mfma_f32_16x16x32_bf16 v[92:95], v[170:173], v[222:225], v[92:95]
	v_mfma_f32_16x16x32_bf16 v[88:91], v[180:183], v[222:225], v[88:91]
	v_mfma_f32_16x16x32_bf16 v[76:79], v[170:173], v[230:233], v[76:79]
	v_mfma_f32_16x16x32_bf16 v[72:75], v[180:183], v[230:233], v[72:75]
	v_mfma_f32_16x16x32_bf16 v[124:127], v[174:177], v[208:211], v[124:127]
	v_mfma_f32_16x16x32_bf16 v[120:123], v[184:187], v[208:211], v[120:123]
	v_mfma_f32_16x16x32_bf16 v[108:111], v[174:177], v[216:219], v[108:111]
	v_mfma_f32_16x16x32_bf16 v[104:107], v[184:187], v[216:219], v[104:107]
	v_mfma_f32_16x16x32_bf16 v[92:95], v[174:177], v[226:229], v[92:95]
	v_mfma_f32_16x16x32_bf16 v[88:91], v[184:187], v[226:229], v[88:91]
	v_mfma_f32_16x16x32_bf16 v[76:79], v[174:177], v[234:237], v[76:79]
	v_mfma_f32_16x16x32_bf16 v[72:75], v[184:187], v[234:237], v[72:75]
	s_setprio 0
	s_setprio 1
	v_mfma_f32_16x16x32_bf16 v[116:119], v[188:191], v[204:207], v[116:119]
	v_mfma_f32_16x16x32_bf16 v[112:115], v[196:199], v[204:207], v[112:115]
	v_mfma_f32_16x16x32_bf16 v[100:103], v[188:191], v[212:215], v[100:103]
	v_mfma_f32_16x16x32_bf16 v[96:99], v[196:199], v[212:215], v[96:99]
	v_mfma_f32_16x16x32_bf16 v[84:87], v[188:191], v[222:225], v[84:87]
	v_mfma_f32_16x16x32_bf16 v[80:83], v[196:199], v[222:225], v[80:83]
	v_mfma_f32_16x16x32_bf16 v[68:71], v[188:191], v[230:233], v[68:71]
	v_mfma_f32_16x16x32_bf16 v[64:67], v[196:199], v[230:233], v[64:67]
	v_mfma_f32_16x16x32_bf16 v[116:119], v[192:195], v[208:211], v[116:119]
	v_mfma_f32_16x16x32_bf16 v[112:115], v[200:203], v[208:211], v[112:115]
	v_mfma_f32_16x16x32_bf16 v[100:103], v[192:195], v[216:219], v[100:103]
	v_mfma_f32_16x16x32_bf16 v[96:99], v[200:203], v[216:219], v[96:99]
	v_mfma_f32_16x16x32_bf16 v[84:87], v[192:195], v[226:229], v[84:87]
	v_mfma_f32_16x16x32_bf16 v[80:83], v[200:203], v[226:229], v[80:83]
	v_mfma_f32_16x16x32_bf16 v[68:71], v[192:195], v[234:237], v[68:71]
	v_mfma_f32_16x16x32_bf16 v[64:67], v[200:203], v[234:237], v[64:67]
	s_setprio 0
	s_barrier
; #define PG8_STAGE(bufoff, gbase, voff) do { _Pragma("unroll") for (int _i = 0; _i < 2; ++_i) \
;         __builtin_amdgcn_global_load_lds((const unsigned*)((const char*)(gbase) + (voff)[_i]), (PG8_LAS unsigned*)(lds + (bufoff) + ldsw + _i * 8192), 16, 0, 0); } while (0)
; #define PG8_LDA(dst, b, h) do { _Pragma("unroll") for (int m = 0; m < 4; ++m) _Pragma("unroll") for (int k = 0; k < 2; ++k) dst[m][k] = *(const PG8_LAS bf16x8*)(lds + PG8_SA(b, h) + aoff + m * 2048 + k * 1024); } while (0)
; #define PG8_MMA(ai, bj, At, Bt) do { __builtin_amdgcn_s_setprio(1); _Pragma("unroll") for (int m = 0; m < 4; ++m) _Pragma("unroll") for (int n = 0; n < 2; ++n) _Pragma("unroll") for (int k = 0; k < 2; ++k) \
;         acc[ai][bj][m][n] = __builtin_amdgcn_mfma_f32_16x16x32_bf16(Bt[n][k], At[m][k], acc[ai][bj][m][n], 0, 0, 0); __builtin_amdgcn_s_setprio(0); } while (0)
; #define PG8_WAIT_V(n) asm volatile("s_waitcnt vmcnt(" #n ")" ::: "memory")
; #define PG8_WAIT_L(n) asm volatile("s_waitcnt lgkmcnt(" #n ")" ::: "memory")
; #define PG8_BAR __builtin_amdgcn_s_barrier()
; #define PG8_SCHED __builtin_amdgcn_sched_barrier(0)
; template <class Epi, class Sched>
; __device__ __forceinline__ void gemm_phase(PG8_LAS unsigned char* lds, PG8_LAS unsigned char* xl, const Gemm g, const Sched& S, const Epi& E) {
;     ...
;             PG8_LDA(At, 1, 1); PG8_STAGE(PG8_SB(1, 0), b3, voffB); PG8_STAGE(PG8_SB(1, 1), b3 + hsB, voffB); PG8_STAGE(PG8_SA(1, 0), a3, voffA);
;             PG8_WAIT_V(8); PG8_WAIT_L(0); PG8_BAR; PG8_MMA(1, 0, At, B0); PG8_MMA(1, 1, At, B1); PG8_BAR; PG8_SCHED;
;         }
	s_add_i32 s36, s68, s56
	v_lshl_add_u64 v[144:145], v[144:145], 0, s[16:17]
	s_mov_b32 m0, s36
	ds_read_b128 v[204:207], v159 offset:49152
	ds_read_b128 v[208:211], v159 offset:50176
	ds_read_b128 v[212:215], v159 offset:51200
	ds_read_b128 v[216:219], v159 offset:52224
	ds_read_b128 v[222:225], v159 offset:53248
	ds_read_b128 v[226:229], v159 offset:54272
	ds_read_b128 v[230:233], v159 offset:55296
	ds_read_b128 v[234:237], v159 offset:56320
	global_load_lds_dwordx4 v[144:145], off
	s_add_i32 m0, s36, 0x2000
	s_add_u32 s34, s34, 0x40080
	v_lshl_add_u64 v[144:145], v[238:239], 0, s[16:17]
	s_addc_u32 s35, s35, 0
	s_add_i32 s36, s76, s56
	global_load_lds_dwordx4 v[144:145], off
	v_lshl_add_u64 v[144:145], s[34:35], 0, v[130:131]
	s_mov_b32 m0, s36
	s_nop 0
	global_load_lds_dwordx4 v[144:145], off
	v_lshl_add_u64 v[144:145], s[34:35], 0, v[134:135]
	s_add_i32 m0, s36, 0x2000
	s_nop 0
	global_load_lds_dwordx4 v[144:145], off
	v_lshl_add_u64 v[144:145], v[240:241], 0, s[16:17]
	s_mov_b32 m0, s62
	s_nop 0
	global_load_lds_dwordx4 v[144:145], off
	v_lshl_add_u64 v[144:145], v[242:243], 0, s[16:17]
	s_mov_b32 m0, s63
	s_nop 0
	global_load_lds_dwordx4 v[144:145], off
	s_waitcnt vmcnt(8)
	s_waitcnt lgkmcnt(0)
	s_barrier
	s_setprio 1
	s_waitcnt lgkmcnt(0)
	v_mfma_f32_16x16x32_bf16 v[60:63], v[170:173], v[204:207], v[60:63]
	v_mfma_f32_16x16x32_bf16 v[56:59], v[180:183], v[204:207], v[56:59]
	v_mfma_f32_16x16x32_bf16 v[44:47], v[170:173], v[212:215], v[44:47]
	v_mfma_f32_16x16x32_bf16 v[40:43], v[180:183], v[212:215], v[40:43]
	v_mfma_f32_16x16x32_bf16 v[28:31], v[170:173], v[222:225], v[28:31]
	v_mfma_f32_16x16x32_bf16 v[24:27], v[180:183], v[222:225], v[24:27]
	v_mfma_f32_16x16x32_bf16 v[12:15], v[170:173], v[230:233], v[12:15]
	v_mfma_f32_16x16x32_bf16 v[8:11], v[180:183], v[230:233], v[8:11]
	v_mfma_f32_16x16x32_bf16 v[60:63], v[174:177], v[208:211], v[60:63]
	v_mfma_f32_16x16x32_bf16 v[56:59], v[184:187], v[208:211], v[56:59]
	v_mfma_f32_16x16x32_bf16 v[44:47], v[174:177], v[216:219], v[44:47]
	v_mfma_f32_16x16x32_bf16 v[40:43], v[184:187], v[216:219], v[40:43]
	v_mfma_f32_16x16x32_bf16 v[28:31], v[174:177], v[226:229], v[28:31]
	v_mfma_f32_16x16x32_bf16 v[24:27], v[184:187], v[226:229], v[24:27]
	v_mfma_f32_16x16x32_bf16 v[12:15], v[174:177], v[234:237], v[12:15]
	v_mfma_f32_16x16x32_bf16 v[8:11], v[184:187], v[234:237], v[8:11]
	s_setprio 0
	s_setprio 1
	v_mfma_f32_16x16x32_bf16 v[52:55], v[188:191], v[204:207], v[52:55]
	v_mfma_f32_16x16x32_bf16 v[48:51], v[196:199], v[204:207], v[48:51]
	v_mfma_f32_16x16x32_bf16 v[36:39], v[188:191], v[212:215], v[36:39]
	v_mfma_f32_16x16x32_bf16 v[32:35], v[196:199], v[212:215], v[32:35]
	v_mfma_f32_16x16x32_bf16 v[20:23], v[188:191], v[222:225], v[20:23]
	v_mfma_f32_16x16x32_bf16 v[16:19], v[196:199], v[222:225], v[16:19]
	v_mfma_f32_16x16x32_bf16 v[4:7], v[188:191], v[230:233], v[4:7]
	v_mfma_f32_16x16x32_bf16 v[0:3], v[196:199], v[230:233], v[0:3]
	v_mfma_f32_16x16x32_bf16 v[52:55], v[192:195], v[208:211], v[52:55]
	v_mfma_f32_16x16x32_bf16 v[48:51], v[200:203], v[208:211], v[48:51]
	v_mfma_f32_16x16x32_bf16 v[36:39], v[192:195], v[216:219], v[36:39]
	v_mfma_f32_16x16x32_bf16 v[32:35], v[200:203], v[216:219], v[32:35]
	v_mfma_f32_16x16x32_bf16 v[20:23], v[192:195], v[226:229], v[20:23]
	v_mfma_f32_16x16x32_bf16 v[16:19], v[200:203], v[226:229], v[16:19]
	v_mfma_f32_16x16x32_bf16 v[4:7], v[192:195], v[234:237], v[4:7]
	v_mfma_f32_16x16x32_bf16 v[0:3], v[200:203], v[234:237], v[0:3]
	s_setprio 0
	s_barrier
	s_add_i32 s75, s75, 2
	s_add_u32 s73, s73, 0x100
	s_addc_u32 s74, s74, 0
	s_add_u32 s30, s30, 0x100
	s_addc_u32 s31, s31, 0
	s_cmp_gt_u32 s75, 13
	s_cbranch_scc1 .Lpeel_after_P7

; #define PG8_BAR __builtin_amdgcn_s_barrier()
;     __device__ __forceinline__ void operator()(Acc& acc, const Unit& u, int wr, int wc, int fr, int fq, PG8_LAS unsigned char* xl) const {
;     ...
;             for (int m = 0; m < 4; ++m) { const int rl = ai * HALF + wr * 64 + m * 16 + fr; const int row = u.r0 + rl; const size_t off = (size_t)row * DM + col; float s = 0.f;
; #pragma unroll
;                 for (int bj = 0; bj < 2; ++bj) {
;                     f32x4 b0, b1;
;                     if (BASE_BF16) unpack8(*(const u32x4*)((const bf16_t*)base + off + bj * HALF), b0, b1);
; template <class Epi, class Sched>
; __device__ __forceinline__ void gemm_phase(PG8_LAS unsigned char* lds, PG8_LAS unsigned char* xl, const Gemm g, const Sched& S, const Epi& E) {
;     ...
;         if (wr == 0) PG8_BAR;
.Lpeel_after_P7:
	v_add_u32_e32 v252, s53, v148
	v_ashrrev_i32_e32 v253, 31, v252
	v_add_u32_e32 v222, s55, v146
	v_ashrrev_i32_e32 v223, 31, v222
	v_lshlrev_b64 v[222:223], 10, v[222:223]
	v_lshl_add_u64 v[222:223], v[222:223], 0, v[252:253]
	v_lshl_add_u64 v[222:223], v[222:223], 1, s[10:11]
	global_load_dwordx4 v[184:187], v[222:223], off
	global_load_dwordx4 v[188:191], v[222:223], off offset:256
	v_add_u32_e32 v222, s55, v149
	v_ashrrev_i32_e32 v223, 31, v222
	v_lshlrev_b64 v[222:223], 10, v[222:223]
	v_lshl_add_u64 v[222:223], v[222:223], 0, v[252:253]
	v_lshl_add_u64 v[222:223], v[222:223], 1, s[10:11]
	global_load_dwordx4 v[192:195], v[222:223], off
	global_load_dwordx4 v[196:199], v[222:223], off offset:256
	v_add_u32_e32 v222, s55, v150
	v_ashrrev_i32_e32 v223, 31, v222
	v_lshlrev_b64 v[222:223], 10, v[222:223]
	v_lshl_add_u64 v[222:223], v[222:223], 0, v[252:253]
	v_lshl_add_u64 v[222:223], v[222:223], 1, s[10:11]
	global_load_dwordx4 v[200:203], v[222:223], off
	global_load_dwordx4 v[204:207], v[222:223], off offset:256
	v_add_u32_e32 v222, s55, v151
	v_ashrrev_i32_e32 v223, 31, v222
	v_lshlrev_b64 v[222:223], 10, v[222:223]
	v_lshl_add_u64 v[222:223], v[222:223], 0, v[252:253]
	v_lshl_add_u64 v[222:223], v[222:223], 1, s[10:11]
	global_load_dwordx4 v[208:211], v[222:223], off
	global_load_dwordx4 v[212:215], v[222:223], off offset:256
	v_add_u32_e32 v222, s55, v152
	v_ashrrev_i32_e32 v223, 31, v222
	v_lshlrev_b64 v[222:223], 10, v[222:223]
	v_lshl_add_u64 v[222:223], v[222:223], 0, v[252:253]
	v_lshl_add_u64 v[222:223], v[222:223], 1, s[10:11]
	global_load_dwordx4 v[216:219], v[222:223], off
	global_load_dwordx4 v[224:227], v[222:223], off offset:256
	v_add_u32_e32 v222, s55, v153
	v_ashrrev_i32_e32 v223, 31, v222
	v_lshlrev_b64 v[222:223], 10, v[222:223]
	v_lshl_add_u64 v[222:223], v[222:223], 0, v[252:253]
	v_lshl_add_u64 v[222:223], v[222:223], 1, s[10:11]
	global_load_dwordx4 v[228:231], v[222:223], off
	global_load_dwordx4 v[232:235], v[222:223], off offset:256
	v_add_u32_e32 v222, s55, v155
	v_ashrrev_i32_e32 v223, 31, v222
	v_lshlrev_b64 v[222:223], 10, v[222:223]
	v_lshl_add_u64 v[222:223], v[222:223], 0, v[252:253]
	v_lshl_add_u64 v[222:223], v[222:223], 1, s[10:11]
	global_load_dwordx4 v[236:239], v[222:223], off
	global_load_dwordx4 v[240:243], v[222:223], off offset:256
	v_add_u32_e32 v222, s55, v156
	v_ashrrev_i32_e32 v223, 31, v222
	v_lshlrev_b64 v[222:223], 10, v[222:223]
	v_lshl_add_u64 v[222:223], v[222:223], 0, v[252:253]
	v_lshl_add_u64 v[222:223], v[222:223], 1, s[10:11]
	global_load_dwordx4 v[244:247], v[222:223], off
	global_load_dwordx4 v[248:251], v[222:223], off offset:256
	s_and_b64 vcc, exec, s[18:19]
	s_cbranch_vccz .LBB0_728
	s_barrier

; #define PG8_STAGE(bufoff, gbase, voff) do { _Pragma("unroll") for (int _i = 0; _i < 2; ++_i) \
;         __builtin_amdgcn_global_load_lds((const unsigned*)((const char*)(gbase) + (voff)[_i]), (PG8_LAS unsigned*)(lds + (bufoff) + ldsw + _i * 8192), 16, 0, 0); } while (0)
; #define PG8_LDA(dst, b, h) do { _Pragma("unroll") for (int m = 0; m < 4; ++m) _Pragma("unroll") for (int k = 0; k < 2; ++k) dst[m][k] = *(const PG8_LAS bf16x8*)(lds + PG8_SA(b, h) + aoff + m * 2048 + k * 1024); } while (0)
; #define PG8_LDB(dst, b, h) do { _Pragma("unroll") for (int n = 0; n < 2; ++n) _Pragma("unroll") for (int k = 0; k < 2; ++k) dst[n][k] = *(const PG8_LAS bf16x8*)(lds + PG8_SB(b, h) + boff + n * 2048 + k * 1024); } while (0)
; #define PG8_MMA(ai, bj, At, Bt) do { __builtin_amdgcn_s_setprio(1); _Pragma("unroll") for (int m = 0; m < 4; ++m) _Pragma("unroll") for (int n = 0; n < 2; ++n) _Pragma("unroll") for (int k = 0; k < 2; ++k) \
;         acc[ai][bj][m][n] = __builtin_amdgcn_mfma_f32_16x16x32_bf16(Bt[n][k], At[m][k], acc[ai][bj][m][n], 0, 0, 0); __builtin_amdgcn_s_setprio(0); } while (0)
; #define PG8_BAR __builtin_amdgcn_s_barrier()
; template <class Epi, class Sched>
; __device__ __forceinline__ void gemm_phase(PG8_LAS unsigned char* lds, PG8_LAS unsigned char* xl, const Gemm g, const Sched& S, const Epi& E) {
;     ...
;         const bool has_next = S.next(ui + 1, nxt);
;         const char* nA = has_next ? (const char*)g.A + nxt.aoff : cA; const char* nB = has_next ? (const char*)g.Bt + nxt.boff : cB;
; #pragma unroll 1
;         for (int t = 0; t < nt; t += 2) {
;             const bool last = (t == nt - 2);
;             const char* a1 = cA + (size_t)(t + 1) * kstep;
;             const char* a2 = last ? nA : cA + (size_t)(t + 2) * kstep; const char* b2 = last ? nB : cB + (size_t)(t + 2) * kstep;
;             const char* a3 = a2 + kstep; const char* b3 = b2 + kstep;
;             PG8_LDB(B0, 0, 0); PG8_LDB(B1, 0, 1); PG8_SCHED; PG8_LDA(At, 0, 0); PG8_STAGE(PG8_SA(1, 1), a1 + hsA, voffA);
;             PG8_WAIT_V(8); PG8_WAIT_L(0); PG8_BAR; PG8_MMA(0, 0, At, B0); PG8_MMA(0, 1, At, B1); PG8_BAR; PG8_SCHED;
;             PG8_LDA(At, 0, 1); PG8_STAGE(PG8_SB(0, 0), b2, voffB); PG8_STAGE(PG8_SB(0, 1), b2 + hsB, voffB); PG8_STAGE(PG8_SA(0, 0), a2, voffA);
;             PG8_WAIT_V(8); PG8_WAIT_L(0); PG8_BAR; PG8_MMA(1, 0, At, B0); PG8_MMA(1, 1, At, B1); PG8_BAR; PG8_SCHED;
.LBB0_824:
	s_add_u32 s26, s37, s20
	s_addc_u32 s27, s42, s21
	s_and_b64 s[28:29], s[6:7], exec
	s_cselect_b32 s46, s27, s31
	s_cselect_b32 s47, s26, s30
	s_add_u32 s28, s43, s22
	s_addc_u32 s29, s50, s23
	s_and_b64 s[34:35], s[6:7], exec
	s_cselect_b32 s70, s29, s3
	s_cselect_b32 s72, s28, s2
	s_add_u32 s73, s2, 0x100
	s_addc_u32 s74, s3, 0
	s_add_u32 s2, s30, 0x40080
	v_mov_b32_e32 v0, 0
	s_addc_u32 s3, s31, 0
	s_mov_b32 s75, -2
	ds_read_b128 v[170:173], v164
	ds_read_b128 v[174:177], v164 offset:1024
	ds_read_b128 v[180:183], v164 offset:2048
	ds_read_b128 v[184:187], v164 offset:3072
	ds_read_b128 v[188:191], v165
	ds_read_b128 v[192:195], v165 offset:1024
	ds_read_b128 v[196:199], v165 offset:2048
	ds_read_b128 v[200:203], v165 offset:3072
	s_add_u32 s30, s2, 0xfffc0080
	s_addc_u32 s31, s3, -1
	s_cmp_eq_u32 s75, 12
	s_cselect_b32 s35, s46, s31
	s_cselect_b32 s34, s47, s30
	s_cselect_b32 s31, s70, s74
	s_cselect_b32 s30, s72, s73
	v_lshl_add_u64 v[238:239], s[2:3], 0, v[140:141]
	s_add_i32 m0, s55, 0xc000
	ds_read_b128 v[204:207], v166
	ds_read_b128 v[208:211], v166 offset:1024
	ds_read_b128 v[212:215], v166 offset:2048
	ds_read_b128 v[216:219], v166 offset:3072
	ds_read_b128 v[222:225], v166 offset:4096
	ds_read_b128 v[226:229], v166 offset:5120
	ds_read_b128 v[230:233], v166 offset:6144
	ds_read_b128 v[234:237], v166 offset:7168
	global_load_lds_dwordx4 v[238:239], off
	v_lshl_add_u64 v[238:239], s[2:3], 0, v[138:139]
	s_add_i32 m0, s55, 0xe000
	s_nop 0
	global_load_lds_dwordx4 v[238:239], off
	s_waitcnt vmcnt(8)
	s_waitcnt lgkmcnt(0)
	s_barrier
	s_setprio 1
	s_waitcnt lgkmcnt(0)
	v_mfma_f32_16x16x32_bf16 v[124:127], v[170:173], v[204:207], 0
	v_mfma_f32_16x16x32_bf16 v[116:119], v[180:183], v[204:207], 0
	v_mfma_f32_16x16x32_bf16 v[108:111], v[170:173], v[212:215], 0
	v_mfma_f32_16x16x32_bf16 v[100:103], v[180:183], v[212:215], 0
	v_mfma_f32_16x16x32_bf16 v[92:95], v[170:173], v[222:225], 0
	v_mfma_f32_16x16x32_bf16 v[84:87], v[180:183], v[222:225], 0
	v_mfma_f32_16x16x32_bf16 v[76:79], v[170:173], v[230:233], 0
	v_mfma_f32_16x16x32_bf16 v[68:71], v[180:183], v[230:233], 0
	v_mfma_f32_16x16x32_bf16 v[124:127], v[174:177], v[208:211], v[124:127]
	v_mfma_f32_16x16x32_bf16 v[116:119], v[184:187], v[208:211], v[116:119]
	v_mfma_f32_16x16x32_bf16 v[108:111], v[174:177], v[216:219], v[108:111]
	v_mfma_f32_16x16x32_bf16 v[100:103], v[184:187], v[216:219], v[100:103]
	v_mfma_f32_16x16x32_bf16 v[92:95], v[174:177], v[226:229], v[92:95]
	v_mfma_f32_16x16x32_bf16 v[84:87], v[184:187], v[226:229], v[84:87]
	v_mfma_f32_16x16x32_bf16 v[76:79], v[174:177], v[234:237], v[76:79]
	v_mfma_f32_16x16x32_bf16 v[68:71], v[184:187], v[234:237], v[68:71]
	s_setprio 0
	s_setprio 1
	v_mfma_f32_16x16x32_bf16 v[120:123], v[188:191], v[204:207], 0
	v_mfma_f32_16x16x32_bf16 v[112:115], v[196:199], v[204:207], 0
	v_mfma_f32_16x16x32_bf16 v[104:107], v[188:191], v[212:215], 0
	v_mfma_f32_16x16x32_bf16 v[96:99], v[196:199], v[212:215], 0
	v_mfma_f32_16x16x32_bf16 v[88:91], v[188:191], v[222:225], 0
	v_mfma_f32_16x16x32_bf16 v[80:83], v[196:199], v[222:225], 0
	v_mfma_f32_16x16x32_bf16 v[72:75], v[188:191], v[230:233], 0
	v_mfma_f32_16x16x32_bf16 v[64:67], v[196:199], v[230:233], 0
	v_mfma_f32_16x16x32_bf16 v[120:123], v[192:195], v[208:211], v[120:123]
	v_mfma_f32_16x16x32_bf16 v[112:115], v[200:203], v[208:211], v[112:115]
	v_mfma_f32_16x16x32_bf16 v[104:107], v[192:195], v[216:219], v[104:107]
	v_mfma_f32_16x16x32_bf16 v[96:99], v[200:203], v[216:219], v[96:99]
	v_mfma_f32_16x16x32_bf16 v[88:91], v[192:195], v[226:229], v[88:91]
	v_mfma_f32_16x16x32_bf16 v[80:83], v[200:203], v[226:229], v[80:83]
	v_mfma_f32_16x16x32_bf16 v[72:75], v[192:195], v[234:237], v[72:75]
	v_mfma_f32_16x16x32_bf16 v[64:67], v[200:203], v[234:237], v[64:67]
	s_setprio 0
	s_barrier
	s_add_i32 s68, s54, s51
	v_lshl_add_u64 v[238:239], s[30:31], 0, v[132:133]
	s_mov_b32 m0, s68
	ds_read_b128 v[204:207], v166 offset:16384
	ds_read_b128 v[208:211], v166 offset:17408
	ds_read_b128 v[212:215], v166 offset:18432
	ds_read_b128 v[216:219], v166 offset:19456
	ds_read_b128 v[222:225], v166 offset:20480
	ds_read_b128 v[226:229], v166 offset:21504
	ds_read_b128 v[230:233], v166 offset:22528
	ds_read_b128 v[234:237], v166 offset:23552
	global_load_lds_dwordx4 v[238:239], off
	s_add_i32 m0, s68, 0x2000
	s_add_u32 s76, s30, 0x40000
	v_lshl_add_u64 v[240:241], s[30:31], 0, v[128:129]
	s_addc_u32 s77, s31, 0
	s_add_i32 s68, s62, s51
	global_load_lds_dwordx4 v[240:241], off
	v_lshl_add_u64 v[242:243], s[76:77], 0, v[132:133]
	s_mov_b32 m0, s68
	v_lshl_add_u64 v[244:245], s[34:35], 0, v[130:131]
	global_load_lds_dwordx4 v[242:243], off
	v_lshl_add_u64 v[242:243], s[76:77], 0, v[128:129]
	s_add_i32 m0, s68, 0x2000
	s_nop 0
	global_load_lds_dwordx4 v[242:243], off
	v_lshl_add_u64 v[242:243], s[34:35], 0, v[134:135]
	s_mov_b32 m0, s55
	s_nop 0
	global_load_lds_dwordx4 v[242:243], off
	s_mov_b32 m0, s56
	s_nop 0
	global_load_lds_dwordx4 v[244:245], off
	s_waitcnt vmcnt(8)
	s_waitcnt lgkmcnt(0)
	s_barrier
; #define PG8_STAGE(bufoff, gbase, voff) do { _Pragma("unroll") for (int _i = 0; _i < 2; ++_i) \
;         __builtin_amdgcn_global_load_lds((const unsigned*)((const char*)(gbase) + (voff)[_i]), (PG8_LAS unsigned*)(lds + (bufoff) + ldsw + _i * 8192), 16, 0, 0); } while (0)
; #define PG8_LDA(dst, b, h) do { _Pragma("unroll") for (int m = 0; m < 4; ++m) _Pragma("unroll") for (int k = 0; k < 2; ++k) dst[m][k] = *(const PG8_LAS bf16x8*)(lds + PG8_SA(b, h) + aoff + m * 2048 + k * 1024); } while (0)
; #define PG8_LDB(dst, b, h) do { _Pragma("unroll") for (int n = 0; n < 2; ++n) _Pragma("unroll") for (int k = 0; k < 2; ++k) dst[n][k] = *(const PG8_LAS bf16x8*)(lds + PG8_SB(b, h) + boff + n * 2048 + k * 1024); } while (0)
; #define PG8_MMA(ai, bj, At, Bt) do { __builtin_amdgcn_s_setprio(1); _Pragma("unroll") for (int m = 0; m < 4; ++m) _Pragma("unroll") for (int n = 0; n < 2; ++n) _Pragma("unroll") for (int k = 0; k < 2; ++k) \
;         acc[ai][bj][m][n] = __builtin_amdgcn_mfma_f32_16x16x32_bf16(Bt[n][k], At[m][k], acc[ai][bj][m][n], 0, 0, 0); __builtin_amdgcn_s_setprio(0); } while (0)
; #define PG8_WAIT_V(n) asm volatile("s_waitcnt vmcnt(" #n ")" ::: "memory")
; #define PG8_WAIT_L(n) asm volatile("s_waitcnt lgkmcnt(" #n ")" ::: "memory")
; #define PG8_BAR __builtin_amdgcn_s_barrier()
; #define PG8_SCHED __builtin_amdgcn_sched_barrier(0)
; template <class Epi, class Sched>
; __device__ __forceinline__ void gemm_phase(PG8_LAS unsigned char* lds, PG8_LAS unsigned char* xl, const Gemm g, const Sched& S, const Epi& E) {
;     ...
;             PG8_WAIT_V(8); PG8_WAIT_L(0); PG8_BAR; PG8_MMA(0, 0, At, B0); PG8_MMA(0, 1, At, B1); PG8_BAR; PG8_SCHED;
;             PG8_LDA(At, 0, 1); PG8_STAGE(PG8_SB(0, 0), b2, voffB); PG8_STAGE(PG8_SB(0, 1), b2 + hsB, voffB); PG8_STAGE(PG8_SA(0, 0), a2, voffA);
;             PG8_WAIT_V(8); PG8_WAIT_L(0); PG8_BAR; PG8_MMA(1, 0, At, B0); PG8_MMA(1, 1, At, B1); PG8_BAR; PG8_SCHED;
;             PG8_LDB(B0, 1, 0); PG8_LDB(B1, 1, 1); PG8_SCHED; PG8_LDA(At, 1, 0); PG8_STAGE(PG8_SA(0, 1), a2 + hsA, voffA);
;             PG8_WAIT_V(8); PG8_WAIT_L(0); PG8_BAR; PG8_MMA(0, 0, At, B0); PG8_MMA(0, 1, At, B1); PG8_BAR; PG8_SCHED;
	s_setprio 1
	s_waitcnt lgkmcnt(0)
	v_mfma_f32_16x16x32_bf16 v[60:63], v[170:173], v[204:207], 0
	v_mfma_f32_16x16x32_bf16 v[52:55], v[180:183], v[204:207], 0
	v_mfma_f32_16x16x32_bf16 v[44:47], v[170:173], v[212:215], 0
	v_mfma_f32_16x16x32_bf16 v[36:39], v[180:183], v[212:215], 0
	v_mfma_f32_16x16x32_bf16 v[28:31], v[170:173], v[222:225], 0
	v_mfma_f32_16x16x32_bf16 v[20:23], v[180:183], v[222:225], 0
	v_mfma_f32_16x16x32_bf16 v[12:15], v[170:173], v[230:233], 0
	v_mfma_f32_16x16x32_bf16 v[4:7], v[180:183], v[230:233], 0
	v_mfma_f32_16x16x32_bf16 v[60:63], v[174:177], v[208:211], v[60:63]
	v_mfma_f32_16x16x32_bf16 v[52:55], v[184:187], v[208:211], v[52:55]
	v_mfma_f32_16x16x32_bf16 v[44:47], v[174:177], v[216:219], v[44:47]
	v_mfma_f32_16x16x32_bf16 v[36:39], v[184:187], v[216:219], v[36:39]
	v_mfma_f32_16x16x32_bf16 v[28:31], v[174:177], v[226:229], v[28:31]
	v_mfma_f32_16x16x32_bf16 v[20:23], v[184:187], v[226:229], v[20:23]
	v_mfma_f32_16x16x32_bf16 v[12:15], v[174:177], v[234:237], v[12:15]
	v_mfma_f32_16x16x32_bf16 v[4:7], v[184:187], v[234:237], v[4:7]
	s_setprio 0
	s_setprio 1
	v_mfma_f32_16x16x32_bf16 v[56:59], v[188:191], v[204:207], 0
	v_mfma_f32_16x16x32_bf16 v[48:51], v[196:199], v[204:207], 0
	v_mfma_f32_16x16x32_bf16 v[40:43], v[188:191], v[212:215], 0
	v_mfma_f32_16x16x32_bf16 v[32:35], v[196:199], v[212:215], 0
	v_mfma_f32_16x16x32_bf16 v[24:27], v[188:191], v[222:225], 0
	v_mfma_f32_16x16x32_bf16 v[16:19], v[196:199], v[222:225], 0
	v_mfma_f32_16x16x32_bf16 v[8:11], v[188:191], v[230:233], 0
	v_mfma_f32_16x16x32_bf16 v[0:3], v[196:199], v[230:233], 0
	v_mfma_f32_16x16x32_bf16 v[56:59], v[192:195], v[208:211], v[56:59]
	v_mfma_f32_16x16x32_bf16 v[48:51], v[200:203], v[208:211], v[48:51]
	v_mfma_f32_16x16x32_bf16 v[40:43], v[192:195], v[216:219], v[40:43]
	v_mfma_f32_16x16x32_bf16 v[32:35], v[200:203], v[216:219], v[32:35]
	v_mfma_f32_16x16x32_bf16 v[24:27], v[192:195], v[226:229], v[24:27]
	v_mfma_f32_16x16x32_bf16 v[16:19], v[200:203], v[226:229], v[16:19]
	v_mfma_f32_16x16x32_bf16 v[8:11], v[192:195], v[234:237], v[8:11]
	v_mfma_f32_16x16x32_bf16 v[0:3], v[200:203], v[234:237], v[0:3]
	s_setprio 0
	s_barrier
	s_add_i32 s68, 0, 0x18000
	v_add_u32_e32 v169, s68, v147
	s_add_i32 s76, 0, 0x1c000
	ds_read_b128 v[170:173], v169
	ds_read_b128 v[174:177], v169 offset:1024
	ds_read_b128 v[180:183], v169 offset:2048
	ds_read_b128 v[184:187], v169 offset:3072
	v_add_u32_e32 v169, s76, v147
	ds_read_b128 v[188:191], v169
	ds_read_b128 v[192:195], v169 offset:1024
	ds_read_b128 v[196:199], v169 offset:2048
	ds_read_b128 v[200:203], v169 offset:3072
	s_add_u32 s34, s34, 0x40000
	s_addc_u32 s35, s35, 0
	s_mov_b32 m0, s57
	v_lshl_add_u64 v[246:247], s[34:35], 0, v[134:135]
	ds_read_b128 v[204:207], v166 offset:32768
	ds_read_b128 v[208:211], v166 offset:33792
	ds_read_b128 v[212:215], v166 offset:34816
	ds_read_b128 v[216:219], v166 offset:35840
	ds_read_b128 v[222:225], v166 offset:36864
	ds_read_b128 v[226:229], v166 offset:37888
	ds_read_b128 v[230:233], v166 offset:38912
	ds_read_b128 v[234:237], v166 offset:39936
	global_load_lds_dwordx4 v[246:247], off
	v_lshl_add_u64 v[246:247], s[34:35], 0, v[130:131]
	s_mov_b32 m0, s58
	s_nop 0
	global_load_lds_dwordx4 v[246:247], off
	s_waitcnt vmcnt(8)
	s_waitcnt lgkmcnt(0)
	s_barrier
	s_setprio 1
	s_waitcnt lgkmcnt(0)
	v_mfma_f32_16x16x32_bf16 v[124:127], v[170:173], v[204:207], v[124:127]
	v_mfma_f32_16x16x32_bf16 v[116:119], v[180:183], v[204:207], v[116:119]
	v_mfma_f32_16x16x32_bf16 v[108:111], v[170:173], v[212:215], v[108:111]
	v_mfma_f32_16x16x32_bf16 v[100:103], v[180:183], v[212:215], v[100:103]
	v_mfma_f32_16x16x32_bf16 v[92:95], v[170:173], v[222:225], v[92:95]
	v_mfma_f32_16x16x32_bf16 v[84:87], v[180:183], v[222:225], v[84:87]
	v_mfma_f32_16x16x32_bf16 v[76:79], v[170:173], v[230:233], v[76:79]
	v_mfma_f32_16x16x32_bf16 v[68:71], v[180:183], v[230:233], v[68:71]
	v_mfma_f32_16x16x32_bf16 v[124:127], v[174:177], v[208:211], v[124:127]
	v_mfma_f32_16x16x32_bf16 v[116:119], v[184:187], v[208:211], v[116:119]
	v_mfma_f32_16x16x32_bf16 v[108:111], v[174:177], v[216:219], v[108:111]
	v_mfma_f32_16x16x32_bf16 v[100:103], v[184:187], v[216:219], v[100:103]
	v_mfma_f32_16x16x32_bf16 v[92:95], v[174:177], v[226:229], v[92:95]
	v_mfma_f32_16x16x32_bf16 v[84:87], v[184:187], v[226:229], v[84:87]
	v_mfma_f32_16x16x32_bf16 v[76:79], v[174:177], v[234:237], v[76:79]
	v_mfma_f32_16x16x32_bf16 v[68:71], v[184:187], v[234:237], v[68:71]
	s_setprio 0
	s_setprio 1
	v_mfma_f32_16x16x32_bf16 v[120:123], v[188:191], v[204:207], v[120:123]
	v_mfma_f32_16x16x32_bf16 v[112:115], v[196:199], v[204:207], v[112:115]
	v_mfma_f32_16x16x32_bf16 v[104:107], v[188:191], v[212:215], v[104:107]
	v_mfma_f32_16x16x32_bf16 v[96:99], v[196:199], v[212:215], v[96:99]
	v_mfma_f32_16x16x32_bf16 v[88:91], v[188:191], v[222:225], v[88:91]
	v_mfma_f32_16x16x32_bf16 v[80:83], v[196:199], v[222:225], v[80:83]
	v_mfma_f32_16x16x32_bf16 v[72:75], v[188:191], v[230:233], v[72:75]
	v_mfma_f32_16x16x32_bf16 v[64:67], v[196:199], v[230:233], v[64:67]
	v_mfma_f32_16x16x32_bf16 v[120:123], v[192:195], v[208:211], v[120:123]
	v_mfma_f32_16x16x32_bf16 v[112:115], v[200:203], v[208:211], v[112:115]
	v_mfma_f32_16x16x32_bf16 v[104:107], v[192:195], v[216:219], v[104:107]
	v_mfma_f32_16x16x32_bf16 v[96:99], v[200:203], v[216:219], v[96:99]
	v_mfma_f32_16x16x32_bf16 v[88:91], v[192:195], v[226:229], v[88:91]
	v_mfma_f32_16x16x32_bf16 v[80:83], v[200:203], v[226:229], v[80:83]
	v_mfma_f32_16x16x32_bf16 v[72:75], v[192:195], v[234:237], v[72:75]
	v_mfma_f32_16x16x32_bf16 v[64:67], v[200:203], v[234:237], v[64:67]
	s_setprio 0
	s_barrier
; #define PG8_STAGE(bufoff, gbase, voff) do { _Pragma("unroll") for (int _i = 0; _i < 2; ++_i) \
;         __builtin_amdgcn_global_load_lds((const unsigned*)((const char*)(gbase) + (voff)[_i]), (PG8_LAS unsigned*)(lds + (bufoff) + ldsw + _i * 8192), 16, 0, 0); } while (0)
; #define PG8_LDA(dst, b, h) do { _Pragma("unroll") for (int m = 0; m < 4; ++m) _Pragma("unroll") for (int k = 0; k < 2; ++k) dst[m][k] = *(const PG8_LAS bf16x8*)(lds + PG8_SA(b, h) + aoff + m * 2048 + k * 1024); } while (0)
; #define PG8_MMA(ai, bj, At, Bt) do { __builtin_amdgcn_s_setprio(1); _Pragma("unroll") for (int m = 0; m < 4; ++m) _Pragma("unroll") for (int n = 0; n < 2; ++n) _Pragma("unroll") for (int k = 0; k < 2; ++k) \
;         acc[ai][bj][m][n] = __builtin_amdgcn_mfma_f32_16x16x32_bf16(Bt[n][k], At[m][k], acc[ai][bj][m][n], 0, 0, 0); __builtin_amdgcn_s_setprio(0); } while (0)
; #define PG8_WAIT_V(n) asm volatile("s_waitcnt vmcnt(" #n ")" ::: "memory")
; #define PG8_WAIT_L(n) asm volatile("s_waitcnt lgkmcnt(" #n ")" ::: "memory")
; #define PG8_BAR __builtin_amdgcn_s_barrier()
; #define PG8_SCHED __builtin_amdgcn_sched_barrier(0)
; template <class Epi, class Sched>
; __device__ __forceinline__ void gemm_phase(PG8_LAS unsigned char* lds, PG8_LAS unsigned char* xl, const Gemm g, const Sched& S, const Epi& E) {
;     ...
;             PG8_LDA(At, 1, 1); PG8_STAGE(PG8_SB(1, 0), b3, voffB); PG8_STAGE(PG8_SB(1, 1), b3 + hsB, voffB); PG8_STAGE(PG8_SA(1, 0), a3, voffA);
;             PG8_WAIT_V(8); PG8_WAIT_L(0); PG8_BAR; PG8_MMA(1, 0, At, B0); PG8_MMA(1, 1, At, B1); PG8_BAR; PG8_SCHED;
;         }
	s_add_i32 s34, s68, s51
	v_lshl_add_u64 v[238:239], v[238:239], 0, s[16:17]
	s_mov_b32 m0, s34
	ds_read_b128 v[204:207], v166 offset:49152
	ds_read_b128 v[208:211], v166 offset:50176
	ds_read_b128 v[212:215], v166 offset:51200
	ds_read_b128 v[216:219], v166 offset:52224
	ds_read_b128 v[222:225], v166 offset:53248
	ds_read_b128 v[226:229], v166 offset:54272
	ds_read_b128 v[230:233], v166 offset:55296
	ds_read_b128 v[234:237], v166 offset:56320
	global_load_lds_dwordx4 v[238:239], off
	s_add_i32 m0, s34, 0x2000
	s_add_u32 s30, s30, 0x40080
	v_lshl_add_u64 v[238:239], v[240:241], 0, s[16:17]
	s_addc_u32 s31, s31, 0
	s_add_i32 s34, s76, s51
	global_load_lds_dwordx4 v[238:239], off
	v_lshl_add_u64 v[238:239], s[30:31], 0, v[132:133]
	s_mov_b32 m0, s34
	s_nop 0
	global_load_lds_dwordx4 v[238:239], off
	v_lshl_add_u64 v[238:239], s[30:31], 0, v[128:129]
	s_add_i32 m0, s34, 0x2000
	s_nop 0
	global_load_lds_dwordx4 v[238:239], off
	v_lshl_add_u64 v[238:239], v[242:243], 0, s[16:17]
	s_mov_b32 m0, s59
	s_nop 0
	global_load_lds_dwordx4 v[238:239], off
	v_lshl_add_u64 v[238:239], v[244:245], 0, s[16:17]
	s_mov_b32 m0, s61
	s_nop 0
	global_load_lds_dwordx4 v[238:239], off
	s_waitcnt vmcnt(8)
	s_waitcnt lgkmcnt(0)
	s_barrier
	s_setprio 1
	s_waitcnt lgkmcnt(0)
	v_mfma_f32_16x16x32_bf16 v[60:63], v[170:173], v[204:207], v[60:63]
	v_mfma_f32_16x16x32_bf16 v[52:55], v[180:183], v[204:207], v[52:55]
	v_mfma_f32_16x16x32_bf16 v[44:47], v[170:173], v[212:215], v[44:47]
	v_mfma_f32_16x16x32_bf16 v[36:39], v[180:183], v[212:215], v[36:39]
	v_mfma_f32_16x16x32_bf16 v[28:31], v[170:173], v[222:225], v[28:31]
	v_mfma_f32_16x16x32_bf16 v[20:23], v[180:183], v[222:225], v[20:23]
	v_mfma_f32_16x16x32_bf16 v[12:15], v[170:173], v[230:233], v[12:15]
	v_mfma_f32_16x16x32_bf16 v[4:7], v[180:183], v[230:233], v[4:7]
	v_mfma_f32_16x16x32_bf16 v[60:63], v[174:177], v[208:211], v[60:63]
	v_mfma_f32_16x16x32_bf16 v[52:55], v[184:187], v[208:211], v[52:55]
	v_mfma_f32_16x16x32_bf16 v[44:47], v[174:177], v[216:219], v[44:47]
	v_mfma_f32_16x16x32_bf16 v[36:39], v[184:187], v[216:219], v[36:39]
	v_mfma_f32_16x16x32_bf16 v[28:31], v[174:177], v[226:229], v[28:31]
	v_mfma_f32_16x16x32_bf16 v[20:23], v[184:187], v[226:229], v[20:23]
	v_mfma_f32_16x16x32_bf16 v[12:15], v[174:177], v[234:237], v[12:15]
	v_mfma_f32_16x16x32_bf16 v[4:7], v[184:187], v[234:237], v[4:7]
	s_setprio 0
	s_setprio 1
	v_mfma_f32_16x16x32_bf16 v[56:59], v[188:191], v[204:207], v[56:59]
	v_mfma_f32_16x16x32_bf16 v[48:51], v[196:199], v[204:207], v[48:51]
	v_mfma_f32_16x16x32_bf16 v[40:43], v[188:191], v[212:215], v[40:43]
	v_mfma_f32_16x16x32_bf16 v[32:35], v[196:199], v[212:215], v[32:35]
	v_mfma_f32_16x16x32_bf16 v[24:27], v[188:191], v[222:225], v[24:27]
	v_mfma_f32_16x16x32_bf16 v[16:19], v[196:199], v[222:225], v[16:19]
	v_mfma_f32_16x16x32_bf16 v[8:11], v[188:191], v[230:233], v[8:11]
	v_mfma_f32_16x16x32_bf16 v[0:3], v[196:199], v[230:233], v[0:3]
	v_mfma_f32_16x16x32_bf16 v[56:59], v[192:195], v[208:211], v[56:59]
	v_mfma_f32_16x16x32_bf16 v[48:51], v[200:203], v[208:211], v[48:51]
	v_mfma_f32_16x16x32_bf16 v[40:43], v[192:195], v[216:219], v[40:43]
	v_mfma_f32_16x16x32_bf16 v[32:35], v[200:203], v[216:219], v[32:35]
	v_mfma_f32_16x16x32_bf16 v[24:27], v[192:195], v[226:229], v[24:27]
	v_mfma_f32_16x16x32_bf16 v[16:19], v[200:203], v[226:229], v[16:19]
	v_mfma_f32_16x16x32_bf16 v[8:11], v[192:195], v[234:237], v[8:11]
	v_mfma_f32_16x16x32_bf16 v[0:3], v[200:203], v[234:237], v[0:3]
	s_setprio 0
	s_barrier
	s_add_i32 s75, s75, 2
	s_add_u32 s73, s73, 0x100
	s_addc_u32 s74, s74, 0
	s_add_u32 s2, s2, 0x100
	s_addc_u32 s3, s3, 0
	s_cmp_gt_u32 s75, 13
	s_cbranch_scc1 .Lpeel_after_P8

; #define PG8_BAR __builtin_amdgcn_s_barrier()
; template <class Epi, class Sched>
; __device__ __forceinline__ void gemm_phase(PG8_LAS unsigned char* lds, PG8_LAS unsigned char* xl, const Gemm g, const Sched& S, const Epi& E) {
;     ...
;         }
;         if (wr == 0) PG8_BAR;
.Lpeel_after_P8:
	s_and_b64 vcc, exec, s[18:19]
	s_cbranch_vccz .LBB0_828
	s_barrier

; #define PG8_STAGE(bufoff, gbase, voff) do { _Pragma("unroll") for (int _i = 0; _i < 2; ++_i) \
;         __builtin_amdgcn_global_load_lds((const unsigned*)((const char*)(gbase) + (voff)[_i]), (PG8_LAS unsigned*)(lds + (bufoff) + ldsw + _i * 8192), 16, 0, 0); } while (0)
; #define PG8_LDA(dst, b, h) do { _Pragma("unroll") for (int m = 0; m < 4; ++m) _Pragma("unroll") for (int k = 0; k < 2; ++k) dst[m][k] = *(const PG8_LAS bf16x8*)(lds + PG8_SA(b, h) + aoff + m * 2048 + k * 1024); } while (0)
; #define PG8_LDB(dst, b, h) do { _Pragma("unroll") for (int n = 0; n < 2; ++n) _Pragma("unroll") for (int k = 0; k < 2; ++k) dst[n][k] = *(const PG8_LAS bf16x8*)(lds + PG8_SB(b, h) + boff + n * 2048 + k * 1024); } while (0)
; #define PG8_MMA(ai, bj, At, Bt) do { __builtin_amdgcn_s_setprio(1); _Pragma("unroll") for (int m = 0; m < 4; ++m) _Pragma("unroll") for (int n = 0; n < 2; ++n) _Pragma("unroll") for (int k = 0; k < 2; ++k) \
;         acc[ai][bj][m][n] = __builtin_amdgcn_mfma_f32_16x16x32_bf16(Bt[n][k], At[m][k], acc[ai][bj][m][n], 0, 0, 0); __builtin_amdgcn_s_setprio(0); } while (0)
; #define PG8_BAR __builtin_amdgcn_s_barrier()
; template <class Epi, class Sched>
; __device__ __forceinline__ void gemm_phase(PG8_LAS unsigned char* lds, PG8_LAS unsigned char* xl, const Gemm g, const Sched& S, const Epi& E) {
;     ...
;         const bool has_next = S.next(ui + 1, nxt);
;         const char* nA = has_next ? (const char*)g.A + nxt.aoff : cA; const char* nB = has_next ? (const char*)g.Bt + nxt.boff : cB;
; #pragma unroll 1
;         for (int t = 0; t < nt; t += 2) {
;             const bool last = (t == nt - 2);
;             const char* a1 = cA + (size_t)(t + 1) * kstep;
;             const char* a2 = last ? nA : cA + (size_t)(t + 2) * kstep; const char* b2 = last ? nB : cB + (size_t)(t + 2) * kstep;
;             const char* a3 = a2 + kstep; const char* b3 = b2 + kstep;
;             PG8_LDB(B0, 0, 0); PG8_LDB(B1, 0, 1); PG8_SCHED; PG8_LDA(At, 0, 0); PG8_STAGE(PG8_SA(1, 1), a1 + hsA, voffA);
;             PG8_WAIT_V(8); PG8_WAIT_L(0); PG8_BAR; PG8_MMA(0, 0, At, B0); PG8_MMA(0, 1, At, B1); PG8_BAR; PG8_SCHED;
;             PG8_LDA(At, 0, 1); PG8_STAGE(PG8_SB(0, 0), b2, voffB); PG8_STAGE(PG8_SB(0, 1), b2 + hsB, voffB); PG8_STAGE(PG8_SA(0, 0), a2, voffA);
;             PG8_WAIT_V(8); PG8_WAIT_L(0); PG8_BAR; PG8_MMA(1, 0, At, B0); PG8_MMA(1, 1, At, B1); PG8_BAR; PG8_SCHED;
.LBB0_941:
	s_add_u32 s34, s55, s28
	s_addc_u32 s35, s56, s29
	s_and_b64 s[36:37], s[10:11], exec
	s_cselect_b32 s33, s35, s3
	s_cselect_b32 s46, s34, s2
	s_add_u32 s36, s57, s30
	s_addc_u32 s37, s58, s31
	s_and_b64 s[50:51], s[10:11], exec
	s_cselect_b32 s47, s37, s49
	s_cselect_b32 s77, s36, s48
	s_add_u32 s78, s48, 0x100
	v_mov_b32_e32 v0, 0
	s_addc_u32 s79, s49, 0
	s_mov_b32 s80, -2
	ds_read_b128 v[144:147], v199
	ds_read_b128 v[148:151], v199 offset:1024
	ds_read_b128 v[152:155], v199 offset:2048
	ds_read_b128 v[156:159], v199 offset:3072
	ds_read_b128 v[160:163], v200
	ds_read_b128 v[164:167], v200 offset:1024
	ds_read_b128 v[168:171], v200 offset:2048
	ds_read_b128 v[172:175], v200 offset:3072
	s_add_u32 s48, s2, 0x100
	s_addc_u32 s49, s3, 0
	s_cmp_eq_u32 s80, 40
	s_cselect_b32 s53, s33, s49
	s_cselect_b32 s52, s46, s48
	s_cselect_b32 s51, s47, s79
	s_cselect_b32 s50, s77, s78
	v_lshl_add_u64 v[176:177], s[2:3], 0, v[138:139]
	s_add_i32 m0, s43, 0xc000
	ds_read_b128 v[214:217], v201
	ds_read_b128 v[222:225], v201 offset:1024
	ds_read_b128 v[226:229], v201 offset:2048
	ds_read_b128 v[230:233], v201 offset:3072
	ds_read_b128 v[234:237], v201 offset:4096
	ds_read_b128 v[238:241], v201 offset:5120
	ds_read_b128 v[242:245], v201 offset:6144
	ds_read_b128 v[246:249], v201 offset:7168
	global_load_lds_dwordx4 v[176:177], off
	v_lshl_add_u64 v[176:177], s[2:3], 0, v[136:137]
	s_add_i32 m0, s43, 0xe000
	s_nop 0
	global_load_lds_dwordx4 v[176:177], off
	s_waitcnt vmcnt(8)
	s_waitcnt lgkmcnt(0)
	s_barrier
	s_setprio 1
	s_waitcnt lgkmcnt(0)
	v_mfma_f32_16x16x32_bf16 v[124:127], v[144:147], v[214:217], 0
	v_mfma_f32_16x16x32_bf16 v[120:123], v[152:155], v[214:217], 0
	v_mfma_f32_16x16x32_bf16 v[108:111], v[144:147], v[226:229], 0
	v_mfma_f32_16x16x32_bf16 v[104:107], v[152:155], v[226:229], 0
	v_mfma_f32_16x16x32_bf16 v[92:95], v[144:147], v[234:237], 0
	v_mfma_f32_16x16x32_bf16 v[88:91], v[152:155], v[234:237], 0
	v_mfma_f32_16x16x32_bf16 v[76:79], v[144:147], v[242:245], 0
	v_mfma_f32_16x16x32_bf16 v[72:75], v[152:155], v[242:245], 0
	v_mfma_f32_16x16x32_bf16 v[124:127], v[148:151], v[222:225], v[124:127]
	v_mfma_f32_16x16x32_bf16 v[120:123], v[156:159], v[222:225], v[120:123]
	v_mfma_f32_16x16x32_bf16 v[108:111], v[148:151], v[230:233], v[108:111]
	v_mfma_f32_16x16x32_bf16 v[104:107], v[156:159], v[230:233], v[104:107]
	v_mfma_f32_16x16x32_bf16 v[92:95], v[148:151], v[238:241], v[92:95]
	v_mfma_f32_16x16x32_bf16 v[88:91], v[156:159], v[238:241], v[88:91]
	v_mfma_f32_16x16x32_bf16 v[76:79], v[148:151], v[246:249], v[76:79]
	v_mfma_f32_16x16x32_bf16 v[72:75], v[156:159], v[246:249], v[72:75]
	s_setprio 0
	s_setprio 1
	v_mfma_f32_16x16x32_bf16 v[116:119], v[160:163], v[214:217], 0
	v_mfma_f32_16x16x32_bf16 v[112:115], v[168:171], v[214:217], 0
	v_mfma_f32_16x16x32_bf16 v[100:103], v[160:163], v[226:229], 0
	v_mfma_f32_16x16x32_bf16 v[96:99], v[168:171], v[226:229], 0
	v_mfma_f32_16x16x32_bf16 v[84:87], v[160:163], v[234:237], 0
	v_mfma_f32_16x16x32_bf16 v[80:83], v[168:171], v[234:237], 0
	v_mfma_f32_16x16x32_bf16 v[68:71], v[160:163], v[242:245], 0
	v_mfma_f32_16x16x32_bf16 v[64:67], v[168:171], v[242:245], 0
	v_mfma_f32_16x16x32_bf16 v[116:119], v[164:167], v[222:225], v[116:119]
	v_mfma_f32_16x16x32_bf16 v[112:115], v[172:175], v[222:225], v[112:115]
	v_mfma_f32_16x16x32_bf16 v[100:103], v[164:167], v[230:233], v[100:103]
	v_mfma_f32_16x16x32_bf16 v[96:99], v[172:175], v[230:233], v[96:99]
	v_mfma_f32_16x16x32_bf16 v[84:87], v[164:167], v[238:241], v[84:87]
	v_mfma_f32_16x16x32_bf16 v[80:83], v[172:175], v[238:241], v[80:83]
	v_mfma_f32_16x16x32_bf16 v[68:71], v[164:167], v[246:249], v[68:71]
	v_mfma_f32_16x16x32_bf16 v[64:67], v[172:175], v[246:249], v[64:67]
	s_setprio 0
	s_barrier
	s_add_i32 s2, s70, s42
	v_lshl_add_u64 v[176:177], s[50:51], 0, v[130:131]
	s_mov_b32 m0, s2
	ds_read_b128 v[214:217], v201 offset:16384
	ds_read_b128 v[222:225], v201 offset:17408
	ds_read_b128 v[226:229], v201 offset:18432
	ds_read_b128 v[230:233], v201 offset:19456
	ds_read_b128 v[234:237], v201 offset:20480
	ds_read_b128 v[238:241], v201 offset:21504
	ds_read_b128 v[242:245], v201 offset:22528
	ds_read_b128 v[246:249], v201 offset:23552
	global_load_lds_dwordx4 v[176:177], off
	s_add_i32 m0, s2, 0x2000
	s_add_u32 s2, s50, 0xb0000
	v_lshl_add_u64 v[218:219], s[50:51], 0, v[134:135]
	s_addc_u32 s3, s51, 0
	s_add_i32 s68, s71, s42
	global_load_lds_dwordx4 v[218:219], off
	v_lshl_add_u64 v[250:251], s[2:3], 0, v[130:131]
	s_mov_b32 m0, s68
	v_lshl_add_u64 v[252:253], s[52:53], 0, v[132:133]
	global_load_lds_dwordx4 v[250:251], off
	v_lshl_add_u64 v[250:251], s[2:3], 0, v[134:135]
	s_add_i32 m0, s68, 0x2000
	s_nop 0
	global_load_lds_dwordx4 v[250:251], off
	v_lshl_add_u64 v[250:251], s[52:53], 0, v[128:129]
	s_mov_b32 m0, s43
	s_nop 0
	global_load_lds_dwordx4 v[250:251], off
	s_mov_b32 m0, s59
	s_nop 0
	global_load_lds_dwordx4 v[252:253], off
	s_waitcnt vmcnt(8)
	s_waitcnt lgkmcnt(0)
	s_barrier
; #define PG8_STAGE(bufoff, gbase, voff) do { _Pragma("unroll") for (int _i = 0; _i < 2; ++_i) \
;         __builtin_amdgcn_global_load_lds((const unsigned*)((const char*)(gbase) + (voff)[_i]), (PG8_LAS unsigned*)(lds + (bufoff) + ldsw + _i * 8192), 16, 0, 0); } while (0)
; #define PG8_LDA(dst, b, h) do { _Pragma("unroll") for (int m = 0; m < 4; ++m) _Pragma("unroll") for (int k = 0; k < 2; ++k) dst[m][k] = *(const PG8_LAS bf16x8*)(lds + PG8_SA(b, h) + aoff + m * 2048 + k * 1024); } while (0)
; #define PG8_LDB(dst, b, h) do { _Pragma("unroll") for (int n = 0; n < 2; ++n) _Pragma("unroll") for (int k = 0; k < 2; ++k) dst[n][k] = *(const PG8_LAS bf16x8*)(lds + PG8_SB(b, h) + boff + n * 2048 + k * 1024); } while (0)
; #define PG8_MMA(ai, bj, At, Bt) do { __builtin_amdgcn_s_setprio(1); _Pragma("unroll") for (int m = 0; m < 4; ++m) _Pragma("unroll") for (int n = 0; n < 2; ++n) _Pragma("unroll") for (int k = 0; k < 2; ++k) \
;         acc[ai][bj][m][n] = __builtin_amdgcn_mfma_f32_16x16x32_bf16(Bt[n][k], At[m][k], acc[ai][bj][m][n], 0, 0, 0); __builtin_amdgcn_s_setprio(0); } while (0)
; #define PG8_WAIT_V(n) asm volatile("s_waitcnt vmcnt(" #n ")" ::: "memory")
; #define PG8_WAIT_L(n) asm volatile("s_waitcnt lgkmcnt(" #n ")" ::: "memory")
; #define PG8_BAR __builtin_amdgcn_s_barrier()
; #define PG8_SCHED __builtin_amdgcn_sched_barrier(0)
; template <class Epi, class Sched>
; __device__ __forceinline__ void gemm_phase(PG8_LAS unsigned char* lds, PG8_LAS unsigned char* xl, const Gemm g, const Sched& S, const Epi& E) {
;     ...
;             PG8_WAIT_V(8); PG8_WAIT_L(0); PG8_BAR; PG8_MMA(1, 0, At, B0); PG8_MMA(1, 1, At, B1); PG8_BAR; PG8_SCHED;
;             PG8_LDB(B0, 1, 0); PG8_LDB(B1, 1, 1); PG8_SCHED; PG8_LDA(At, 1, 0); PG8_STAGE(PG8_SA(0, 1), a2 + hsA, voffA);
;             PG8_WAIT_V(8); PG8_WAIT_L(0); PG8_BAR; PG8_MMA(0, 0, At, B0); PG8_MMA(0, 1, At, B1); PG8_BAR; PG8_SCHED;
	s_setprio 1
	s_waitcnt lgkmcnt(0)
	v_mfma_f32_16x16x32_bf16 v[60:63], v[144:147], v[214:217], 0
	v_mfma_f32_16x16x32_bf16 v[56:59], v[152:155], v[214:217], 0
	v_mfma_f32_16x16x32_bf16 v[44:47], v[144:147], v[226:229], 0
	v_mfma_f32_16x16x32_bf16 v[40:43], v[152:155], v[226:229], 0
	v_mfma_f32_16x16x32_bf16 v[28:31], v[144:147], v[234:237], 0
	v_mfma_f32_16x16x32_bf16 v[24:27], v[152:155], v[234:237], 0
	v_mfma_f32_16x16x32_bf16 v[12:15], v[144:147], v[242:245], 0
	v_mfma_f32_16x16x32_bf16 v[8:11], v[152:155], v[242:245], 0
	v_mfma_f32_16x16x32_bf16 v[60:63], v[148:151], v[222:225], v[60:63]
	v_mfma_f32_16x16x32_bf16 v[56:59], v[156:159], v[222:225], v[56:59]
	v_mfma_f32_16x16x32_bf16 v[44:47], v[148:151], v[230:233], v[44:47]
	v_mfma_f32_16x16x32_bf16 v[40:43], v[156:159], v[230:233], v[40:43]
	v_mfma_f32_16x16x32_bf16 v[28:31], v[148:151], v[238:241], v[28:31]
	v_mfma_f32_16x16x32_bf16 v[24:27], v[156:159], v[238:241], v[24:27]
	v_mfma_f32_16x16x32_bf16 v[12:15], v[148:151], v[246:249], v[12:15]
	v_mfma_f32_16x16x32_bf16 v[8:11], v[156:159], v[246:249], v[8:11]
	s_setprio 0
	s_setprio 1
	v_mfma_f32_16x16x32_bf16 v[52:55], v[160:163], v[214:217], 0
	v_mfma_f32_16x16x32_bf16 v[48:51], v[168:171], v[214:217], 0
	v_mfma_f32_16x16x32_bf16 v[36:39], v[160:163], v[226:229], 0
	v_mfma_f32_16x16x32_bf16 v[32:35], v[168:171], v[226:229], 0
	v_mfma_f32_16x16x32_bf16 v[20:23], v[160:163], v[234:237], 0
	v_mfma_f32_16x16x32_bf16 v[16:19], v[168:171], v[234:237], 0
	v_mfma_f32_16x16x32_bf16 v[4:7], v[160:163], v[242:245], 0
	v_mfma_f32_16x16x32_bf16 v[0:3], v[168:171], v[242:245], 0
	v_mfma_f32_16x16x32_bf16 v[52:55], v[164:167], v[222:225], v[52:55]
	v_mfma_f32_16x16x32_bf16 v[48:51], v[172:175], v[222:225], v[48:51]
	v_mfma_f32_16x16x32_bf16 v[36:39], v[164:167], v[230:233], v[36:39]
	v_mfma_f32_16x16x32_bf16 v[32:35], v[172:175], v[230:233], v[32:35]
	v_mfma_f32_16x16x32_bf16 v[20:23], v[164:167], v[238:241], v[20:23]
	v_mfma_f32_16x16x32_bf16 v[16:19], v[172:175], v[238:241], v[16:19]
	v_mfma_f32_16x16x32_bf16 v[4:7], v[164:167], v[246:249], v[4:7]
	v_mfma_f32_16x16x32_bf16 v[0:3], v[172:175], v[246:249], v[0:3]
	s_setprio 0
	s_barrier
	s_add_i32 s68, 0, 0x18000
	s_add_i32 s81, 0, 0x1c000
	v_add_u32_e32 v156, s68, v181
	v_add_u32_e32 v172, s81, v181
	ds_read_b128 v[144:147], v156
	ds_read_b128 v[148:151], v156 offset:1024
	ds_read_b128 v[152:155], v156 offset:2048
	ds_read_b128 v[156:159], v156 offset:3072
	ds_read_b128 v[160:163], v172
	ds_read_b128 v[164:167], v172 offset:1024
	ds_read_b128 v[168:171], v172 offset:2048
	ds_read_b128 v[172:175], v172 offset:3072
	s_add_u32 s2, s52, 0xb0000
	s_addc_u32 s3, s53, 0
	s_mov_b32 m0, s60
	v_lshl_add_u64 v[212:213], s[2:3], 0, v[128:129]
	ds_read_b128 v[214:217], v201 offset:32768
	ds_read_b128 v[222:225], v201 offset:33792
	ds_read_b128 v[226:229], v201 offset:34816
	ds_read_b128 v[230:233], v201 offset:35840
	ds_read_b128 v[234:237], v201 offset:36864
	ds_read_b128 v[238:241], v201 offset:37888
	ds_read_b128 v[242:245], v201 offset:38912
	ds_read_b128 v[246:249], v201 offset:39936
	global_load_lds_dwordx4 v[212:213], off
	v_lshl_add_u64 v[212:213], s[2:3], 0, v[132:133]
	s_mov_b32 m0, s61
	s_nop 0
	global_load_lds_dwordx4 v[212:213], off
	s_waitcnt vmcnt(8)
	s_waitcnt lgkmcnt(0)
	s_barrier
	s_setprio 1
	s_waitcnt lgkmcnt(0)
	v_mfma_f32_16x16x32_bf16 v[124:127], v[144:147], v[214:217], v[124:127]
	v_mfma_f32_16x16x32_bf16 v[120:123], v[152:155], v[214:217], v[120:123]
	v_mfma_f32_16x16x32_bf16 v[108:111], v[144:147], v[226:229], v[108:111]
	v_mfma_f32_16x16x32_bf16 v[104:107], v[152:155], v[226:229], v[104:107]
	v_mfma_f32_16x16x32_bf16 v[92:95], v[144:147], v[234:237], v[92:95]
	v_mfma_f32_16x16x32_bf16 v[88:91], v[152:155], v[234:237], v[88:91]
	v_mfma_f32_16x16x32_bf16 v[76:79], v[144:147], v[242:245], v[76:79]
	v_mfma_f32_16x16x32_bf16 v[72:75], v[152:155], v[242:245], v[72:75]
	v_mfma_f32_16x16x32_bf16 v[124:127], v[148:151], v[222:225], v[124:127]
	v_mfma_f32_16x16x32_bf16 v[120:123], v[156:159], v[222:225], v[120:123]
	v_mfma_f32_16x16x32_bf16 v[108:111], v[148:151], v[230:233], v[108:111]
	v_mfma_f32_16x16x32_bf16 v[104:107], v[156:159], v[230:233], v[104:107]
	v_mfma_f32_16x16x32_bf16 v[92:95], v[148:151], v[238:241], v[92:95]
	v_mfma_f32_16x16x32_bf16 v[88:91], v[156:159], v[238:241], v[88:91]
	v_mfma_f32_16x16x32_bf16 v[76:79], v[148:151], v[246:249], v[76:79]
	v_mfma_f32_16x16x32_bf16 v[72:75], v[156:159], v[246:249], v[72:75]
	s_setprio 0
	s_setprio 1
	v_mfma_f32_16x16x32_bf16 v[116:119], v[160:163], v[214:217], v[116:119]
	v_mfma_f32_16x16x32_bf16 v[112:115], v[168:171], v[214:217], v[112:115]
	v_mfma_f32_16x16x32_bf16 v[100:103], v[160:163], v[226:229], v[100:103]
	v_mfma_f32_16x16x32_bf16 v[96:99], v[168:171], v[226:229], v[96:99]
	v_mfma_f32_16x16x32_bf16 v[84:87], v[160:163], v[234:237], v[84:87]
	v_mfma_f32_16x16x32_bf16 v[80:83], v[168:171], v[234:237], v[80:83]
	v_mfma_f32_16x16x32_bf16 v[68:71], v[160:163], v[242:245], v[68:71]
	v_mfma_f32_16x16x32_bf16 v[64:67], v[168:171], v[242:245], v[64:67]
	v_mfma_f32_16x16x32_bf16 v[116:119], v[164:167], v[222:225], v[116:119]
	v_mfma_f32_16x16x32_bf16 v[112:115], v[172:175], v[222:225], v[112:115]
	v_mfma_f32_16x16x32_bf16 v[100:103], v[164:167], v[230:233], v[100:103]
	v_mfma_f32_16x16x32_bf16 v[96:99], v[172:175], v[230:233], v[96:99]
	v_mfma_f32_16x16x32_bf16 v[84:87], v[164:167], v[238:241], v[84:87]
	v_mfma_f32_16x16x32_bf16 v[80:83], v[172:175], v[238:241], v[80:83]
	v_mfma_f32_16x16x32_bf16 v[68:71], v[164:167], v[246:249], v[68:71]
	v_mfma_f32_16x16x32_bf16 v[64:67], v[172:175], v[246:249], v[64:67]
	s_setprio 0
	s_barrier
; #define PG8_STAGE(bufoff, gbase, voff) do { _Pragma("unroll") for (int _i = 0; _i < 2; ++_i) \
;         __builtin_amdgcn_global_load_lds((const unsigned*)((const char*)(gbase) + (voff)[_i]), (PG8_LAS unsigned*)(lds + (bufoff) + ldsw + _i * 8192), 16, 0, 0); } while (0)
; #define PG8_LDA(dst, b, h) do { _Pragma("unroll") for (int m = 0; m < 4; ++m) _Pragma("unroll") for (int k = 0; k < 2; ++k) dst[m][k] = *(const PG8_LAS bf16x8*)(lds + PG8_SA(b, h) + aoff + m * 2048 + k * 1024); } while (0)
; #define PG8_MMA(ai, bj, At, Bt) do { __builtin_amdgcn_s_setprio(1); _Pragma("unroll") for (int m = 0; m < 4; ++m) _Pragma("unroll") for (int n = 0; n < 2; ++n) _Pragma("unroll") for (int k = 0; k < 2; ++k) \
;         acc[ai][bj][m][n] = __builtin_amdgcn_mfma_f32_16x16x32_bf16(Bt[n][k], At[m][k], acc[ai][bj][m][n], 0, 0, 0); __builtin_amdgcn_s_setprio(0); } while (0)
; #define PG8_WAIT_V(n) asm volatile("s_waitcnt vmcnt(" #n ")" ::: "memory")
; #define PG8_WAIT_L(n) asm volatile("s_waitcnt lgkmcnt(" #n ")" ::: "memory")
; #define PG8_BAR __builtin_amdgcn_s_barrier()
; #define PG8_SCHED __builtin_amdgcn_sched_barrier(0)
; template <class Epi, class Sched>
; __device__ __forceinline__ void gemm_phase(PG8_LAS unsigned char* lds, PG8_LAS unsigned char* xl, const Gemm g, const Sched& S, const Epi& E) {
;     ...
;             PG8_LDA(At, 1, 1); PG8_STAGE(PG8_SB(1, 0), b3, voffB); PG8_STAGE(PG8_SB(1, 1), b3 + hsB, voffB); PG8_STAGE(PG8_SA(1, 0), a3, voffA);
;             PG8_WAIT_V(8); PG8_WAIT_L(0); PG8_BAR; PG8_MMA(1, 0, At, B0); PG8_MMA(1, 1, At, B1); PG8_BAR; PG8_SCHED;
;         }
	s_add_i32 s2, s68, s42
	v_lshl_add_u64 v[176:177], v[176:177], 0, s[22:23]
	s_mov_b32 m0, s2
	ds_read_b128 v[214:217], v201 offset:49152
	ds_read_b128 v[222:225], v201 offset:50176
	ds_read_b128 v[226:229], v201 offset:51200
	ds_read_b128 v[230:233], v201 offset:52224
	ds_read_b128 v[234:237], v201 offset:53248
	ds_read_b128 v[238:241], v201 offset:54272
	ds_read_b128 v[242:245], v201 offset:55296
	ds_read_b128 v[246:249], v201 offset:56320
	global_load_lds_dwordx4 v[176:177], off
	s_add_i32 m0, s2, 0x2000
	s_add_u32 s2, s50, 0xb0080
	v_lshl_add_u64 v[176:177], v[218:219], 0, s[22:23]
	s_addc_u32 s3, s51, 0
	s_add_i32 s50, s81, s42
	global_load_lds_dwordx4 v[176:177], off
	v_lshl_add_u64 v[176:177], s[2:3], 0, v[130:131]
	s_mov_b32 m0, s50
	s_nop 0
	global_load_lds_dwordx4 v[176:177], off
	v_lshl_add_u64 v[176:177], s[2:3], 0, v[134:135]
	s_add_i32 m0, s50, 0x2000
	s_nop 0
	global_load_lds_dwordx4 v[176:177], off
	v_lshl_add_u64 v[176:177], v[250:251], 0, s[22:23]
	s_mov_b32 m0, s65
	s_nop 0
	global_load_lds_dwordx4 v[176:177], off
	v_lshl_add_u64 v[176:177], v[252:253], 0, s[22:23]
	s_mov_b32 m0, s66
	s_nop 0
	global_load_lds_dwordx4 v[176:177], off
	s_waitcnt vmcnt(8)
	s_waitcnt lgkmcnt(0)
	s_barrier
	s_setprio 1
	s_waitcnt lgkmcnt(0)
	v_mfma_f32_16x16x32_bf16 v[60:63], v[144:147], v[214:217], v[60:63]
	v_mfma_f32_16x16x32_bf16 v[56:59], v[152:155], v[214:217], v[56:59]
	v_mfma_f32_16x16x32_bf16 v[44:47], v[144:147], v[226:229], v[44:47]
	v_mfma_f32_16x16x32_bf16 v[40:43], v[152:155], v[226:229], v[40:43]
	v_mfma_f32_16x16x32_bf16 v[28:31], v[144:147], v[234:237], v[28:31]
	v_mfma_f32_16x16x32_bf16 v[24:27], v[152:155], v[234:237], v[24:27]
	v_mfma_f32_16x16x32_bf16 v[12:15], v[144:147], v[242:245], v[12:15]
	v_mfma_f32_16x16x32_bf16 v[8:11], v[152:155], v[242:245], v[8:11]
	v_mfma_f32_16x16x32_bf16 v[60:63], v[148:151], v[222:225], v[60:63]
	v_mfma_f32_16x16x32_bf16 v[56:59], v[156:159], v[222:225], v[56:59]
	v_mfma_f32_16x16x32_bf16 v[44:47], v[148:151], v[230:233], v[44:47]
	v_mfma_f32_16x16x32_bf16 v[40:43], v[156:159], v[230:233], v[40:43]
	v_mfma_f32_16x16x32_bf16 v[28:31], v[148:151], v[238:241], v[28:31]
	v_mfma_f32_16x16x32_bf16 v[24:27], v[156:159], v[238:241], v[24:27]
	v_mfma_f32_16x16x32_bf16 v[12:15], v[148:151], v[246:249], v[12:15]
	v_mfma_f32_16x16x32_bf16 v[8:11], v[156:159], v[246:249], v[8:11]
	s_setprio 0
	s_setprio 1
	v_mfma_f32_16x16x32_bf16 v[52:55], v[160:163], v[214:217], v[52:55]
	v_mfma_f32_16x16x32_bf16 v[48:51], v[168:171], v[214:217], v[48:51]
	v_mfma_f32_16x16x32_bf16 v[36:39], v[160:163], v[226:229], v[36:39]
	v_mfma_f32_16x16x32_bf16 v[32:35], v[168:171], v[226:229], v[32:35]
	v_mfma_f32_16x16x32_bf16 v[20:23], v[160:163], v[234:237], v[20:23]
	v_mfma_f32_16x16x32_bf16 v[16:19], v[168:171], v[234:237], v[16:19]
	v_mfma_f32_16x16x32_bf16 v[4:7], v[160:163], v[242:245], v[4:7]
	v_mfma_f32_16x16x32_bf16 v[0:3], v[168:171], v[242:245], v[0:3]
	v_mfma_f32_16x16x32_bf16 v[52:55], v[164:167], v[222:225], v[52:55]
	v_mfma_f32_16x16x32_bf16 v[48:51], v[172:175], v[222:225], v[48:51]
	v_mfma_f32_16x16x32_bf16 v[36:39], v[164:167], v[230:233], v[36:39]
	v_mfma_f32_16x16x32_bf16 v[32:35], v[172:175], v[230:233], v[32:35]
	v_mfma_f32_16x16x32_bf16 v[20:23], v[164:167], v[238:241], v[20:23]
	v_mfma_f32_16x16x32_bf16 v[16:19], v[172:175], v[238:241], v[16:19]
	v_mfma_f32_16x16x32_bf16 v[4:7], v[164:167], v[246:249], v[4:7]
	v_mfma_f32_16x16x32_bf16 v[0:3], v[172:175], v[246:249], v[0:3]
	s_setprio 0
	s_barrier
	s_add_i32 s80, s80, 2
	s_add_u32 s78, s78, 0x100
	s_addc_u32 s79, s79, 0
	s_cmp_gt_u32 s80, 41
	s_mov_b64 s[2:3], s[48:49]
	s_cbranch_scc1 .Lpeel_after_P9

; #define PG8_BAR __builtin_amdgcn_s_barrier()
;     __device__ __forceinline__ void operator()(Acc& acc, const Unit& u, int wr, int wc, int fr, int fq, PG8_LAS unsigned char* xl) const {
;     ...
;             for (int m = 0; m < 4; ++m) { const int rl = ai * HALF + wr * 64 + m * 16 + fr; const size_t off = (size_t)(u.r0 + rl) * DM + col; float s = 0.f;
; #pragma unroll
;                 for (int bj = 0; bj < 2; ++bj) {
;                     f32x4 b0, b1; unpack8(*(const u32x4*)(base + off + bj * HALF), b0, b1);
; template <class Epi, class Sched>
; __device__ __forceinline__ void gemm_phase(PG8_LAS unsigned char* lds, PG8_LAS unsigned char* xl, const Gemm g, const Sched& S, const Epi& E) {
;     ...
;         if (wr == 0) PG8_BAR;
.Lpeel_after_P9:
	v_add_u32_e32 v252, s76, v183
	v_ashrrev_i32_e32 v253, 31, v252
	v_add_u32_e32 v248, s75, v180
	v_ashrrev_i32_e32 v249, 31, v248
	v_lshlrev_b64 v[248:249], 10, v[248:249]
	v_lshl_add_u64 v[248:249], v[248:249], 0, v[252:253]
	v_lshl_add_u64 v[248:249], v[248:249], 1, s[18:19]
	global_load_dwordx4 v[224:227], v[248:249], off
	global_load_dwordx4 v[228:231], v[248:249], off offset:256
	v_add_u32_e32 v248, s75, v184
	v_ashrrev_i32_e32 v249, 31, v248
	v_lshlrev_b64 v[248:249], 10, v[248:249]
	v_lshl_add_u64 v[248:249], v[248:249], 0, v[252:253]
	v_lshl_add_u64 v[248:249], v[248:249], 1, s[18:19]
	global_load_dwordx4 v[232:235], v[248:249], off
	global_load_dwordx4 v[236:239], v[248:249], off offset:256
	v_add_u32_e32 v248, s75, v185
	v_ashrrev_i32_e32 v249, 31, v248
	v_lshlrev_b64 v[248:249], 10, v[248:249]
	v_lshl_add_u64 v[248:249], v[248:249], 0, v[252:253]
	v_lshl_add_u64 v[248:249], v[248:249], 1, s[18:19]
	global_load_dwordx4 v[240:243], v[248:249], off
	global_load_dwordx4 v[244:247], v[248:249], off offset:256
	s_and_b64 vcc, exec, s[26:27]
	s_cbranch_vccz .LBB0_945
	s_barrier
